# K-loops: s_setprio 1 raised before the pre-burst barrier, duplicate lgkmcnt(0) after it dropped, s_setprio 0 moved after the closing barrier (shorter critical stretch around each of the 4 barriers per
# speedup vs baseline: 1.0128x; 1.0045x over previous
; #define PG8_STAGE(bufoff, gbase, voff) do { _Pragma("unroll") for (int _i = 0; _i < 2; ++_i) \
;         __builtin_amdgcn_global_load_lds((const unsigned*)((const char*)(gbase) + (voff)[_i]), (LAS unsigned*)(lds + (bufoff) + ldsw + _i * 8192), 16, 0, 0); } while (0)
; #define PG8_LDA(dst, b, h) do { _Pragma("unroll") for (int m = 0; m < 4; ++m) _Pragma("unroll") for (int k = 0; k < 2; ++k) dst[m][k] = *(const LAS bf16x8*)(lds + PG8_SA(b, h) + aoff + m * 2048 + k * 1024); } while (0)
; #define PG8_LDB(dst, b, h) do { _Pragma("unroll") for (int n = 0; n < 2; ++n) _Pragma("unroll") for (int k = 0; k < 2; ++k) dst[n][k] = *(const LAS bf16x8*)(lds + PG8_SB(b, h) + boff + n * 2048 + k * 1024); } while (0)
; template <class Epi, class Sched, bool ALIGN_EPI>
; __device__ __forceinline__ void gemm_phase(LAS unsigned char* lds, const Gemm g, const Sched& S, const Epi& E, const int wid) {
;     ...
;         for (int t = 0; t < nt; t += 2) {
;             const bool last = (t == nt - 2);
;             if constexpr (Epi::HAS_PRE) { if (last) X.pre = E.pre(cur, tid); }
;             const char* a1 = cA + (size_t)(t + 1) * kstepA;
;             const char* a2 = last ? nA : cA + (size_t)(t + 2) * kstepA; const char* b2 = last ? nB : cB + (size_t)(t + 2) * kstep;
;             const char* a3 = a2 + kstepA; const char* b3 = b2 + kstep;
;             PG8_LDB(B0, 0, 0); PG8_LDB(B1, 0, 1); PG8_SCHED; PG8_LDA(At, 0, 0); PG8_STAGE(PG8_SA(1, 1), a1 + hstepA, voffA);
;             PG8_WAIT_V(8); PG8_WAIT_L(0); PG8_BAR; PG8_MMA(0, 0, At, B0); PG8_MMA(0, 1, At, B1); PG8_BAR; PG8_SCHED;
;             PG8_LDA(At, 0, 1); PG8_STAGE(PG8_SB(0, 0), b2, voffB); PG8_STAGE(PG8_SB(0, 1), b2 + hstepB, voffB); PG8_STAGE(PG8_SA(0, 0), a2, voffA);
;             PG8_WAIT_V(8); PG8_WAIT_L(0); PG8_BAR; PG8_MMA(1, 0, At, B0); PG8_MMA(1, 1, At, B1); PG8_BAR; PG8_SCHED;
;             PG8_LDB(B0, 1, 0); PG8_LDB(B1, 1, 1); PG8_SCHED; PG8_LDA(At, 1, 0); PG8_STAGE(PG8_SA(0, 1), a2 + hstepA, voffA);
;             PG8_WAIT_V(8); PG8_WAIT_L(0); PG8_BAR; PG8_MMA(0, 0, At, B0); PG8_MMA(0, 1, At, B1); PG8_BAR; PG8_SCHED;
;             PG8_LDA(At, 1, 1); PG8_STAGE(PG8_SB(1, 0), b3, voffB); PG8_STAGE(PG8_SB(1, 1), b3 + hstepB, voffB); PG8_STAGE(PG8_SA(1, 0), a3, voffA);
;             PG8_WAIT_V(8); PG8_WAIT_L(0); PG8_BAR; PG8_MMA(1, 0, At, B0); PG8_MMA(1, 1, At, B1); PG8_BAR; PG8_SCHED;
.LBB0_166:
	ds_read_b128 v[152:155], v149
	ds_read_b128 v[156:159], v149 offset:1024
	ds_read_b128 v[160:163], v149 offset:2048
	ds_read_b128 v[164:167], v149 offset:3072
	ds_read_b128 v[168:171], v150
	ds_read_b128 v[172:175], v150 offset:1024
	ds_read_b128 v[176:179], v150 offset:2048
	ds_read_b128 v[180:183], v150 offset:3072
	s_add_u32 s26, s24, 0x4000
	s_addc_u32 s27, s25, 0
	s_cmp_eq_u32 s66, 60
	s_cselect_b32 s50, s35, s26
	s_cselect_b32 s51, s17, s27
	s_cselect_b32 s48, s63, s64
	s_cselect_b32 s49, s15, s65
	s_add_u32 s26, s50, 0x8000
	s_addc_u32 s27, s51, 0
	s_add_i32 m0, s47, 0xc000
	ds_read_b128 v[184:187], v151
	ds_read_b128 v[188:191], v151 offset:1024
	ds_read_b128 v[192:195], v151 offset:2048
	ds_read_b128 v[196:199], v151 offset:3072
	ds_read_b128 v[200:203], v151 offset:4096
	ds_read_b128 v[204:207], v151 offset:5120
	ds_read_b128 v[208:211], v151 offset:6144
	ds_read_b128 v[212:215], v151 offset:7168
	global_load_lds_dwordx4 v138, s[24:25]
	s_add_i32 m0, s47, 0xe000
	s_nop 0
	global_load_lds_dwordx4 v140, s[24:25]
	s_waitcnt vmcnt(8)
	s_waitcnt lgkmcnt(0)
	s_setprio 1
	s_barrier
	v_mfma_f32_16x16x32_bf16 v[124:127], v[152:155], v[184:187], v[124:127]
	v_mfma_f32_16x16x32_bf16 v[120:123], v[160:163], v[184:187], v[120:123]
	v_mfma_f32_16x16x32_bf16 v[108:111], v[152:155], v[192:195], v[108:111]
	v_mfma_f32_16x16x32_bf16 v[104:107], v[160:163], v[192:195], v[104:107]
	v_mfma_f32_16x16x32_bf16 v[92:95], v[152:155], v[200:203], v[92:95]
	v_mfma_f32_16x16x32_bf16 v[88:91], v[160:163], v[200:203], v[88:91]
	v_mfma_f32_16x16x32_bf16 v[76:79], v[152:155], v[208:211], v[76:79]
	v_mfma_f32_16x16x32_bf16 v[72:75], v[160:163], v[208:211], v[72:75]
	v_mfma_f32_16x16x32_bf16 v[124:127], v[156:159], v[188:191], v[124:127]
	v_mfma_f32_16x16x32_bf16 v[120:123], v[164:167], v[188:191], v[120:123]
	v_mfma_f32_16x16x32_bf16 v[108:111], v[156:159], v[196:199], v[108:111]
	v_mfma_f32_16x16x32_bf16 v[104:107], v[164:167], v[196:199], v[104:107]
	v_mfma_f32_16x16x32_bf16 v[92:95], v[156:159], v[204:207], v[92:95]
	v_mfma_f32_16x16x32_bf16 v[88:91], v[164:167], v[204:207], v[88:91]
	v_mfma_f32_16x16x32_bf16 v[76:79], v[156:159], v[212:215], v[76:79]
	v_mfma_f32_16x16x32_bf16 v[72:75], v[164:167], v[212:215], v[72:75]
	s_setprio 0
	s_setprio 1
	v_mfma_f32_16x16x32_bf16 v[116:119], v[168:171], v[184:187], v[116:119]
	v_mfma_f32_16x16x32_bf16 v[112:115], v[176:179], v[184:187], v[112:115]
	v_mfma_f32_16x16x32_bf16 v[100:103], v[168:171], v[192:195], v[100:103]
	v_mfma_f32_16x16x32_bf16 v[96:99], v[176:179], v[192:195], v[96:99]
	v_mfma_f32_16x16x32_bf16 v[84:87], v[168:171], v[200:203], v[84:87]
	v_mfma_f32_16x16x32_bf16 v[80:83], v[176:179], v[200:203], v[80:83]
	v_mfma_f32_16x16x32_bf16 v[68:71], v[168:171], v[208:211], v[68:71]
	v_mfma_f32_16x16x32_bf16 v[64:67], v[176:179], v[208:211], v[64:67]
	v_mfma_f32_16x16x32_bf16 v[116:119], v[172:175], v[188:191], v[116:119]
	v_mfma_f32_16x16x32_bf16 v[112:115], v[180:183], v[188:191], v[112:115]
	v_mfma_f32_16x16x32_bf16 v[100:103], v[172:175], v[196:199], v[100:103]
	v_mfma_f32_16x16x32_bf16 v[96:99], v[180:183], v[196:199], v[96:99]
	v_mfma_f32_16x16x32_bf16 v[84:87], v[172:175], v[204:207], v[84:87]
	v_mfma_f32_16x16x32_bf16 v[80:83], v[180:183], v[204:207], v[80:83]
	v_mfma_f32_16x16x32_bf16 v[68:71], v[172:175], v[212:215], v[68:71]
	v_mfma_f32_16x16x32_bf16 v[64:67], v[180:183], v[212:215], v[64:67]
	s_barrier
	s_setprio 0
	s_add_i32 s38, s61, s3
	s_mov_b32 m0, s38
	ds_read_b128 v[184:187], v151 offset:16384
	ds_read_b128 v[188:191], v151 offset:17408
	ds_read_b128 v[192:195], v151 offset:18432
	ds_read_b128 v[196:199], v151 offset:19456
	ds_read_b128 v[200:203], v151 offset:20480
	ds_read_b128 v[204:207], v151 offset:21504
	ds_read_b128 v[208:211], v151 offset:22528
	ds_read_b128 v[212:215], v151 offset:23552
	global_load_lds_dwordx4 v132, s[48:49]
	s_add_i32 m0, s38, 0x2000
	s_add_u32 s68, s48, 0x1000
	s_addc_u32 s69, s49, 0
	s_add_i32 s38, s62, s3
	global_load_lds_dwordx4 v128, s[48:49]
	s_mov_b32 m0, s38
	s_nop 0
	global_load_lds_dwordx4 v132, s[68:69]
	s_add_i32 m0, s38, 0x2000
	s_nop 0
	global_load_lds_dwordx4 v128, s[68:69]
	s_mov_b32 m0, s47
	s_nop 0
	global_load_lds_dwordx4 v134, s[50:51]
	s_mov_b32 m0, s52
	s_nop 0
	global_load_lds_dwordx4 v130, s[50:51]
	s_waitcnt vmcnt(8)
	s_waitcnt lgkmcnt(0)
	s_setprio 1
	s_barrier
	v_mfma_f32_16x16x32_bf16 v[60:63], v[152:155], v[184:187], v[60:63]
	v_mfma_f32_16x16x32_bf16 v[56:59], v[160:163], v[184:187], v[56:59]
	v_mfma_f32_16x16x32_bf16 v[44:47], v[152:155], v[192:195], v[44:47]
	v_mfma_f32_16x16x32_bf16 v[40:43], v[160:163], v[192:195], v[40:43]
	v_mfma_f32_16x16x32_bf16 v[28:31], v[152:155], v[200:203], v[28:31]
	v_mfma_f32_16x16x32_bf16 v[24:27], v[160:163], v[200:203], v[24:27]
	v_mfma_f32_16x16x32_bf16 v[12:15], v[152:155], v[208:211], v[12:15]
	v_mfma_f32_16x16x32_bf16 v[8:11], v[160:163], v[208:211], v[8:11]
	v_mfma_f32_16x16x32_bf16 v[60:63], v[156:159], v[188:191], v[60:63]
	v_mfma_f32_16x16x32_bf16 v[56:59], v[164:167], v[188:191], v[56:59]
	v_mfma_f32_16x16x32_bf16 v[44:47], v[156:159], v[196:199], v[44:47]
	v_mfma_f32_16x16x32_bf16 v[40:43], v[164:167], v[196:199], v[40:43]
	v_mfma_f32_16x16x32_bf16 v[28:31], v[156:159], v[204:207], v[28:31]
	v_mfma_f32_16x16x32_bf16 v[24:27], v[164:167], v[204:207], v[24:27]
	v_mfma_f32_16x16x32_bf16 v[12:15], v[156:159], v[212:215], v[12:15]
	v_mfma_f32_16x16x32_bf16 v[8:11], v[164:167], v[212:215], v[8:11]
	s_setprio 0
	s_setprio 1
	v_mfma_f32_16x16x32_bf16 v[52:55], v[168:171], v[184:187], v[52:55]
	v_mfma_f32_16x16x32_bf16 v[48:51], v[176:179], v[184:187], v[48:51]
	v_mfma_f32_16x16x32_bf16 v[36:39], v[168:171], v[192:195], v[36:39]
	v_mfma_f32_16x16x32_bf16 v[32:35], v[176:179], v[192:195], v[32:35]
	v_mfma_f32_16x16x32_bf16 v[20:23], v[168:171], v[200:203], v[20:23]
	v_mfma_f32_16x16x32_bf16 v[16:19], v[176:179], v[200:203], v[16:19]
	v_mfma_f32_16x16x32_bf16 v[4:7], v[168:171], v[208:211], v[4:7]
	v_mfma_f32_16x16x32_bf16 v[0:3], v[176:179], v[208:211], v[0:3]
	v_mfma_f32_16x16x32_bf16 v[52:55], v[172:175], v[188:191], v[52:55]
	v_mfma_f32_16x16x32_bf16 v[48:51], v[180:183], v[188:191], v[48:51]
	v_mfma_f32_16x16x32_bf16 v[36:39], v[172:175], v[196:199], v[36:39]
	v_mfma_f32_16x16x32_bf16 v[32:35], v[180:183], v[196:199], v[32:35]
	v_mfma_f32_16x16x32_bf16 v[20:23], v[172:175], v[204:207], v[20:23]
	v_mfma_f32_16x16x32_bf16 v[16:19], v[180:183], v[204:207], v[16:19]
	v_mfma_f32_16x16x32_bf16 v[4:7], v[172:175], v[212:215], v[4:7]
	v_mfma_f32_16x16x32_bf16 v[0:3], v[180:183], v[212:215], v[0:3]
	s_barrier
; #define PG8_STAGE(bufoff, gbase, voff) do { _Pragma("unroll") for (int _i = 0; _i < 2; ++_i) \
;         __builtin_amdgcn_global_load_lds((const unsigned*)((const char*)(gbase) + (voff)[_i]), (LAS unsigned*)(lds + (bufoff) + ldsw + _i * 8192), 16, 0, 0); } while (0)
; #define PG8_LDA(dst, b, h) do { _Pragma("unroll") for (int m = 0; m < 4; ++m) _Pragma("unroll") for (int k = 0; k < 2; ++k) dst[m][k] = *(const LAS bf16x8*)(lds + PG8_SA(b, h) + aoff + m * 2048 + k * 1024); } while (0)
; #define PG8_LDB(dst, b, h) do { _Pragma("unroll") for (int n = 0; n < 2; ++n) _Pragma("unroll") for (int k = 0; k < 2; ++k) dst[n][k] = *(const LAS bf16x8*)(lds + PG8_SB(b, h) + boff + n * 2048 + k * 1024); } while (0)
; template <class Epi, class Sched, bool ALIGN_EPI>
; __device__ __forceinline__ void gemm_phase(LAS unsigned char* lds, const Gemm g, const Sched& S, const Epi& E, const int wid) {
;     ...
;         for (int t = 0; t < nt; t += 2) {
;             const bool last = (t == nt - 2);
;             if constexpr (Epi::HAS_PRE) { if (last) X.pre = E.pre(cur, tid); }
;             const char* a1 = cA + (size_t)(t + 1) * kstepA;
;             const char* a2 = last ? nA : cA + (size_t)(t + 2) * kstepA; const char* b2 = last ? nB : cB + (size_t)(t + 2) * kstep;
;             const char* a3 = a2 + kstepA; const char* b3 = b2 + kstep;
;             PG8_LDB(B0, 0, 0); PG8_LDB(B1, 0, 1); PG8_SCHED; PG8_LDA(At, 0, 0); PG8_STAGE(PG8_SA(1, 1), a1 + hstepA, voffA);
;             PG8_WAIT_V(8); PG8_WAIT_L(0); PG8_BAR; PG8_MMA(0, 0, At, B0); PG8_MMA(0, 1, At, B1); PG8_BAR; PG8_SCHED;
;             PG8_LDA(At, 0, 1); PG8_STAGE(PG8_SB(0, 0), b2, voffB); PG8_STAGE(PG8_SB(0, 1), b2 + hstepB, voffB); PG8_STAGE(PG8_SA(0, 0), a2, voffA);
;             PG8_WAIT_V(8); PG8_WAIT_L(0); PG8_BAR; PG8_MMA(1, 0, At, B0); PG8_MMA(1, 1, At, B1); PG8_BAR; PG8_SCHED;
;             PG8_LDB(B0, 1, 0); PG8_LDB(B1, 1, 1); PG8_SCHED; PG8_LDA(At, 1, 0); PG8_STAGE(PG8_SA(0, 1), a2 + hstepA, voffA);
;             PG8_WAIT_V(8); PG8_WAIT_L(0); PG8_BAR; PG8_MMA(0, 0, At, B0); PG8_MMA(0, 1, At, B1); PG8_BAR; PG8_SCHED;
;             PG8_LDA(At, 1, 1); PG8_STAGE(PG8_SB(1, 0), b3, voffB); PG8_STAGE(PG8_SB(1, 1), b3 + hstepB, voffB); PG8_STAGE(PG8_SA(1, 0), a3, voffA);
;             PG8_WAIT_V(8); PG8_WAIT_L(0); PG8_BAR; PG8_MMA(1, 0, At, B0); PG8_MMA(1, 1, At, B1); PG8_BAR; PG8_SCHED;
	s_setprio 0
	s_add_i32 s38, 0, 0x18000
	v_add_u32_e32 v136, s38, v146
	s_add_i32 s39, 0, 0x1c000
	ds_read_b128 v[152:155], v136
	ds_read_b128 v[156:159], v136 offset:1024
	ds_read_b128 v[160:163], v136 offset:2048
	ds_read_b128 v[164:167], v136 offset:3072
	v_add_u32_e32 v136, s39, v146
	ds_read_b128 v[168:171], v136
	ds_read_b128 v[172:175], v136 offset:1024
	ds_read_b128 v[176:179], v136 offset:2048
	ds_read_b128 v[180:183], v136 offset:3072
	s_add_u32 s50, s50, 0x4000
	s_addc_u32 s51, s51, 0
	s_mov_b32 m0, s53
	ds_read_b128 v[184:187], v151 offset:32768
	ds_read_b128 v[188:191], v151 offset:33792
	ds_read_b128 v[192:195], v151 offset:34816
	ds_read_b128 v[196:199], v151 offset:35840
	ds_read_b128 v[200:203], v151 offset:36864
	ds_read_b128 v[204:207], v151 offset:37888
	ds_read_b128 v[208:211], v151 offset:38912
	ds_read_b128 v[212:215], v151 offset:39936
	global_load_lds_dwordx4 v134, s[50:51]
	s_mov_b32 m0, s54
	s_nop 0
	global_load_lds_dwordx4 v130, s[50:51]
	s_waitcnt vmcnt(8)
	s_waitcnt lgkmcnt(0)
	s_setprio 1
	s_barrier
	v_mfma_f32_16x16x32_bf16 v[124:127], v[152:155], v[184:187], v[124:127]
	v_mfma_f32_16x16x32_bf16 v[120:123], v[160:163], v[184:187], v[120:123]
	v_mfma_f32_16x16x32_bf16 v[108:111], v[152:155], v[192:195], v[108:111]
	v_mfma_f32_16x16x32_bf16 v[104:107], v[160:163], v[192:195], v[104:107]
	v_mfma_f32_16x16x32_bf16 v[92:95], v[152:155], v[200:203], v[92:95]
	v_mfma_f32_16x16x32_bf16 v[88:91], v[160:163], v[200:203], v[88:91]
	v_mfma_f32_16x16x32_bf16 v[76:79], v[152:155], v[208:211], v[76:79]
	v_mfma_f32_16x16x32_bf16 v[72:75], v[160:163], v[208:211], v[72:75]
	v_mfma_f32_16x16x32_bf16 v[124:127], v[156:159], v[188:191], v[124:127]
	v_mfma_f32_16x16x32_bf16 v[120:123], v[164:167], v[188:191], v[120:123]
	v_mfma_f32_16x16x32_bf16 v[108:111], v[156:159], v[196:199], v[108:111]
	v_mfma_f32_16x16x32_bf16 v[104:107], v[164:167], v[196:199], v[104:107]
	v_mfma_f32_16x16x32_bf16 v[92:95], v[156:159], v[204:207], v[92:95]
	v_mfma_f32_16x16x32_bf16 v[88:91], v[164:167], v[204:207], v[88:91]
	v_mfma_f32_16x16x32_bf16 v[76:79], v[156:159], v[212:215], v[76:79]
	v_mfma_f32_16x16x32_bf16 v[72:75], v[164:167], v[212:215], v[72:75]
	s_setprio 0
	s_setprio 1
	v_mfma_f32_16x16x32_bf16 v[116:119], v[168:171], v[184:187], v[116:119]
	v_mfma_f32_16x16x32_bf16 v[112:115], v[176:179], v[184:187], v[112:115]
	v_mfma_f32_16x16x32_bf16 v[100:103], v[168:171], v[192:195], v[100:103]
	v_mfma_f32_16x16x32_bf16 v[96:99], v[176:179], v[192:195], v[96:99]
	v_mfma_f32_16x16x32_bf16 v[84:87], v[168:171], v[200:203], v[84:87]
	v_mfma_f32_16x16x32_bf16 v[80:83], v[176:179], v[200:203], v[80:83]
	v_mfma_f32_16x16x32_bf16 v[68:71], v[168:171], v[208:211], v[68:71]
	v_mfma_f32_16x16x32_bf16 v[64:67], v[176:179], v[208:211], v[64:67]
	v_mfma_f32_16x16x32_bf16 v[116:119], v[172:175], v[188:191], v[116:119]
	v_mfma_f32_16x16x32_bf16 v[112:115], v[180:183], v[188:191], v[112:115]
	v_mfma_f32_16x16x32_bf16 v[100:103], v[172:175], v[196:199], v[100:103]
	v_mfma_f32_16x16x32_bf16 v[96:99], v[180:183], v[196:199], v[96:99]
	v_mfma_f32_16x16x32_bf16 v[84:87], v[172:175], v[204:207], v[84:87]
	v_mfma_f32_16x16x32_bf16 v[80:83], v[180:183], v[204:207], v[80:83]
	v_mfma_f32_16x16x32_bf16 v[68:71], v[172:175], v[212:215], v[68:71]
	v_mfma_f32_16x16x32_bf16 v[64:67], v[180:183], v[212:215], v[64:67]
	s_barrier
	s_setprio 0
	s_add_u32 s50, s48, 0x8000
	s_addc_u32 s51, s49, 0
	s_add_i32 s38, s38, s3
	s_mov_b32 m0, s38
	ds_read_b128 v[184:187], v151 offset:49152
	ds_read_b128 v[188:191], v151 offset:50176
	ds_read_b128 v[192:195], v151 offset:51200
	ds_read_b128 v[196:199], v151 offset:52224
	ds_read_b128 v[200:203], v151 offset:53248
	ds_read_b128 v[204:207], v151 offset:54272
	ds_read_b128 v[208:211], v151 offset:55296
	ds_read_b128 v[212:215], v151 offset:56320
	global_load_lds_dwordx4 v132, s[50:51]
	s_add_i32 m0, s38, 0x2000
	s_add_u32 s48, s48, 0x9000
	s_addc_u32 s49, s49, 0
	s_add_i32 s38, s39, s3
	global_load_lds_dwordx4 v128, s[50:51]
	s_mov_b32 m0, s38
	s_nop 0
	global_load_lds_dwordx4 v132, s[48:49]
	s_add_i32 m0, s38, 0x2000
	s_nop 0
	global_load_lds_dwordx4 v128, s[48:49]
	s_mov_b32 m0, s58
	s_nop 0
	global_load_lds_dwordx4 v134, s[26:27]
	s_mov_b32 m0, s59
	s_nop 0
	global_load_lds_dwordx4 v130, s[26:27]
	s_waitcnt vmcnt(8)
	s_waitcnt lgkmcnt(0)
	s_setprio 1
	s_barrier
	v_mfma_f32_16x16x32_bf16 v[60:63], v[152:155], v[184:187], v[60:63]
	v_mfma_f32_16x16x32_bf16 v[56:59], v[160:163], v[184:187], v[56:59]
	v_mfma_f32_16x16x32_bf16 v[44:47], v[152:155], v[192:195], v[44:47]
	v_mfma_f32_16x16x32_bf16 v[40:43], v[160:163], v[192:195], v[40:43]
	v_mfma_f32_16x16x32_bf16 v[28:31], v[152:155], v[200:203], v[28:31]
	v_mfma_f32_16x16x32_bf16 v[24:27], v[160:163], v[200:203], v[24:27]
	v_mfma_f32_16x16x32_bf16 v[12:15], v[152:155], v[208:211], v[12:15]
	v_mfma_f32_16x16x32_bf16 v[8:11], v[160:163], v[208:211], v[8:11]
	v_mfma_f32_16x16x32_bf16 v[60:63], v[156:159], v[188:191], v[60:63]
	v_mfma_f32_16x16x32_bf16 v[56:59], v[164:167], v[188:191], v[56:59]
	v_mfma_f32_16x16x32_bf16 v[44:47], v[156:159], v[196:199], v[44:47]
	v_mfma_f32_16x16x32_bf16 v[40:43], v[164:167], v[196:199], v[40:43]
	v_mfma_f32_16x16x32_bf16 v[28:31], v[156:159], v[204:207], v[28:31]
	v_mfma_f32_16x16x32_bf16 v[24:27], v[164:167], v[204:207], v[24:27]
	v_mfma_f32_16x16x32_bf16 v[12:15], v[156:159], v[212:215], v[12:15]
	v_mfma_f32_16x16x32_bf16 v[8:11], v[164:167], v[212:215], v[8:11]
	s_setprio 0
	s_setprio 1
	v_mfma_f32_16x16x32_bf16 v[52:55], v[168:171], v[184:187], v[52:55]
	v_mfma_f32_16x16x32_bf16 v[48:51], v[176:179], v[184:187], v[48:51]
	v_mfma_f32_16x16x32_bf16 v[36:39], v[168:171], v[192:195], v[36:39]
	v_mfma_f32_16x16x32_bf16 v[32:35], v[176:179], v[192:195], v[32:35]
	v_mfma_f32_16x16x32_bf16 v[20:23], v[168:171], v[200:203], v[20:23]
	v_mfma_f32_16x16x32_bf16 v[16:19], v[176:179], v[200:203], v[16:19]
	v_mfma_f32_16x16x32_bf16 v[4:7], v[168:171], v[208:211], v[4:7]
	v_mfma_f32_16x16x32_bf16 v[0:3], v[176:179], v[208:211], v[0:3]
	v_mfma_f32_16x16x32_bf16 v[52:55], v[172:175], v[188:191], v[52:55]
	v_mfma_f32_16x16x32_bf16 v[48:51], v[180:183], v[188:191], v[48:51]
	v_mfma_f32_16x16x32_bf16 v[36:39], v[172:175], v[196:199], v[36:39]
	v_mfma_f32_16x16x32_bf16 v[32:35], v[180:183], v[196:199], v[32:35]
	v_mfma_f32_16x16x32_bf16 v[20:23], v[172:175], v[204:207], v[20:23]
	v_mfma_f32_16x16x32_bf16 v[16:19], v[180:183], v[204:207], v[16:19]
	v_mfma_f32_16x16x32_bf16 v[4:7], v[172:175], v[212:215], v[4:7]
	v_mfma_f32_16x16x32_bf16 v[0:3], v[180:183], v[212:215], v[0:3]
	s_barrier
	s_setprio 0
	s_add_i32 s66, s66, 2
	s_add_u32 s24, s24, 0x10000
	s_addc_u32 s25, s25, 0
	s_add_u32 s64, s64, 0x10000
	s_addc_u32 s65, s65, 0
	s_cmp_gt_u32 s66, 61
	s_cbranch_scc0 .LBB0_166
	s_and_b64 vcc, exec, s[28:29]
	s_cbranch_vccz .LBB0_169
	s_barrier

; #define PG8_STAGE(bufoff, gbase, voff) do { _Pragma("unroll") for (int _i = 0; _i < 2; ++_i) \
;         __builtin_amdgcn_global_load_lds((const unsigned*)((const char*)(gbase) + (voff)[_i]), (LAS unsigned*)(lds + (bufoff) + ldsw + _i * 8192), 16, 0, 0); } while (0)
; #define PG8_LDA(dst, b, h) do { _Pragma("unroll") for (int m = 0; m < 4; ++m) _Pragma("unroll") for (int k = 0; k < 2; ++k) dst[m][k] = *(const LAS bf16x8*)(lds + PG8_SA(b, h) + aoff + m * 2048 + k * 1024); } while (0)
; #define PG8_LDB(dst, b, h) do { _Pragma("unroll") for (int n = 0; n < 2; ++n) _Pragma("unroll") for (int k = 0; k < 2; ++k) dst[n][k] = *(const LAS bf16x8*)(lds + PG8_SB(b, h) + boff + n * 2048 + k * 1024); } while (0)
; template <class Epi, class Sched, bool ALIGN_EPI>
; __device__ __forceinline__ void gemm_phase(LAS unsigned char* lds, const Gemm g, const Sched& S, const Epi& E, const int wid) {
;     ...
;         for (int t = 0; t < nt; t += 2) {
;             const bool last = (t == nt - 2);
;             if constexpr (Epi::HAS_PRE) { if (last) X.pre = E.pre(cur, tid); }
;             const char* a1 = cA + (size_t)(t + 1) * kstepA;
;             const char* a2 = last ? nA : cA + (size_t)(t + 2) * kstepA; const char* b2 = last ? nB : cB + (size_t)(t + 2) * kstep;
;             const char* a3 = a2 + kstepA; const char* b3 = b2 + kstep;
;             PG8_LDB(B0, 0, 0); PG8_LDB(B1, 0, 1); PG8_SCHED; PG8_LDA(At, 0, 0); PG8_STAGE(PG8_SA(1, 1), a1 + hstepA, voffA);
;             PG8_WAIT_V(8); PG8_WAIT_L(0); PG8_BAR; PG8_MMA(0, 0, At, B0); PG8_MMA(0, 1, At, B1); PG8_BAR; PG8_SCHED;
;             PG8_LDA(At, 0, 1); PG8_STAGE(PG8_SB(0, 0), b2, voffB); PG8_STAGE(PG8_SB(0, 1), b2 + hstepB, voffB); PG8_STAGE(PG8_SA(0, 0), a2, voffA);
;             PG8_WAIT_V(8); PG8_WAIT_L(0); PG8_BAR; PG8_MMA(1, 0, At, B0); PG8_MMA(1, 1, At, B1); PG8_BAR; PG8_SCHED;
;             PG8_LDB(B0, 1, 0); PG8_LDB(B1, 1, 1); PG8_SCHED; PG8_LDA(At, 1, 0); PG8_STAGE(PG8_SA(0, 1), a2 + hstepA, voffA);
;             PG8_WAIT_V(8); PG8_WAIT_L(0); PG8_BAR; PG8_MMA(0, 0, At, B0); PG8_MMA(0, 1, At, B1); PG8_BAR; PG8_SCHED;
;             PG8_LDA(At, 1, 1); PG8_STAGE(PG8_SB(1, 0), b3, voffB); PG8_STAGE(PG8_SB(1, 1), b3 + hstepB, voffB); PG8_STAGE(PG8_SA(1, 0), a3, voffA);
;             PG8_WAIT_V(8); PG8_WAIT_L(0); PG8_BAR; PG8_MMA(1, 0, At, B0); PG8_MMA(1, 1, At, B1); PG8_BAR; PG8_SCHED;
.LBB0_243:
	s_add_u32 s38, s26, s60
	s_addc_u32 s39, s27, s61
	s_add_u32 s64, s38, 0x100
	s_addc_u32 s65, s39, 0
	s_and_b64 s[62:63], s[58:59], exec
	s_cselect_b32 s63, s21, s65
	s_cselect_b32 s62, s20, s64
	s_add_u32 s60, s10, s60
	s_addc_u32 s61, s11, s61
	s_add_u32 s60, s60, 0x100
	ds_read_b128 v[142:145], v137
	ds_read_b128 v[146:149], v137 offset:1024
	ds_read_b128 v[150:153], v137 offset:2048
	ds_read_b128 v[154:157], v137 offset:3072
	ds_read_b128 v[158:161], v138
	ds_read_b128 v[162:165], v138 offset:1024
	ds_read_b128 v[166:169], v138 offset:2048
	ds_read_b128 v[170:173], v138 offset:3072
	s_addc_u32 s61, s61, 0
	s_and_b64 s[58:59], s[58:59], exec
	s_cselect_b32 s65, s35, s61
	s_cselect_b32 s64, s55, s60
	s_add_u32 s68, s38, 0x18080
	s_addc_u32 s69, s39, 0
	s_add_u32 s66, s64, 0x4000
	s_addc_u32 s67, s65, 0
	s_add_u32 s60, s62, 0x18000
	s_addc_u32 s61, s63, 0
	s_add_u32 s58, s64, 0x4080
	s_addc_u32 s59, s65, 0
	s_mov_b32 m0, s30
	ds_read_b128 v[174:177], v139
	ds_read_b128 v[178:181], v139 offset:1024
	ds_read_b128 v[182:185], v139 offset:2048
	ds_read_b128 v[186:189], v139 offset:3072
	ds_read_b128 v[190:193], v139 offset:4096
	ds_read_b128 v[194:197], v139 offset:5120
	ds_read_b128 v[198:201], v139 offset:6144
	ds_read_b128 v[202:205], v139 offset:7168
	global_load_lds_dwordx4 v134, s[68:69]
	s_mov_b32 m0, s77
	s_nop 0
	global_load_lds_dwordx4 v130, s[68:69]
	s_waitcnt vmcnt(8)
	s_waitcnt lgkmcnt(0)
	s_setprio 1
	s_barrier
	v_mfma_f32_16x16x32_bf16 v[124:127], v[142:145], v[174:177], v[124:127]
	v_mfma_f32_16x16x32_bf16 v[120:123], v[150:153], v[174:177], v[120:123]
	v_mfma_f32_16x16x32_bf16 v[108:111], v[142:145], v[182:185], v[108:111]
	v_mfma_f32_16x16x32_bf16 v[104:107], v[150:153], v[182:185], v[104:107]
	v_mfma_f32_16x16x32_bf16 v[92:95], v[142:145], v[190:193], v[92:95]
	v_mfma_f32_16x16x32_bf16 v[88:91], v[150:153], v[190:193], v[88:91]
	v_mfma_f32_16x16x32_bf16 v[76:79], v[142:145], v[198:201], v[76:79]
	v_mfma_f32_16x16x32_bf16 v[72:75], v[150:153], v[198:201], v[72:75]
	v_mfma_f32_16x16x32_bf16 v[124:127], v[146:149], v[178:181], v[124:127]
	v_mfma_f32_16x16x32_bf16 v[120:123], v[154:157], v[178:181], v[120:123]
	v_mfma_f32_16x16x32_bf16 v[108:111], v[146:149], v[186:189], v[108:111]
	v_mfma_f32_16x16x32_bf16 v[104:107], v[154:157], v[186:189], v[104:107]
	v_mfma_f32_16x16x32_bf16 v[92:95], v[146:149], v[194:197], v[92:95]
	v_mfma_f32_16x16x32_bf16 v[88:91], v[154:157], v[194:197], v[88:91]
	v_mfma_f32_16x16x32_bf16 v[76:79], v[146:149], v[202:205], v[76:79]
	v_mfma_f32_16x16x32_bf16 v[72:75], v[154:157], v[202:205], v[72:75]
	s_setprio 0
	s_setprio 1
	v_mfma_f32_16x16x32_bf16 v[116:119], v[158:161], v[174:177], v[116:119]
	v_mfma_f32_16x16x32_bf16 v[112:115], v[166:169], v[174:177], v[112:115]
	v_mfma_f32_16x16x32_bf16 v[100:103], v[158:161], v[182:185], v[100:103]
	v_mfma_f32_16x16x32_bf16 v[96:99], v[166:169], v[182:185], v[96:99]
	v_mfma_f32_16x16x32_bf16 v[84:87], v[158:161], v[190:193], v[84:87]
	v_mfma_f32_16x16x32_bf16 v[80:83], v[166:169], v[190:193], v[80:83]
	v_mfma_f32_16x16x32_bf16 v[68:71], v[158:161], v[198:201], v[68:71]
	v_mfma_f32_16x16x32_bf16 v[64:67], v[166:169], v[198:201], v[64:67]
	v_mfma_f32_16x16x32_bf16 v[116:119], v[162:165], v[178:181], v[116:119]
	v_mfma_f32_16x16x32_bf16 v[112:115], v[170:173], v[178:181], v[112:115]
	v_mfma_f32_16x16x32_bf16 v[100:103], v[162:165], v[186:189], v[100:103]
	v_mfma_f32_16x16x32_bf16 v[96:99], v[170:173], v[186:189], v[96:99]
	v_mfma_f32_16x16x32_bf16 v[84:87], v[162:165], v[194:197], v[84:87]
	v_mfma_f32_16x16x32_bf16 v[80:83], v[170:173], v[194:197], v[80:83]
	v_mfma_f32_16x16x32_bf16 v[68:71], v[162:165], v[202:205], v[68:71]
	v_mfma_f32_16x16x32_bf16 v[64:67], v[170:173], v[202:205], v[64:67]
	s_barrier
	s_setprio 0
	s_mov_b32 m0, s79
	v_lshl_add_u64 v[206:207], s[64:65], 0, v[132:133]
	ds_read_b128 v[174:177], v139 offset:16384
	ds_read_b128 v[178:181], v139 offset:17408
	ds_read_b128 v[182:185], v139 offset:18432
	ds_read_b128 v[186:189], v139 offset:19456
	ds_read_b128 v[190:193], v139 offset:20480
	ds_read_b128 v[194:197], v139 offset:21504
	ds_read_b128 v[198:201], v139 offset:22528
	ds_read_b128 v[202:205], v139 offset:23552
	global_load_lds_dwordx4 v[206:207], off
	v_lshl_add_u64 v[208:209], s[64:65], 0, v[128:129]
	s_mov_b32 m0, s80
	s_nop 0
	global_load_lds_dwordx4 v[208:209], off
	s_mov_b32 m0, s81
	v_lshl_add_u64 v[212:213], s[62:63], 0, v[130:131]
	global_load_lds_dwordx4 v132, s[66:67]
	s_mov_b32 m0, s84
	s_nop 0
	global_load_lds_dwordx4 v128, s[66:67]
	v_lshl_add_u64 v[210:211], s[62:63], 0, v[134:135]
	s_mov_b32 m0, s13
	s_nop 0
	global_load_lds_dwordx4 v[210:211], off
	s_mov_b32 m0, s52
	s_nop 0
	global_load_lds_dwordx4 v[212:213], off
	s_waitcnt vmcnt(8)
	s_waitcnt lgkmcnt(0)
	s_setprio 1
	s_barrier
; #define PG8_STAGE(bufoff, gbase, voff) do { _Pragma("unroll") for (int _i = 0; _i < 2; ++_i) \
;         __builtin_amdgcn_global_load_lds((const unsigned*)((const char*)(gbase) + (voff)[_i]), (LAS unsigned*)(lds + (bufoff) + ldsw + _i * 8192), 16, 0, 0); } while (0)
; #define PG8_LDA(dst, b, h) do { _Pragma("unroll") for (int m = 0; m < 4; ++m) _Pragma("unroll") for (int k = 0; k < 2; ++k) dst[m][k] = *(const LAS bf16x8*)(lds + PG8_SA(b, h) + aoff + m * 2048 + k * 1024); } while (0)
; #define PG8_LDB(dst, b, h) do { _Pragma("unroll") for (int n = 0; n < 2; ++n) _Pragma("unroll") for (int k = 0; k < 2; ++k) dst[n][k] = *(const LAS bf16x8*)(lds + PG8_SB(b, h) + boff + n * 2048 + k * 1024); } while (0)
; template <class Epi, class Sched, bool ALIGN_EPI>
; __device__ __forceinline__ void gemm_phase(LAS unsigned char* lds, const Gemm g, const Sched& S, const Epi& E, const int wid) {
;     ...
;         for (int t = 0; t < nt; t += 2) {
;             const bool last = (t == nt - 2);
;             if constexpr (Epi::HAS_PRE) { if (last) X.pre = E.pre(cur, tid); }
;             const char* a1 = cA + (size_t)(t + 1) * kstepA;
;             const char* a2 = last ? nA : cA + (size_t)(t + 2) * kstepA; const char* b2 = last ? nB : cB + (size_t)(t + 2) * kstep;
;             const char* a3 = a2 + kstepA; const char* b3 = b2 + kstep;
;             PG8_LDB(B0, 0, 0); PG8_LDB(B1, 0, 1); PG8_SCHED; PG8_LDA(At, 0, 0); PG8_STAGE(PG8_SA(1, 1), a1 + hstepA, voffA);
;             PG8_WAIT_V(8); PG8_WAIT_L(0); PG8_BAR; PG8_MMA(0, 0, At, B0); PG8_MMA(0, 1, At, B1); PG8_BAR; PG8_SCHED;
;             PG8_LDA(At, 0, 1); PG8_STAGE(PG8_SB(0, 0), b2, voffB); PG8_STAGE(PG8_SB(0, 1), b2 + hstepB, voffB); PG8_STAGE(PG8_SA(0, 0), a2, voffA);
;             PG8_WAIT_V(8); PG8_WAIT_L(0); PG8_BAR; PG8_MMA(1, 0, At, B0); PG8_MMA(1, 1, At, B1); PG8_BAR; PG8_SCHED;
;             PG8_LDB(B0, 1, 0); PG8_LDB(B1, 1, 1); PG8_SCHED; PG8_LDA(At, 1, 0); PG8_STAGE(PG8_SA(0, 1), a2 + hstepA, voffA);
;             PG8_WAIT_V(8); PG8_WAIT_L(0); PG8_BAR; PG8_MMA(0, 0, At, B0); PG8_MMA(0, 1, At, B1); PG8_BAR; PG8_SCHED;
;             PG8_LDA(At, 1, 1); PG8_STAGE(PG8_SB(1, 0), b3, voffB); PG8_STAGE(PG8_SB(1, 1), b3 + hstepB, voffB); PG8_STAGE(PG8_SA(1, 0), a3, voffA);
;             PG8_WAIT_V(8); PG8_WAIT_L(0); PG8_BAR; PG8_MMA(1, 0, At, B0); PG8_MMA(1, 1, At, B1); PG8_BAR; PG8_SCHED;
	v_mfma_f32_16x16x32_bf16 v[60:63], v[142:145], v[174:177], v[60:63]
	v_mfma_f32_16x16x32_bf16 v[56:59], v[150:153], v[174:177], v[56:59]
	v_mfma_f32_16x16x32_bf16 v[44:47], v[142:145], v[182:185], v[44:47]
	v_mfma_f32_16x16x32_bf16 v[40:43], v[150:153], v[182:185], v[40:43]
	v_mfma_f32_16x16x32_bf16 v[28:31], v[142:145], v[190:193], v[28:31]
	v_mfma_f32_16x16x32_bf16 v[24:27], v[150:153], v[190:193], v[24:27]
	v_mfma_f32_16x16x32_bf16 v[12:15], v[142:145], v[198:201], v[12:15]
	v_mfma_f32_16x16x32_bf16 v[8:11], v[150:153], v[198:201], v[8:11]
	v_mfma_f32_16x16x32_bf16 v[60:63], v[146:149], v[178:181], v[60:63]
	v_mfma_f32_16x16x32_bf16 v[56:59], v[154:157], v[178:181], v[56:59]
	v_mfma_f32_16x16x32_bf16 v[44:47], v[146:149], v[186:189], v[44:47]
	v_mfma_f32_16x16x32_bf16 v[40:43], v[154:157], v[186:189], v[40:43]
	v_mfma_f32_16x16x32_bf16 v[28:31], v[146:149], v[194:197], v[28:31]
	v_mfma_f32_16x16x32_bf16 v[24:27], v[154:157], v[194:197], v[24:27]
	v_mfma_f32_16x16x32_bf16 v[12:15], v[146:149], v[202:205], v[12:15]
	v_mfma_f32_16x16x32_bf16 v[8:11], v[154:157], v[202:205], v[8:11]
	s_setprio 0
	s_setprio 1
	v_mfma_f32_16x16x32_bf16 v[52:55], v[158:161], v[174:177], v[52:55]
	v_mfma_f32_16x16x32_bf16 v[48:51], v[166:169], v[174:177], v[48:51]
	v_mfma_f32_16x16x32_bf16 v[36:39], v[158:161], v[182:185], v[36:39]
	v_mfma_f32_16x16x32_bf16 v[32:35], v[166:169], v[182:185], v[32:35]
	v_mfma_f32_16x16x32_bf16 v[20:23], v[158:161], v[190:193], v[20:23]
	v_mfma_f32_16x16x32_bf16 v[16:19], v[166:169], v[190:193], v[16:19]
	v_mfma_f32_16x16x32_bf16 v[4:7], v[158:161], v[198:201], v[4:7]
	v_mfma_f32_16x16x32_bf16 v[0:3], v[166:169], v[198:201], v[0:3]
	v_mfma_f32_16x16x32_bf16 v[52:55], v[162:165], v[178:181], v[52:55]
	v_mfma_f32_16x16x32_bf16 v[48:51], v[170:173], v[178:181], v[48:51]
	v_mfma_f32_16x16x32_bf16 v[36:39], v[162:165], v[186:189], v[36:39]
	v_mfma_f32_16x16x32_bf16 v[32:35], v[170:173], v[186:189], v[32:35]
	v_mfma_f32_16x16x32_bf16 v[20:23], v[162:165], v[194:197], v[20:23]
	v_mfma_f32_16x16x32_bf16 v[16:19], v[170:173], v[194:197], v[16:19]
	v_mfma_f32_16x16x32_bf16 v[4:7], v[162:165], v[202:205], v[4:7]
	v_mfma_f32_16x16x32_bf16 v[0:3], v[170:173], v[202:205], v[0:3]
	s_barrier
	s_setprio 0
	ds_read_b128 v[142:145], v140
	ds_read_b128 v[146:149], v140 offset:1024
	ds_read_b128 v[150:153], v140 offset:2048
	ds_read_b128 v[154:157], v140 offset:3072
	ds_read_b128 v[158:161], v141
	ds_read_b128 v[162:165], v141 offset:1024
	ds_read_b128 v[166:169], v141 offset:2048
	ds_read_b128 v[170:173], v141 offset:3072
	s_mov_b32 m0, s70
	ds_read_b128 v[174:177], v139 offset:32768
	ds_read_b128 v[178:181], v139 offset:33792
	ds_read_b128 v[182:185], v139 offset:34816
	ds_read_b128 v[186:189], v139 offset:35840
	ds_read_b128 v[190:193], v139 offset:36864
	ds_read_b128 v[194:197], v139 offset:37888
	ds_read_b128 v[198:201], v139 offset:38912
	ds_read_b128 v[202:205], v139 offset:39936
	global_load_lds_dwordx4 v134, s[60:61]
	s_mov_b32 m0, s71
	s_nop 0
	global_load_lds_dwordx4 v130, s[60:61]
	s_waitcnt vmcnt(8)
	s_waitcnt lgkmcnt(0)
	s_setprio 1
	s_barrier
	v_mfma_f32_16x16x32_bf16 v[124:127], v[142:145], v[174:177], v[124:127]
	v_mfma_f32_16x16x32_bf16 v[120:123], v[150:153], v[174:177], v[120:123]
	v_mfma_f32_16x16x32_bf16 v[108:111], v[142:145], v[182:185], v[108:111]
	v_mfma_f32_16x16x32_bf16 v[104:107], v[150:153], v[182:185], v[104:107]
	v_mfma_f32_16x16x32_bf16 v[92:95], v[142:145], v[190:193], v[92:95]
	v_mfma_f32_16x16x32_bf16 v[88:91], v[150:153], v[190:193], v[88:91]
	v_mfma_f32_16x16x32_bf16 v[76:79], v[142:145], v[198:201], v[76:79]
	v_mfma_f32_16x16x32_bf16 v[72:75], v[150:153], v[198:201], v[72:75]
	v_mfma_f32_16x16x32_bf16 v[124:127], v[146:149], v[178:181], v[124:127]
	v_mfma_f32_16x16x32_bf16 v[120:123], v[154:157], v[178:181], v[120:123]
	v_mfma_f32_16x16x32_bf16 v[108:111], v[146:149], v[186:189], v[108:111]
	v_mfma_f32_16x16x32_bf16 v[104:107], v[154:157], v[186:189], v[104:107]
	v_mfma_f32_16x16x32_bf16 v[92:95], v[146:149], v[194:197], v[92:95]
	v_mfma_f32_16x16x32_bf16 v[88:91], v[154:157], v[194:197], v[88:91]
	v_mfma_f32_16x16x32_bf16 v[76:79], v[146:149], v[202:205], v[76:79]
	v_mfma_f32_16x16x32_bf16 v[72:75], v[154:157], v[202:205], v[72:75]
	s_setprio 0
	s_setprio 1
	v_mfma_f32_16x16x32_bf16 v[116:119], v[158:161], v[174:177], v[116:119]
	v_mfma_f32_16x16x32_bf16 v[112:115], v[166:169], v[174:177], v[112:115]
	v_mfma_f32_16x16x32_bf16 v[100:103], v[158:161], v[182:185], v[100:103]
	v_mfma_f32_16x16x32_bf16 v[96:99], v[166:169], v[182:185], v[96:99]
	v_mfma_f32_16x16x32_bf16 v[84:87], v[158:161], v[190:193], v[84:87]
	v_mfma_f32_16x16x32_bf16 v[80:83], v[166:169], v[190:193], v[80:83]
	v_mfma_f32_16x16x32_bf16 v[68:71], v[158:161], v[198:201], v[68:71]
	v_mfma_f32_16x16x32_bf16 v[64:67], v[166:169], v[198:201], v[64:67]
	v_mfma_f32_16x16x32_bf16 v[116:119], v[162:165], v[178:181], v[116:119]
	v_mfma_f32_16x16x32_bf16 v[112:115], v[170:173], v[178:181], v[112:115]
	v_mfma_f32_16x16x32_bf16 v[100:103], v[162:165], v[186:189], v[100:103]
	v_mfma_f32_16x16x32_bf16 v[96:99], v[170:173], v[186:189], v[96:99]
	v_mfma_f32_16x16x32_bf16 v[84:87], v[162:165], v[194:197], v[84:87]
	v_mfma_f32_16x16x32_bf16 v[80:83], v[170:173], v[194:197], v[80:83]
	v_mfma_f32_16x16x32_bf16 v[68:71], v[162:165], v[202:205], v[68:71]
	v_mfma_f32_16x16x32_bf16 v[64:67], v[170:173], v[202:205], v[64:67]
	s_barrier
; #define PG8_STAGE(bufoff, gbase, voff) do { _Pragma("unroll") for (int _i = 0; _i < 2; ++_i) \
;         __builtin_amdgcn_global_load_lds((const unsigned*)((const char*)(gbase) + (voff)[_i]), (LAS unsigned*)(lds + (bufoff) + ldsw + _i * 8192), 16, 0, 0); } while (0)
; #define PG8_LDA(dst, b, h) do { _Pragma("unroll") for (int m = 0; m < 4; ++m) _Pragma("unroll") for (int k = 0; k < 2; ++k) dst[m][k] = *(const LAS bf16x8*)(lds + PG8_SA(b, h) + aoff + m * 2048 + k * 1024); } while (0)
; #define PG8_LDB(dst, b, h) do { _Pragma("unroll") for (int n = 0; n < 2; ++n) _Pragma("unroll") for (int k = 0; k < 2; ++k) dst[n][k] = *(const LAS bf16x8*)(lds + PG8_SB(b, h) + boff + n * 2048 + k * 1024); } while (0)
; template <class Epi, class Sched, bool ALIGN_EPI>
; __device__ __forceinline__ void gemm_phase(LAS unsigned char* lds, const Gemm g, const Sched& S, const Epi& E, const int wid) {
;     ...
;         for (int t = 0; t < nt; t += 2) {
;             const bool last = (t == nt - 2);
;             if constexpr (Epi::HAS_PRE) { if (last) X.pre = E.pre(cur, tid); }
;             const char* a1 = cA + (size_t)(t + 1) * kstepA;
;             const char* a2 = last ? nA : cA + (size_t)(t + 2) * kstepA; const char* b2 = last ? nB : cB + (size_t)(t + 2) * kstep;
;             const char* a3 = a2 + kstepA; const char* b3 = b2 + kstep;
;             PG8_LDB(B0, 0, 0); PG8_LDB(B1, 0, 1); PG8_SCHED; PG8_LDA(At, 0, 0); PG8_STAGE(PG8_SA(1, 1), a1 + hstepA, voffA);
;             PG8_WAIT_V(8); PG8_WAIT_L(0); PG8_BAR; PG8_MMA(0, 0, At, B0); PG8_MMA(0, 1, At, B1); PG8_BAR; PG8_SCHED;
;             PG8_LDA(At, 0, 1); PG8_STAGE(PG8_SB(0, 0), b2, voffB); PG8_STAGE(PG8_SB(0, 1), b2 + hstepB, voffB); PG8_STAGE(PG8_SA(0, 0), a2, voffA);
;             PG8_WAIT_V(8); PG8_WAIT_L(0); PG8_BAR; PG8_MMA(1, 0, At, B0); PG8_MMA(1, 1, At, B1); PG8_BAR; PG8_SCHED;
;             PG8_LDB(B0, 1, 0); PG8_LDB(B1, 1, 1); PG8_SCHED; PG8_LDA(At, 1, 0); PG8_STAGE(PG8_SA(0, 1), a2 + hstepA, voffA);
;             PG8_WAIT_V(8); PG8_WAIT_L(0); PG8_BAR; PG8_MMA(0, 0, At, B0); PG8_MMA(0, 1, At, B1); PG8_BAR; PG8_SCHED;
;             PG8_LDA(At, 1, 1); PG8_STAGE(PG8_SB(1, 0), b3, voffB); PG8_STAGE(PG8_SB(1, 1), b3 + hstepB, voffB); PG8_STAGE(PG8_SA(1, 0), a3, voffA);
;             PG8_WAIT_V(8); PG8_WAIT_L(0); PG8_BAR; PG8_MMA(1, 0, At, B0); PG8_MMA(1, 1, At, B1); PG8_BAR; PG8_SCHED;
	s_setprio 0
	s_mov_b32 m0, s85
	v_lshl_add_u64 v[206:207], v[206:207], 0, s[18:19]
	ds_read_b128 v[174:177], v139 offset:49152
	ds_read_b128 v[178:181], v139 offset:50176
	ds_read_b128 v[182:185], v139 offset:51200
	ds_read_b128 v[186:189], v139 offset:52224
	ds_read_b128 v[190:193], v139 offset:53248
	ds_read_b128 v[194:197], v139 offset:54272
	ds_read_b128 v[198:201], v139 offset:55296
	ds_read_b128 v[202:205], v139 offset:56320
	global_load_lds_dwordx4 v[206:207], off
	v_lshl_add_u64 v[206:207], v[208:209], 0, s[18:19]
	s_mov_b32 m0, s86
	s_nop 0
	global_load_lds_dwordx4 v[206:207], off
	s_mov_b32 m0, s87
	s_nop 0
	global_load_lds_dwordx4 v132, s[58:59]
	s_mov_b32 m0, s89
	s_nop 0
	global_load_lds_dwordx4 v128, s[58:59]
	v_lshl_add_u64 v[206:207], v[210:211], 0, s[18:19]
	s_mov_b32 m0, s75
	s_nop 0
	global_load_lds_dwordx4 v[206:207], off
	v_lshl_add_u64 v[206:207], v[212:213], 0, s[18:19]
	s_mov_b32 m0, s76
	s_nop 0
	global_load_lds_dwordx4 v[206:207], off
	s_waitcnt vmcnt(8)
	s_waitcnt lgkmcnt(0)
	s_setprio 1
	s_barrier
	v_mfma_f32_16x16x32_bf16 v[60:63], v[142:145], v[174:177], v[60:63]
	v_mfma_f32_16x16x32_bf16 v[56:59], v[150:153], v[174:177], v[56:59]
	v_mfma_f32_16x16x32_bf16 v[44:47], v[142:145], v[182:185], v[44:47]
	v_mfma_f32_16x16x32_bf16 v[40:43], v[150:153], v[182:185], v[40:43]
	v_mfma_f32_16x16x32_bf16 v[28:31], v[142:145], v[190:193], v[28:31]
	v_mfma_f32_16x16x32_bf16 v[24:27], v[150:153], v[190:193], v[24:27]
	v_mfma_f32_16x16x32_bf16 v[12:15], v[142:145], v[198:201], v[12:15]
	v_mfma_f32_16x16x32_bf16 v[8:11], v[150:153], v[198:201], v[8:11]
	v_mfma_f32_16x16x32_bf16 v[60:63], v[146:149], v[178:181], v[60:63]
	v_mfma_f32_16x16x32_bf16 v[56:59], v[154:157], v[178:181], v[56:59]
	v_mfma_f32_16x16x32_bf16 v[44:47], v[146:149], v[186:189], v[44:47]
	v_mfma_f32_16x16x32_bf16 v[40:43], v[154:157], v[186:189], v[40:43]
	v_mfma_f32_16x16x32_bf16 v[28:31], v[146:149], v[194:197], v[28:31]
	v_mfma_f32_16x16x32_bf16 v[24:27], v[154:157], v[194:197], v[24:27]
	v_mfma_f32_16x16x32_bf16 v[12:15], v[146:149], v[202:205], v[12:15]
	v_mfma_f32_16x16x32_bf16 v[8:11], v[154:157], v[202:205], v[8:11]
	s_setprio 0
	s_setprio 1
	v_mfma_f32_16x16x32_bf16 v[52:55], v[158:161], v[174:177], v[52:55]
	v_mfma_f32_16x16x32_bf16 v[48:51], v[166:169], v[174:177], v[48:51]
	v_mfma_f32_16x16x32_bf16 v[36:39], v[158:161], v[182:185], v[36:39]
	v_mfma_f32_16x16x32_bf16 v[32:35], v[166:169], v[182:185], v[32:35]
	v_mfma_f32_16x16x32_bf16 v[20:23], v[158:161], v[190:193], v[20:23]
	v_mfma_f32_16x16x32_bf16 v[16:19], v[166:169], v[190:193], v[16:19]
	v_mfma_f32_16x16x32_bf16 v[4:7], v[158:161], v[198:201], v[4:7]
	v_mfma_f32_16x16x32_bf16 v[0:3], v[166:169], v[198:201], v[0:3]
	v_mfma_f32_16x16x32_bf16 v[52:55], v[162:165], v[178:181], v[52:55]
	v_mfma_f32_16x16x32_bf16 v[48:51], v[170:173], v[178:181], v[48:51]
	v_mfma_f32_16x16x32_bf16 v[36:39], v[162:165], v[186:189], v[36:39]
	v_mfma_f32_16x16x32_bf16 v[32:35], v[170:173], v[186:189], v[32:35]
	v_mfma_f32_16x16x32_bf16 v[20:23], v[162:165], v[194:197], v[20:23]
	v_mfma_f32_16x16x32_bf16 v[16:19], v[170:173], v[194:197], v[16:19]
	v_mfma_f32_16x16x32_bf16 v[4:7], v[162:165], v[202:205], v[4:7]
	v_mfma_f32_16x16x32_bf16 v[0:3], v[170:173], v[202:205], v[0:3]
	s_barrier
	s_setprio 0
	s_andn2_b64 vcc, exec, s[56:57]
	s_mov_b64 s[58:59], -1
	s_mov_b64 s[56:57], 0
	s_mov_b64 s[60:61], 0x100
	s_cbranch_vccz .LBB0_243
	s_and_b64 vcc, exec, s[28:29]
	s_cbranch_vccz .LBB0_246
	s_barrier

; #define PG8_STAGE(bufoff, gbase, voff) do { _Pragma("unroll") for (int _i = 0; _i < 2; ++_i) \
;         __builtin_amdgcn_global_load_lds((const unsigned*)((const char*)(gbase) + (voff)[_i]), (LAS unsigned*)(lds + (bufoff) + ldsw + _i * 8192), 16, 0, 0); } while (0)
; #define PG8_LDA(dst, b, h) do { _Pragma("unroll") for (int m = 0; m < 4; ++m) _Pragma("unroll") for (int k = 0; k < 2; ++k) dst[m][k] = *(const LAS bf16x8*)(lds + PG8_SA(b, h) + aoff + m * 2048 + k * 1024); } while (0)
; #define PG8_LDB(dst, b, h) do { _Pragma("unroll") for (int n = 0; n < 2; ++n) _Pragma("unroll") for (int k = 0; k < 2; ++k) dst[n][k] = *(const LAS bf16x8*)(lds + PG8_SB(b, h) + boff + n * 2048 + k * 1024); } while (0)
; template <class Epi, class Sched, bool ALIGN_EPI>
; __device__ __forceinline__ void gemm_phase(LAS unsigned char* lds, const Gemm g, const Sched& S, const Epi& E, const int wid) {
;     ...
;         for (int t = 0; t < nt; t += 2) {
;             const bool last = (t == nt - 2);
;             if constexpr (Epi::HAS_PRE) { if (last) X.pre = E.pre(cur, tid); }
;             const char* a1 = cA + (size_t)(t + 1) * kstepA;
;             const char* a2 = last ? nA : cA + (size_t)(t + 2) * kstepA; const char* b2 = last ? nB : cB + (size_t)(t + 2) * kstep;
;             const char* a3 = a2 + kstepA; const char* b3 = b2 + kstep;
;             PG8_LDB(B0, 0, 0); PG8_LDB(B1, 0, 1); PG8_SCHED; PG8_LDA(At, 0, 0); PG8_STAGE(PG8_SA(1, 1), a1 + hstepA, voffA);
;             PG8_WAIT_V(8); PG8_WAIT_L(0); PG8_BAR; PG8_MMA(0, 0, At, B0); PG8_MMA(0, 1, At, B1); PG8_BAR; PG8_SCHED;
;             PG8_LDA(At, 0, 1); PG8_STAGE(PG8_SB(0, 0), b2, voffB); PG8_STAGE(PG8_SB(0, 1), b2 + hstepB, voffB); PG8_STAGE(PG8_SA(0, 0), a2, voffA);
;             PG8_WAIT_V(8); PG8_WAIT_L(0); PG8_BAR; PG8_MMA(1, 0, At, B0); PG8_MMA(1, 1, At, B1); PG8_BAR; PG8_SCHED;
;             PG8_LDB(B0, 1, 0); PG8_LDB(B1, 1, 1); PG8_SCHED; PG8_LDA(At, 1, 0); PG8_STAGE(PG8_SA(0, 1), a2 + hstepA, voffA);
;             PG8_WAIT_V(8); PG8_WAIT_L(0); PG8_BAR; PG8_MMA(0, 0, At, B0); PG8_MMA(0, 1, At, B1); PG8_BAR; PG8_SCHED;
;             PG8_LDA(At, 1, 1); PG8_STAGE(PG8_SB(1, 0), b3, voffB); PG8_STAGE(PG8_SB(1, 1), b3 + hstepB, voffB); PG8_STAGE(PG8_SA(1, 0), a3, voffA);
;             PG8_WAIT_V(8); PG8_WAIT_L(0); PG8_BAR; PG8_MMA(1, 0, At, B0); PG8_MMA(1, 1, At, B1); PG8_BAR; PG8_SCHED;
.LBB0_282:
	ds_read_b128 v[40:43], v153
	ds_read_b128 v[44:47], v153 offset:1024
	ds_read_b128 v[156:159], v153 offset:2048
	ds_read_b128 v[160:163], v153 offset:3072
	ds_read_b128 v[164:167], v154
	ds_read_b128 v[168:171], v154 offset:1024
	ds_read_b128 v[172:175], v154 offset:2048
	ds_read_b128 v[176:179], v154 offset:3072
	s_add_u32 s24, s22, 0x100
	s_addc_u32 s25, s23, 0
	s_cmp_eq_u32 s68, 2
	s_cselect_b32 s55, s19, s25
	s_cselect_b32 s54, s18, s24
	s_cselect_b32 s27, s21, s67
	s_cselect_b32 s26, s20, s13
	s_mov_b32 m0, s63
	v_lshl_add_u64 v[212:213], s[22:23], 0, v[146:147]
	ds_read_b128 v[180:183], v155
	ds_read_b128 v[184:187], v155 offset:1024
	ds_read_b128 v[188:191], v155 offset:2048
	ds_read_b128 v[192:195], v155 offset:3072
	ds_read_b128 v[196:199], v155 offset:4096
	ds_read_b128 v[200:203], v155 offset:5120
	ds_read_b128 v[204:207], v155 offset:6144
	ds_read_b128 v[208:211], v155 offset:7168
	global_load_lds_dwordx4 v[212:213], off
	v_lshl_add_u64 v[212:213], s[22:23], 0, v[148:149]
	s_mov_b32 m0, s64
	s_nop 0
	global_load_lds_dwordx4 v[212:213], off
	s_waitcnt vmcnt(8)
	s_waitcnt lgkmcnt(0)
	s_setprio 1
	s_barrier
	v_mfma_f32_16x16x32_bf16 v[132:135], v[40:43], v[180:183], v[132:135]
	v_mfma_f32_16x16x32_bf16 v[128:131], v[156:159], v[180:183], v[128:131]
	v_mfma_f32_16x16x32_bf16 v[116:119], v[40:43], v[188:191], v[116:119]
	v_mfma_f32_16x16x32_bf16 v[112:115], v[156:159], v[188:191], v[112:115]
	v_mfma_f32_16x16x32_bf16 v[100:103], v[40:43], v[196:199], v[100:103]
	v_mfma_f32_16x16x32_bf16 v[96:99], v[156:159], v[196:199], v[96:99]
	v_mfma_f32_16x16x32_bf16 v[84:87], v[40:43], v[204:207], v[84:87]
	v_mfma_f32_16x16x32_bf16 v[80:83], v[156:159], v[204:207], v[80:83]
	v_mfma_f32_16x16x32_bf16 v[132:135], v[44:47], v[184:187], v[132:135]
	v_mfma_f32_16x16x32_bf16 v[128:131], v[160:163], v[184:187], v[128:131]
	v_mfma_f32_16x16x32_bf16 v[116:119], v[44:47], v[192:195], v[116:119]
	v_mfma_f32_16x16x32_bf16 v[112:115], v[160:163], v[192:195], v[112:115]
	v_mfma_f32_16x16x32_bf16 v[100:103], v[44:47], v[200:203], v[100:103]
	v_mfma_f32_16x16x32_bf16 v[96:99], v[160:163], v[200:203], v[96:99]
	v_mfma_f32_16x16x32_bf16 v[84:87], v[44:47], v[208:211], v[84:87]
	v_mfma_f32_16x16x32_bf16 v[80:83], v[160:163], v[208:211], v[80:83]
	s_setprio 0
	s_setprio 1
	v_mfma_f32_16x16x32_bf16 v[124:127], v[164:167], v[180:183], v[124:127]
	v_mfma_f32_16x16x32_bf16 v[120:123], v[172:175], v[180:183], v[120:123]
	v_mfma_f32_16x16x32_bf16 v[108:111], v[164:167], v[188:191], v[108:111]
	v_mfma_f32_16x16x32_bf16 v[104:107], v[172:175], v[188:191], v[104:107]
	v_mfma_f32_16x16x32_bf16 v[92:95], v[164:167], v[196:199], v[92:95]
	v_mfma_f32_16x16x32_bf16 v[88:91], v[172:175], v[196:199], v[88:91]
	v_mfma_f32_16x16x32_bf16 v[76:79], v[164:167], v[204:207], v[76:79]
	v_mfma_f32_16x16x32_bf16 v[72:75], v[172:175], v[204:207], v[72:75]
	v_mfma_f32_16x16x32_bf16 v[124:127], v[168:171], v[184:187], v[124:127]
	v_mfma_f32_16x16x32_bf16 v[120:123], v[176:179], v[184:187], v[120:123]
	v_mfma_f32_16x16x32_bf16 v[108:111], v[168:171], v[192:195], v[108:111]
	v_mfma_f32_16x16x32_bf16 v[104:107], v[176:179], v[192:195], v[104:107]
	v_mfma_f32_16x16x32_bf16 v[92:95], v[168:171], v[200:203], v[92:95]
	v_mfma_f32_16x16x32_bf16 v[88:91], v[176:179], v[200:203], v[88:91]
	v_mfma_f32_16x16x32_bf16 v[76:79], v[168:171], v[208:211], v[76:79]
	v_mfma_f32_16x16x32_bf16 v[72:75], v[176:179], v[208:211], v[72:75]
	s_barrier
	s_setprio 0
	s_add_i32 s22, s61, s3
	v_lshl_add_u64 v[212:213], s[26:27], 0, v[140:141]
	s_mov_b32 m0, s22
	ds_read_b128 v[180:183], v155 offset:16384
	ds_read_b128 v[184:187], v155 offset:17408
	ds_read_b128 v[188:191], v155 offset:18432
	ds_read_b128 v[192:195], v155 offset:19456
	ds_read_b128 v[196:199], v155 offset:20480
	ds_read_b128 v[200:203], v155 offset:21504
	ds_read_b128 v[204:207], v155 offset:22528
	ds_read_b128 v[208:211], v155 offset:23552
	global_load_lds_dwordx4 v[212:213], off
	s_add_i32 m0, s22, 0x2000
	s_add_u32 s22, s26, 0x6000
	v_lshl_add_u64 v[214:215], s[26:27], 0, v[136:137]
	s_addc_u32 s23, s27, 0
	s_add_i32 s38, s62, s3
	global_load_lds_dwordx4 v[214:215], off
	s_mov_b32 m0, s38
	v_lshl_add_u64 v[218:219], s[54:55], 0, v[138:139]
	global_load_lds_dwordx4 v140, s[22:23]
	s_add_i32 m0, s38, 0x2000
	s_nop 0
	global_load_lds_dwordx4 v136, s[22:23]
	v_lshl_add_u64 v[216:217], s[54:55], 0, v[142:143]
	s_mov_b32 m0, s52
	s_nop 0
	global_load_lds_dwordx4 v[216:217], off
	s_mov_b32 m0, s53
	s_nop 0
	global_load_lds_dwordx4 v[218:219], off
	s_waitcnt vmcnt(8)
	s_waitcnt lgkmcnt(0)
	s_setprio 1
	s_barrier
; #define PG8_STAGE(bufoff, gbase, voff) do { _Pragma("unroll") for (int _i = 0; _i < 2; ++_i) \
;         __builtin_amdgcn_global_load_lds((const unsigned*)((const char*)(gbase) + (voff)[_i]), (LAS unsigned*)(lds + (bufoff) + ldsw + _i * 8192), 16, 0, 0); } while (0)
; #define PG8_LDA(dst, b, h) do { _Pragma("unroll") for (int m = 0; m < 4; ++m) _Pragma("unroll") for (int k = 0; k < 2; ++k) dst[m][k] = *(const LAS bf16x8*)(lds + PG8_SA(b, h) + aoff + m * 2048 + k * 1024); } while (0)
; #define PG8_LDB(dst, b, h) do { _Pragma("unroll") for (int n = 0; n < 2; ++n) _Pragma("unroll") for (int k = 0; k < 2; ++k) dst[n][k] = *(const LAS bf16x8*)(lds + PG8_SB(b, h) + boff + n * 2048 + k * 1024); } while (0)
; template <class Epi, class Sched, bool ALIGN_EPI>
; __device__ __forceinline__ void gemm_phase(LAS unsigned char* lds, const Gemm g, const Sched& S, const Epi& E, const int wid) {
;     ...
;         for (int t = 0; t < nt; t += 2) {
;             const bool last = (t == nt - 2);
;             if constexpr (Epi::HAS_PRE) { if (last) X.pre = E.pre(cur, tid); }
;             const char* a1 = cA + (size_t)(t + 1) * kstepA;
;             const char* a2 = last ? nA : cA + (size_t)(t + 2) * kstepA; const char* b2 = last ? nB : cB + (size_t)(t + 2) * kstep;
;             const char* a3 = a2 + kstepA; const char* b3 = b2 + kstep;
;             PG8_LDB(B0, 0, 0); PG8_LDB(B1, 0, 1); PG8_SCHED; PG8_LDA(At, 0, 0); PG8_STAGE(PG8_SA(1, 1), a1 + hstepA, voffA);
;             PG8_WAIT_V(8); PG8_WAIT_L(0); PG8_BAR; PG8_MMA(0, 0, At, B0); PG8_MMA(0, 1, At, B1); PG8_BAR; PG8_SCHED;
;             PG8_LDA(At, 0, 1); PG8_STAGE(PG8_SB(0, 0), b2, voffB); PG8_STAGE(PG8_SB(0, 1), b2 + hstepB, voffB); PG8_STAGE(PG8_SA(0, 0), a2, voffA);
;             PG8_WAIT_V(8); PG8_WAIT_L(0); PG8_BAR; PG8_MMA(1, 0, At, B0); PG8_MMA(1, 1, At, B1); PG8_BAR; PG8_SCHED;
;             PG8_LDB(B0, 1, 0); PG8_LDB(B1, 1, 1); PG8_SCHED; PG8_LDA(At, 1, 0); PG8_STAGE(PG8_SA(0, 1), a2 + hstepA, voffA);
;             PG8_WAIT_V(8); PG8_WAIT_L(0); PG8_BAR; PG8_MMA(0, 0, At, B0); PG8_MMA(0, 1, At, B1); PG8_BAR; PG8_SCHED;
;             PG8_LDA(At, 1, 1); PG8_STAGE(PG8_SB(1, 0), b3, voffB); PG8_STAGE(PG8_SB(1, 1), b3 + hstepB, voffB); PG8_STAGE(PG8_SA(1, 0), a3, voffA);
;             PG8_WAIT_V(8); PG8_WAIT_L(0); PG8_BAR; PG8_MMA(1, 0, At, B0); PG8_MMA(1, 1, At, B1); PG8_BAR; PG8_SCHED;
	v_mfma_f32_16x16x32_bf16 v[68:71], v[40:43], v[180:183], v[68:71]
	v_mfma_f32_16x16x32_bf16 v[64:67], v[156:159], v[180:183], v[64:67]
	v_mfma_f32_16x16x32_bf16 v[52:55], v[40:43], v[188:191], v[52:55]
	v_mfma_f32_16x16x32_bf16 v[48:51], v[156:159], v[188:191], v[48:51]
	v_mfma_f32_16x16x32_bf16 v[28:31], v[40:43], v[196:199], v[28:31]
	v_mfma_f32_16x16x32_bf16 v[24:27], v[156:159], v[196:199], v[24:27]
	v_mfma_f32_16x16x32_bf16 v[12:15], v[40:43], v[204:207], v[12:15]
	v_mfma_f32_16x16x32_bf16 v[8:11], v[156:159], v[204:207], v[8:11]
	v_mfma_f32_16x16x32_bf16 v[68:71], v[44:47], v[184:187], v[68:71]
	v_mfma_f32_16x16x32_bf16 v[64:67], v[160:163], v[184:187], v[64:67]
	v_mfma_f32_16x16x32_bf16 v[52:55], v[44:47], v[192:195], v[52:55]
	v_mfma_f32_16x16x32_bf16 v[48:51], v[160:163], v[192:195], v[48:51]
	v_mfma_f32_16x16x32_bf16 v[28:31], v[44:47], v[200:203], v[28:31]
	v_mfma_f32_16x16x32_bf16 v[24:27], v[160:163], v[200:203], v[24:27]
	v_mfma_f32_16x16x32_bf16 v[12:15], v[44:47], v[208:211], v[12:15]
	v_mfma_f32_16x16x32_bf16 v[8:11], v[160:163], v[208:211], v[8:11]
	s_setprio 0
	s_setprio 1
	v_mfma_f32_16x16x32_bf16 v[36:39], v[164:167], v[188:191], v[36:39]
	v_mfma_f32_16x16x32_bf16 v[32:35], v[172:175], v[188:191], v[32:35]
	v_mfma_f32_16x16x32_bf16 v[20:23], v[164:167], v[196:199], v[20:23]
	v_mfma_f32_16x16x32_bf16 v[16:19], v[172:175], v[196:199], v[16:19]
	v_mfma_f32_16x16x32_bf16 v[4:7], v[164:167], v[204:207], v[4:7]
	v_mfma_f32_16x16x32_bf16 v[0:3], v[172:175], v[204:207], v[0:3]
	v_mfma_f32_16x16x32_bf16 v[40:43], v[164:167], v[180:183], v[60:63]
	v_mfma_f32_16x16x32_bf16 v[44:47], v[172:175], v[180:183], v[56:59]
	v_mfma_f32_16x16x32_bf16 v[36:39], v[168:171], v[192:195], v[36:39]
	v_mfma_f32_16x16x32_bf16 v[32:35], v[176:179], v[192:195], v[32:35]
	v_mfma_f32_16x16x32_bf16 v[20:23], v[168:171], v[200:203], v[20:23]
	v_mfma_f32_16x16x32_bf16 v[16:19], v[176:179], v[200:203], v[16:19]
	v_mfma_f32_16x16x32_bf16 v[4:7], v[168:171], v[208:211], v[4:7]
	v_mfma_f32_16x16x32_bf16 v[0:3], v[176:179], v[208:211], v[0:3]
	v_mfma_f32_16x16x32_bf16 v[40:43], v[168:171], v[184:187], v[40:43]
	v_mfma_f32_16x16x32_bf16 v[44:47], v[176:179], v[184:187], v[44:47]
	s_barrier
	s_setprio 0
	s_add_i32 s38, 0, 0x18000
	s_add_i32 s39, 0, 0x1c000
	v_add_u32_e32 v160, s38, v150
	v_add_u32_e32 v176, s39, v150
	ds_read_b128 v[56:59], v160
	ds_read_b128 v[60:63], v160 offset:1024
	ds_read_b128 v[156:159], v160 offset:2048
	ds_read_b128 v[160:163], v160 offset:3072
	ds_read_b128 v[164:167], v176
	ds_read_b128 v[168:171], v176 offset:1024
	ds_read_b128 v[172:175], v176 offset:2048
	ds_read_b128 v[176:179], v176 offset:3072
	s_add_u32 s22, s54, 0x18000
	s_addc_u32 s23, s55, 0
	s_mov_b32 m0, s56
	ds_read_b128 v[180:183], v155 offset:32768
	ds_read_b128 v[184:187], v155 offset:33792
	ds_read_b128 v[188:191], v155 offset:34816
	ds_read_b128 v[192:195], v155 offset:35840
	ds_read_b128 v[196:199], v155 offset:36864
	ds_read_b128 v[200:203], v155 offset:37888
	ds_read_b128 v[204:207], v155 offset:38912
	ds_read_b128 v[208:211], v155 offset:39936
	global_load_lds_dwordx4 v142, s[22:23]
	s_mov_b32 m0, s57
	s_nop 0
	global_load_lds_dwordx4 v138, s[22:23]
	s_waitcnt vmcnt(8)
	s_waitcnt lgkmcnt(0)
	s_setprio 1
	s_barrier
	v_mfma_f32_16x16x32_bf16 v[132:135], v[56:59], v[180:183], v[132:135]
	v_mfma_f32_16x16x32_bf16 v[128:131], v[156:159], v[180:183], v[128:131]
	v_mfma_f32_16x16x32_bf16 v[116:119], v[56:59], v[188:191], v[116:119]
	v_mfma_f32_16x16x32_bf16 v[112:115], v[156:159], v[188:191], v[112:115]
	v_mfma_f32_16x16x32_bf16 v[100:103], v[56:59], v[196:199], v[100:103]
	v_mfma_f32_16x16x32_bf16 v[96:99], v[156:159], v[196:199], v[96:99]
	v_mfma_f32_16x16x32_bf16 v[84:87], v[56:59], v[204:207], v[84:87]
	v_mfma_f32_16x16x32_bf16 v[80:83], v[156:159], v[204:207], v[80:83]
	v_mfma_f32_16x16x32_bf16 v[132:135], v[60:63], v[184:187], v[132:135]
	v_mfma_f32_16x16x32_bf16 v[128:131], v[160:163], v[184:187], v[128:131]
	v_mfma_f32_16x16x32_bf16 v[116:119], v[60:63], v[192:195], v[116:119]
	v_mfma_f32_16x16x32_bf16 v[112:115], v[160:163], v[192:195], v[112:115]
	v_mfma_f32_16x16x32_bf16 v[100:103], v[60:63], v[200:203], v[100:103]
	v_mfma_f32_16x16x32_bf16 v[96:99], v[160:163], v[200:203], v[96:99]
	v_mfma_f32_16x16x32_bf16 v[84:87], v[60:63], v[208:211], v[84:87]
	v_mfma_f32_16x16x32_bf16 v[80:83], v[160:163], v[208:211], v[80:83]
	s_setprio 0
	s_setprio 1
	v_mfma_f32_16x16x32_bf16 v[124:127], v[164:167], v[180:183], v[124:127]
	v_mfma_f32_16x16x32_bf16 v[120:123], v[172:175], v[180:183], v[120:123]
	v_mfma_f32_16x16x32_bf16 v[108:111], v[164:167], v[188:191], v[108:111]
	v_mfma_f32_16x16x32_bf16 v[104:107], v[172:175], v[188:191], v[104:107]
	v_mfma_f32_16x16x32_bf16 v[92:95], v[164:167], v[196:199], v[92:95]
	v_mfma_f32_16x16x32_bf16 v[88:91], v[172:175], v[196:199], v[88:91]
	v_mfma_f32_16x16x32_bf16 v[76:79], v[164:167], v[204:207], v[76:79]
	v_mfma_f32_16x16x32_bf16 v[72:75], v[172:175], v[204:207], v[72:75]
	v_mfma_f32_16x16x32_bf16 v[124:127], v[168:171], v[184:187], v[124:127]
	v_mfma_f32_16x16x32_bf16 v[120:123], v[176:179], v[184:187], v[120:123]
	v_mfma_f32_16x16x32_bf16 v[108:111], v[168:171], v[192:195], v[108:111]
	v_mfma_f32_16x16x32_bf16 v[104:107], v[176:179], v[192:195], v[104:107]
	v_mfma_f32_16x16x32_bf16 v[92:95], v[168:171], v[200:203], v[92:95]
	v_mfma_f32_16x16x32_bf16 v[88:91], v[176:179], v[200:203], v[88:91]
	v_mfma_f32_16x16x32_bf16 v[76:79], v[168:171], v[208:211], v[76:79]
	v_mfma_f32_16x16x32_bf16 v[72:75], v[176:179], v[208:211], v[72:75]
	s_barrier
; #define PG8_STAGE(bufoff, gbase, voff) do { _Pragma("unroll") for (int _i = 0; _i < 2; ++_i) \
;         __builtin_amdgcn_global_load_lds((const unsigned*)((const char*)(gbase) + (voff)[_i]), (LAS unsigned*)(lds + (bufoff) + ldsw + _i * 8192), 16, 0, 0); } while (0)
; #define PG8_LDA(dst, b, h) do { _Pragma("unroll") for (int m = 0; m < 4; ++m) _Pragma("unroll") for (int k = 0; k < 2; ++k) dst[m][k] = *(const LAS bf16x8*)(lds + PG8_SA(b, h) + aoff + m * 2048 + k * 1024); } while (0)
; #define PG8_LDB(dst, b, h) do { _Pragma("unroll") for (int n = 0; n < 2; ++n) _Pragma("unroll") for (int k = 0; k < 2; ++k) dst[n][k] = *(const LAS bf16x8*)(lds + PG8_SB(b, h) + boff + n * 2048 + k * 1024); } while (0)
; template <class Epi, class Sched, bool ALIGN_EPI>
; __device__ __forceinline__ void gemm_phase(LAS unsigned char* lds, const Gemm g, const Sched& S, const Epi& E, const int wid) {
;     ...
;         for (int t = 0; t < nt; t += 2) {
;             const bool last = (t == nt - 2);
;             if constexpr (Epi::HAS_PRE) { if (last) X.pre = E.pre(cur, tid); }
;             const char* a1 = cA + (size_t)(t + 1) * kstepA;
;             const char* a2 = last ? nA : cA + (size_t)(t + 2) * kstepA; const char* b2 = last ? nB : cB + (size_t)(t + 2) * kstep;
;             const char* a3 = a2 + kstepA; const char* b3 = b2 + kstep;
;             PG8_LDB(B0, 0, 0); PG8_LDB(B1, 0, 1); PG8_SCHED; PG8_LDA(At, 0, 0); PG8_STAGE(PG8_SA(1, 1), a1 + hstepA, voffA);
;             PG8_WAIT_V(8); PG8_WAIT_L(0); PG8_BAR; PG8_MMA(0, 0, At, B0); PG8_MMA(0, 1, At, B1); PG8_BAR; PG8_SCHED;
;             PG8_LDA(At, 0, 1); PG8_STAGE(PG8_SB(0, 0), b2, voffB); PG8_STAGE(PG8_SB(0, 1), b2 + hstepB, voffB); PG8_STAGE(PG8_SA(0, 0), a2, voffA);
;             PG8_WAIT_V(8); PG8_WAIT_L(0); PG8_BAR; PG8_MMA(1, 0, At, B0); PG8_MMA(1, 1, At, B1); PG8_BAR; PG8_SCHED;
;             PG8_LDB(B0, 1, 0); PG8_LDB(B1, 1, 1); PG8_SCHED; PG8_LDA(At, 1, 0); PG8_STAGE(PG8_SA(0, 1), a2 + hstepA, voffA);
;             PG8_WAIT_V(8); PG8_WAIT_L(0); PG8_BAR; PG8_MMA(0, 0, At, B0); PG8_MMA(0, 1, At, B1); PG8_BAR; PG8_SCHED;
;             PG8_LDA(At, 1, 1); PG8_STAGE(PG8_SB(1, 0), b3, voffB); PG8_STAGE(PG8_SB(1, 1), b3 + hstepB, voffB); PG8_STAGE(PG8_SA(1, 0), a3, voffA);
;             PG8_WAIT_V(8); PG8_WAIT_L(0); PG8_BAR; PG8_MMA(1, 0, At, B0); PG8_MMA(1, 1, At, B1); PG8_BAR; PG8_SCHED;
	s_setprio 0
	s_add_i32 s22, s38, s3
	v_lshl_add_u64 v[212:213], v[212:213], 0, s[16:17]
	s_mov_b32 m0, s22
	ds_read_b128 v[180:183], v155 offset:49152
	ds_read_b128 v[184:187], v155 offset:50176
	ds_read_b128 v[188:191], v155 offset:51200
	ds_read_b128 v[192:195], v155 offset:52224
	ds_read_b128 v[196:199], v155 offset:53248
	ds_read_b128 v[200:203], v155 offset:54272
	ds_read_b128 v[204:207], v155 offset:55296
	ds_read_b128 v[208:211], v155 offset:56320
	global_load_lds_dwordx4 v[212:213], off
	s_add_i32 m0, s22, 0x2000
	s_add_u32 s22, s26, 0x6080
	v_lshl_add_u64 v[212:213], v[214:215], 0, s[16:17]
	s_addc_u32 s23, s27, 0
	s_add_i32 s26, s39, s3
	global_load_lds_dwordx4 v[212:213], off
	s_mov_b32 m0, s26
	s_nop 0
	global_load_lds_dwordx4 v140, s[22:23]
	s_add_i32 m0, s26, 0x2000
	s_nop 0
	global_load_lds_dwordx4 v136, s[22:23]
	v_lshl_add_u64 v[212:213], v[216:217], 0, s[16:17]
	s_mov_b32 m0, s30
	s_nop 0
	global_load_lds_dwordx4 v[212:213], off
	v_lshl_add_u64 v[212:213], v[218:219], 0, s[16:17]
	s_mov_b32 m0, s31
	s_nop 0
	global_load_lds_dwordx4 v[212:213], off
	s_waitcnt vmcnt(8)
	s_waitcnt lgkmcnt(0)
	s_setprio 1
	s_barrier
	v_mfma_f32_16x16x32_bf16 v[68:71], v[56:59], v[180:183], v[68:71]
	v_mfma_f32_16x16x32_bf16 v[64:67], v[156:159], v[180:183], v[64:67]
	v_mfma_f32_16x16x32_bf16 v[52:55], v[56:59], v[188:191], v[52:55]
	v_mfma_f32_16x16x32_bf16 v[48:51], v[156:159], v[188:191], v[48:51]
	v_mfma_f32_16x16x32_bf16 v[28:31], v[56:59], v[196:199], v[28:31]
	v_mfma_f32_16x16x32_bf16 v[24:27], v[156:159], v[196:199], v[24:27]
	v_mfma_f32_16x16x32_bf16 v[12:15], v[56:59], v[204:207], v[12:15]
	v_mfma_f32_16x16x32_bf16 v[8:11], v[156:159], v[204:207], v[8:11]
	v_mfma_f32_16x16x32_bf16 v[68:71], v[60:63], v[184:187], v[68:71]
	v_mfma_f32_16x16x32_bf16 v[64:67], v[160:163], v[184:187], v[64:67]
	v_mfma_f32_16x16x32_bf16 v[52:55], v[60:63], v[192:195], v[52:55]
	v_mfma_f32_16x16x32_bf16 v[48:51], v[160:163], v[192:195], v[48:51]
	v_mfma_f32_16x16x32_bf16 v[28:31], v[60:63], v[200:203], v[28:31]
	v_mfma_f32_16x16x32_bf16 v[24:27], v[160:163], v[200:203], v[24:27]
	v_mfma_f32_16x16x32_bf16 v[12:15], v[60:63], v[208:211], v[12:15]
	v_mfma_f32_16x16x32_bf16 v[8:11], v[160:163], v[208:211], v[8:11]
	s_setprio 0
	s_setprio 1
	v_mfma_f32_16x16x32_bf16 v[40:43], v[164:167], v[180:183], v[40:43]
	v_mfma_f32_16x16x32_bf16 v[60:63], v[168:171], v[184:187], v[40:43]
	v_mfma_f32_16x16x32_bf16 v[40:43], v[172:175], v[180:183], v[44:47]
	v_mfma_f32_16x16x32_bf16 v[36:39], v[164:167], v[188:191], v[36:39]
	v_mfma_f32_16x16x32_bf16 v[32:35], v[172:175], v[188:191], v[32:35]
	v_mfma_f32_16x16x32_bf16 v[20:23], v[164:167], v[196:199], v[20:23]
	v_mfma_f32_16x16x32_bf16 v[16:19], v[172:175], v[196:199], v[16:19]
	v_mfma_f32_16x16x32_bf16 v[4:7], v[164:167], v[204:207], v[4:7]
	v_mfma_f32_16x16x32_bf16 v[0:3], v[172:175], v[204:207], v[0:3]
	v_mfma_f32_16x16x32_bf16 v[56:59], v[176:179], v[184:187], v[40:43]
	v_mfma_f32_16x16x32_bf16 v[36:39], v[168:171], v[192:195], v[36:39]
	v_mfma_f32_16x16x32_bf16 v[32:35], v[176:179], v[192:195], v[32:35]
	v_mfma_f32_16x16x32_bf16 v[20:23], v[168:171], v[200:203], v[20:23]
	v_mfma_f32_16x16x32_bf16 v[16:19], v[176:179], v[200:203], v[16:19]
	v_mfma_f32_16x16x32_bf16 v[4:7], v[168:171], v[208:211], v[4:7]
	v_mfma_f32_16x16x32_bf16 v[0:3], v[176:179], v[208:211], v[0:3]
	s_barrier
	s_setprio 0
	s_add_i32 s68, s68, 2
	s_add_u32 s13, s13, 0x100
	s_addc_u32 s67, s67, 0
	s_cmp_gt_u32 s68, 3
	s_mov_b64 s[22:23], s[24:25]
	s_cbranch_scc0 .LBB0_282
	s_and_b64 vcc, exec, s[28:29]
	s_cbranch_vccz .LBB0_285
	s_barrier

; #define PG8_STAGE(bufoff, gbase, voff) do { _Pragma("unroll") for (int _i = 0; _i < 2; ++_i) \
;         __builtin_amdgcn_global_load_lds((const unsigned*)((const char*)(gbase) + (voff)[_i]), (LAS unsigned*)(lds + (bufoff) + ldsw + _i * 8192), 16, 0, 0); } while (0)
; #define PG8_LDA(dst, b, h) do { _Pragma("unroll") for (int m = 0; m < 4; ++m) _Pragma("unroll") for (int k = 0; k < 2; ++k) dst[m][k] = *(const LAS bf16x8*)(lds + PG8_SA(b, h) + aoff + m * 2048 + k * 1024); } while (0)
; #define PG8_LDB(dst, b, h) do { _Pragma("unroll") for (int n = 0; n < 2; ++n) _Pragma("unroll") for (int k = 0; k < 2; ++k) dst[n][k] = *(const LAS bf16x8*)(lds + PG8_SB(b, h) + boff + n * 2048 + k * 1024); } while (0)
; template <class Epi, class Sched, bool ALIGN_EPI>
; __device__ __forceinline__ void gemm_phase(LAS unsigned char* lds, const Gemm g, const Sched& S, const Epi& E, const int wid) {
;     ...
;         for (int t = 0; t < nt; t += 2) {
;             const bool last = (t == nt - 2);
;             if constexpr (Epi::HAS_PRE) { if (last) X.pre = E.pre(cur, tid); }
;             const char* a1 = cA + (size_t)(t + 1) * kstepA;
;             const char* a2 = last ? nA : cA + (size_t)(t + 2) * kstepA; const char* b2 = last ? nB : cB + (size_t)(t + 2) * kstep;
;             const char* a3 = a2 + kstepA; const char* b3 = b2 + kstep;
;             PG8_LDB(B0, 0, 0); PG8_LDB(B1, 0, 1); PG8_SCHED; PG8_LDA(At, 0, 0); PG8_STAGE(PG8_SA(1, 1), a1 + hstepA, voffA);
;             PG8_WAIT_V(8); PG8_WAIT_L(0); PG8_BAR; PG8_MMA(0, 0, At, B0); PG8_MMA(0, 1, At, B1); PG8_BAR; PG8_SCHED;
;             PG8_LDA(At, 0, 1); PG8_STAGE(PG8_SB(0, 0), b2, voffB); PG8_STAGE(PG8_SB(0, 1), b2 + hstepB, voffB); PG8_STAGE(PG8_SA(0, 0), a2, voffA);
;             PG8_WAIT_V(8); PG8_WAIT_L(0); PG8_BAR; PG8_MMA(1, 0, At, B0); PG8_MMA(1, 1, At, B1); PG8_BAR; PG8_SCHED;
;             PG8_LDB(B0, 1, 0); PG8_LDB(B1, 1, 1); PG8_SCHED; PG8_LDA(At, 1, 0); PG8_STAGE(PG8_SA(0, 1), a2 + hstepA, voffA);
;             PG8_WAIT_V(8); PG8_WAIT_L(0); PG8_BAR; PG8_MMA(0, 0, At, B0); PG8_MMA(0, 1, At, B1); PG8_BAR; PG8_SCHED;
;             PG8_LDA(At, 1, 1); PG8_STAGE(PG8_SB(1, 0), b3, voffB); PG8_STAGE(PG8_SB(1, 1), b3 + hstepB, voffB); PG8_STAGE(PG8_SA(1, 0), a3, voffA);
;             PG8_WAIT_V(8); PG8_WAIT_L(0); PG8_BAR; PG8_MMA(1, 0, At, B0); PG8_MMA(1, 1, At, B1); PG8_BAR; PG8_SCHED;
.LBB0_499:
	ds_read_b128 v[150:153], v147
	ds_read_b128 v[154:157], v147 offset:1024
	ds_read_b128 v[158:161], v147 offset:2048
	ds_read_b128 v[162:165], v147 offset:3072
	ds_read_b128 v[166:169], v148
	ds_read_b128 v[170:173], v148 offset:1024
	ds_read_b128 v[174:177], v148 offset:2048
	ds_read_b128 v[178:181], v148 offset:3072
	s_add_u32 s38, s24, 0xfff80080
	s_addc_u32 s39, s25, -1
	s_cmp_eq_u32 s67, 28
	s_cselect_b32 s57, s19, s39
	s_cselect_b32 s56, s27, s38
	s_cselect_b32 s55, s17, s66
	s_cselect_b32 s54, s64, s65
	s_add_i32 m0, s46, 0xc000
	ds_read_b128 v[182:185], v149
	ds_read_b128 v[186:189], v149 offset:1024
	ds_read_b128 v[190:193], v149 offset:2048
	ds_read_b128 v[194:197], v149 offset:3072
	ds_read_b128 v[198:201], v149 offset:4096
	ds_read_b128 v[202:205], v149 offset:5120
	ds_read_b128 v[206:209], v149 offset:6144
	ds_read_b128 v[210:213], v149 offset:7168
	global_load_lds_dwordx4 v136, s[24:25]
	s_add_i32 m0, s46, 0xe000
	s_nop 0
	global_load_lds_dwordx4 v138, s[24:25]
	s_waitcnt vmcnt(8)
	s_waitcnt lgkmcnt(0)
	s_setprio 1
	s_barrier
	v_mfma_f32_16x16x32_bf16 v[124:127], v[150:153], v[182:185], v[124:127]
	v_mfma_f32_16x16x32_bf16 v[120:123], v[158:161], v[182:185], v[120:123]
	v_mfma_f32_16x16x32_bf16 v[108:111], v[150:153], v[190:193], v[108:111]
	v_mfma_f32_16x16x32_bf16 v[104:107], v[158:161], v[190:193], v[104:107]
	v_mfma_f32_16x16x32_bf16 v[92:95], v[150:153], v[198:201], v[92:95]
	v_mfma_f32_16x16x32_bf16 v[88:91], v[158:161], v[198:201], v[88:91]
	v_mfma_f32_16x16x32_bf16 v[76:79], v[150:153], v[206:209], v[76:79]
	v_mfma_f32_16x16x32_bf16 v[72:75], v[158:161], v[206:209], v[72:75]
	v_mfma_f32_16x16x32_bf16 v[124:127], v[154:157], v[186:189], v[124:127]
	v_mfma_f32_16x16x32_bf16 v[120:123], v[162:165], v[186:189], v[120:123]
	v_mfma_f32_16x16x32_bf16 v[108:111], v[154:157], v[194:197], v[108:111]
	v_mfma_f32_16x16x32_bf16 v[104:107], v[162:165], v[194:197], v[104:107]
	v_mfma_f32_16x16x32_bf16 v[92:95], v[154:157], v[202:205], v[92:95]
	v_mfma_f32_16x16x32_bf16 v[88:91], v[162:165], v[202:205], v[88:91]
	v_mfma_f32_16x16x32_bf16 v[76:79], v[154:157], v[210:213], v[76:79]
	v_mfma_f32_16x16x32_bf16 v[72:75], v[162:165], v[210:213], v[72:75]
	s_setprio 0
	s_setprio 1
	v_mfma_f32_16x16x32_bf16 v[116:119], v[166:169], v[182:185], v[116:119]
	v_mfma_f32_16x16x32_bf16 v[112:115], v[174:177], v[182:185], v[112:115]
	v_mfma_f32_16x16x32_bf16 v[100:103], v[166:169], v[190:193], v[100:103]
	v_mfma_f32_16x16x32_bf16 v[96:99], v[174:177], v[190:193], v[96:99]
	v_mfma_f32_16x16x32_bf16 v[84:87], v[166:169], v[198:201], v[84:87]
	v_mfma_f32_16x16x32_bf16 v[80:83], v[174:177], v[198:201], v[80:83]
	v_mfma_f32_16x16x32_bf16 v[68:71], v[166:169], v[206:209], v[68:71]
	v_mfma_f32_16x16x32_bf16 v[64:67], v[174:177], v[206:209], v[64:67]
	v_mfma_f32_16x16x32_bf16 v[116:119], v[170:173], v[186:189], v[116:119]
	v_mfma_f32_16x16x32_bf16 v[112:115], v[178:181], v[186:189], v[112:115]
	v_mfma_f32_16x16x32_bf16 v[100:103], v[170:173], v[194:197], v[100:103]
	v_mfma_f32_16x16x32_bf16 v[96:99], v[178:181], v[194:197], v[96:99]
	v_mfma_f32_16x16x32_bf16 v[84:87], v[170:173], v[202:205], v[84:87]
	v_mfma_f32_16x16x32_bf16 v[80:83], v[178:181], v[202:205], v[80:83]
	v_mfma_f32_16x16x32_bf16 v[68:71], v[170:173], v[210:213], v[68:71]
	v_mfma_f32_16x16x32_bf16 v[64:67], v[178:181], v[210:213], v[64:67]
	s_barrier
	s_setprio 0
	s_add_i32 s38, s43, s3
	s_mov_b32 m0, s38
	ds_read_b128 v[182:185], v149 offset:16384
	ds_read_b128 v[186:189], v149 offset:17408
	ds_read_b128 v[190:193], v149 offset:18432
	ds_read_b128 v[194:197], v149 offset:19456
	ds_read_b128 v[198:201], v149 offset:20480
	ds_read_b128 v[202:205], v149 offset:21504
	ds_read_b128 v[206:209], v149 offset:22528
	ds_read_b128 v[210:213], v149 offset:23552
	global_load_lds_dwordx4 v132, s[54:55]
	s_add_i32 m0, s38, 0x2000
	s_add_u32 s68, s54, 0x1000
	s_addc_u32 s69, s55, 0
	s_add_i32 s38, s63, s3
	global_load_lds_dwordx4 v128, s[54:55]
	s_mov_b32 m0, s38
	v_lshl_add_u64 v[216:217], s[56:57], 0, v[130:131]
	global_load_lds_dwordx4 v132, s[68:69]
	s_add_i32 m0, s38, 0x2000
	s_nop 0
	global_load_lds_dwordx4 v128, s[68:69]
	v_lshl_add_u64 v[214:215], s[56:57], 0, v[134:135]
	s_mov_b32 m0, s46
	s_nop 0
	global_load_lds_dwordx4 v[214:215], off
	s_mov_b32 m0, s47
	s_nop 0
	global_load_lds_dwordx4 v[216:217], off
	s_waitcnt vmcnt(8)
	s_waitcnt lgkmcnt(0)
	s_setprio 1
	s_barrier
	v_mfma_f32_16x16x32_bf16 v[60:63], v[150:153], v[182:185], v[60:63]
	v_mfma_f32_16x16x32_bf16 v[56:59], v[158:161], v[182:185], v[56:59]
	v_mfma_f32_16x16x32_bf16 v[44:47], v[150:153], v[190:193], v[44:47]
	v_mfma_f32_16x16x32_bf16 v[40:43], v[158:161], v[190:193], v[40:43]
	v_mfma_f32_16x16x32_bf16 v[28:31], v[150:153], v[198:201], v[28:31]
	v_mfma_f32_16x16x32_bf16 v[24:27], v[158:161], v[198:201], v[24:27]
	v_mfma_f32_16x16x32_bf16 v[12:15], v[150:153], v[206:209], v[12:15]
	v_mfma_f32_16x16x32_bf16 v[8:11], v[158:161], v[206:209], v[8:11]
	v_mfma_f32_16x16x32_bf16 v[60:63], v[154:157], v[186:189], v[60:63]
	v_mfma_f32_16x16x32_bf16 v[56:59], v[162:165], v[186:189], v[56:59]
	v_mfma_f32_16x16x32_bf16 v[44:47], v[154:157], v[194:197], v[44:47]
	v_mfma_f32_16x16x32_bf16 v[40:43], v[162:165], v[194:197], v[40:43]
	v_mfma_f32_16x16x32_bf16 v[28:31], v[154:157], v[202:205], v[28:31]
	v_mfma_f32_16x16x32_bf16 v[24:27], v[162:165], v[202:205], v[24:27]
	v_mfma_f32_16x16x32_bf16 v[12:15], v[154:157], v[210:213], v[12:15]
	v_mfma_f32_16x16x32_bf16 v[8:11], v[162:165], v[210:213], v[8:11]
	s_setprio 0
	s_setprio 1
	v_mfma_f32_16x16x32_bf16 v[52:55], v[166:169], v[182:185], v[52:55]
	v_mfma_f32_16x16x32_bf16 v[48:51], v[174:177], v[182:185], v[48:51]
	v_mfma_f32_16x16x32_bf16 v[36:39], v[166:169], v[190:193], v[36:39]
	v_mfma_f32_16x16x32_bf16 v[32:35], v[174:177], v[190:193], v[32:35]
	v_mfma_f32_16x16x32_bf16 v[20:23], v[166:169], v[198:201], v[20:23]
	v_mfma_f32_16x16x32_bf16 v[16:19], v[174:177], v[198:201], v[16:19]
	v_mfma_f32_16x16x32_bf16 v[4:7], v[166:169], v[206:209], v[4:7]
	v_mfma_f32_16x16x32_bf16 v[0:3], v[174:177], v[206:209], v[0:3]
	v_mfma_f32_16x16x32_bf16 v[52:55], v[170:173], v[186:189], v[52:55]
	v_mfma_f32_16x16x32_bf16 v[48:51], v[178:181], v[186:189], v[48:51]
	v_mfma_f32_16x16x32_bf16 v[36:39], v[170:173], v[194:197], v[36:39]
	v_mfma_f32_16x16x32_bf16 v[32:35], v[178:181], v[194:197], v[32:35]
	v_mfma_f32_16x16x32_bf16 v[20:23], v[170:173], v[202:205], v[20:23]
	v_mfma_f32_16x16x32_bf16 v[16:19], v[178:181], v[202:205], v[16:19]
	v_mfma_f32_16x16x32_bf16 v[4:7], v[170:173], v[210:213], v[4:7]
	v_mfma_f32_16x16x32_bf16 v[0:3], v[178:181], v[210:213], v[0:3]
	s_barrier
; #define PG8_STAGE(bufoff, gbase, voff) do { _Pragma("unroll") for (int _i = 0; _i < 2; ++_i) \
;         __builtin_amdgcn_global_load_lds((const unsigned*)((const char*)(gbase) + (voff)[_i]), (LAS unsigned*)(lds + (bufoff) + ldsw + _i * 8192), 16, 0, 0); } while (0)
; #define PG8_LDA(dst, b, h) do { _Pragma("unroll") for (int m = 0; m < 4; ++m) _Pragma("unroll") for (int k = 0; k < 2; ++k) dst[m][k] = *(const LAS bf16x8*)(lds + PG8_SA(b, h) + aoff + m * 2048 + k * 1024); } while (0)
; #define PG8_LDB(dst, b, h) do { _Pragma("unroll") for (int n = 0; n < 2; ++n) _Pragma("unroll") for (int k = 0; k < 2; ++k) dst[n][k] = *(const LAS bf16x8*)(lds + PG8_SB(b, h) + boff + n * 2048 + k * 1024); } while (0)
; template <class Epi, class Sched, bool ALIGN_EPI>
; __device__ __forceinline__ void gemm_phase(LAS unsigned char* lds, const Gemm g, const Sched& S, const Epi& E, const int wid) {
;     ...
;         for (int t = 0; t < nt; t += 2) {
;             const bool last = (t == nt - 2);
;             if constexpr (Epi::HAS_PRE) { if (last) X.pre = E.pre(cur, tid); }
;             const char* a1 = cA + (size_t)(t + 1) * kstepA;
;             const char* a2 = last ? nA : cA + (size_t)(t + 2) * kstepA; const char* b2 = last ? nB : cB + (size_t)(t + 2) * kstep;
;             const char* a3 = a2 + kstepA; const char* b3 = b2 + kstep;
;             PG8_LDB(B0, 0, 0); PG8_LDB(B1, 0, 1); PG8_SCHED; PG8_LDA(At, 0, 0); PG8_STAGE(PG8_SA(1, 1), a1 + hstepA, voffA);
;             PG8_WAIT_V(8); PG8_WAIT_L(0); PG8_BAR; PG8_MMA(0, 0, At, B0); PG8_MMA(0, 1, At, B1); PG8_BAR; PG8_SCHED;
;             PG8_LDA(At, 0, 1); PG8_STAGE(PG8_SB(0, 0), b2, voffB); PG8_STAGE(PG8_SB(0, 1), b2 + hstepB, voffB); PG8_STAGE(PG8_SA(0, 0), a2, voffA);
;             PG8_WAIT_V(8); PG8_WAIT_L(0); PG8_BAR; PG8_MMA(1, 0, At, B0); PG8_MMA(1, 1, At, B1); PG8_BAR; PG8_SCHED;
;             PG8_LDB(B0, 1, 0); PG8_LDB(B1, 1, 1); PG8_SCHED; PG8_LDA(At, 1, 0); PG8_STAGE(PG8_SA(0, 1), a2 + hstepA, voffA);
;             PG8_WAIT_V(8); PG8_WAIT_L(0); PG8_BAR; PG8_MMA(0, 0, At, B0); PG8_MMA(0, 1, At, B1); PG8_BAR; PG8_SCHED;
;             PG8_LDA(At, 1, 1); PG8_STAGE(PG8_SB(1, 0), b3, voffB); PG8_STAGE(PG8_SB(1, 1), b3 + hstepB, voffB); PG8_STAGE(PG8_SA(1, 0), a3, voffA);
;             PG8_WAIT_V(8); PG8_WAIT_L(0); PG8_BAR; PG8_MMA(1, 0, At, B0); PG8_MMA(1, 1, At, B1); PG8_BAR; PG8_SCHED;
	s_setprio 0
	s_add_i32 s38, 0, 0x18000
	s_add_i32 s39, 0, 0x1c000
	v_add_u32_e32 v162, s38, v144
	v_add_u32_e32 v178, s39, v144
	ds_read_b128 v[150:153], v162
	ds_read_b128 v[154:157], v162 offset:1024
	ds_read_b128 v[158:161], v162 offset:2048
	ds_read_b128 v[162:165], v162 offset:3072
	ds_read_b128 v[166:169], v178
	ds_read_b128 v[170:173], v178 offset:1024
	ds_read_b128 v[174:177], v178 offset:2048
	ds_read_b128 v[178:181], v178 offset:3072
	s_add_u32 s56, s56, 0x80000
	s_addc_u32 s57, s57, 0
	s_mov_b32 m0, s52
	ds_read_b128 v[182:185], v149 offset:32768
	ds_read_b128 v[186:189], v149 offset:33792
	ds_read_b128 v[190:193], v149 offset:34816
	ds_read_b128 v[194:197], v149 offset:35840
	ds_read_b128 v[198:201], v149 offset:36864
	ds_read_b128 v[202:205], v149 offset:37888
	ds_read_b128 v[206:209], v149 offset:38912
	ds_read_b128 v[210:213], v149 offset:39936
	global_load_lds_dwordx4 v134, s[56:57]
	s_mov_b32 m0, s53
	s_nop 0
	global_load_lds_dwordx4 v130, s[56:57]
	s_waitcnt vmcnt(8)
	s_waitcnt lgkmcnt(0)
	s_setprio 1
	s_barrier
	v_mfma_f32_16x16x32_bf16 v[124:127], v[150:153], v[182:185], v[124:127]
	v_mfma_f32_16x16x32_bf16 v[120:123], v[158:161], v[182:185], v[120:123]
	v_mfma_f32_16x16x32_bf16 v[108:111], v[150:153], v[190:193], v[108:111]
	v_mfma_f32_16x16x32_bf16 v[104:107], v[158:161], v[190:193], v[104:107]
	v_mfma_f32_16x16x32_bf16 v[92:95], v[150:153], v[198:201], v[92:95]
	v_mfma_f32_16x16x32_bf16 v[88:91], v[158:161], v[198:201], v[88:91]
	v_mfma_f32_16x16x32_bf16 v[76:79], v[150:153], v[206:209], v[76:79]
	v_mfma_f32_16x16x32_bf16 v[72:75], v[158:161], v[206:209], v[72:75]
	v_mfma_f32_16x16x32_bf16 v[124:127], v[154:157], v[186:189], v[124:127]
	v_mfma_f32_16x16x32_bf16 v[120:123], v[162:165], v[186:189], v[120:123]
	v_mfma_f32_16x16x32_bf16 v[108:111], v[154:157], v[194:197], v[108:111]
	v_mfma_f32_16x16x32_bf16 v[104:107], v[162:165], v[194:197], v[104:107]
	v_mfma_f32_16x16x32_bf16 v[92:95], v[154:157], v[202:205], v[92:95]
	v_mfma_f32_16x16x32_bf16 v[88:91], v[162:165], v[202:205], v[88:91]
	v_mfma_f32_16x16x32_bf16 v[76:79], v[154:157], v[210:213], v[76:79]
	v_mfma_f32_16x16x32_bf16 v[72:75], v[162:165], v[210:213], v[72:75]
	s_setprio 0
	s_setprio 1
	v_mfma_f32_16x16x32_bf16 v[116:119], v[166:169], v[182:185], v[116:119]
	v_mfma_f32_16x16x32_bf16 v[112:115], v[174:177], v[182:185], v[112:115]
	v_mfma_f32_16x16x32_bf16 v[100:103], v[166:169], v[190:193], v[100:103]
	v_mfma_f32_16x16x32_bf16 v[96:99], v[174:177], v[190:193], v[96:99]
	v_mfma_f32_16x16x32_bf16 v[84:87], v[166:169], v[198:201], v[84:87]
	v_mfma_f32_16x16x32_bf16 v[80:83], v[174:177], v[198:201], v[80:83]
	v_mfma_f32_16x16x32_bf16 v[68:71], v[166:169], v[206:209], v[68:71]
	v_mfma_f32_16x16x32_bf16 v[64:67], v[174:177], v[206:209], v[64:67]
	v_mfma_f32_16x16x32_bf16 v[116:119], v[170:173], v[186:189], v[116:119]
	v_mfma_f32_16x16x32_bf16 v[112:115], v[178:181], v[186:189], v[112:115]
	v_mfma_f32_16x16x32_bf16 v[100:103], v[170:173], v[194:197], v[100:103]
	v_mfma_f32_16x16x32_bf16 v[96:99], v[178:181], v[194:197], v[96:99]
	v_mfma_f32_16x16x32_bf16 v[84:87], v[170:173], v[202:205], v[84:87]
	v_mfma_f32_16x16x32_bf16 v[80:83], v[178:181], v[202:205], v[80:83]
	v_mfma_f32_16x16x32_bf16 v[68:71], v[170:173], v[210:213], v[68:71]
	v_mfma_f32_16x16x32_bf16 v[64:67], v[178:181], v[210:213], v[64:67]
	s_barrier
	s_setprio 0
	s_add_u32 s56, s54, 0x8000
	s_addc_u32 s57, s55, 0
	s_add_i32 s38, s38, s3
	s_mov_b32 m0, s38
	ds_read_b128 v[182:185], v149 offset:49152
	ds_read_b128 v[186:189], v149 offset:50176
	ds_read_b128 v[190:193], v149 offset:51200
	ds_read_b128 v[194:197], v149 offset:52224
	ds_read_b128 v[198:201], v149 offset:53248
	ds_read_b128 v[202:205], v149 offset:54272
	ds_read_b128 v[206:209], v149 offset:55296
	ds_read_b128 v[210:213], v149 offset:56320
	global_load_lds_dwordx4 v132, s[56:57]
	s_add_i32 m0, s38, 0x2000
	s_add_u32 s54, s54, 0x9000
	s_addc_u32 s55, s55, 0
	s_add_i32 s38, s39, s3
	global_load_lds_dwordx4 v128, s[56:57]
	s_mov_b32 m0, s38
	v_lshl_add_u64 v[214:215], v[214:215], 0, s[12:13]
	global_load_lds_dwordx4 v132, s[54:55]
	s_add_i32 m0, s38, 0x2000
	s_nop 0
	global_load_lds_dwordx4 v128, s[54:55]
	s_mov_b32 m0, s61
	s_nop 0
	global_load_lds_dwordx4 v[214:215], off
	v_lshl_add_u64 v[214:215], v[216:217], 0, s[12:13]
	s_mov_b32 m0, s62
	s_nop 0
	global_load_lds_dwordx4 v[214:215], off
	s_waitcnt vmcnt(8)
	s_waitcnt lgkmcnt(0)
	s_setprio 1
	s_barrier
	v_mfma_f32_16x16x32_bf16 v[60:63], v[150:153], v[182:185], v[60:63]
	v_mfma_f32_16x16x32_bf16 v[56:59], v[158:161], v[182:185], v[56:59]
	v_mfma_f32_16x16x32_bf16 v[44:47], v[150:153], v[190:193], v[44:47]
	v_mfma_f32_16x16x32_bf16 v[40:43], v[158:161], v[190:193], v[40:43]
	v_mfma_f32_16x16x32_bf16 v[28:31], v[150:153], v[198:201], v[28:31]
	v_mfma_f32_16x16x32_bf16 v[24:27], v[158:161], v[198:201], v[24:27]
	v_mfma_f32_16x16x32_bf16 v[12:15], v[150:153], v[206:209], v[12:15]
	v_mfma_f32_16x16x32_bf16 v[8:11], v[158:161], v[206:209], v[8:11]
	v_mfma_f32_16x16x32_bf16 v[60:63], v[154:157], v[186:189], v[60:63]
	v_mfma_f32_16x16x32_bf16 v[56:59], v[162:165], v[186:189], v[56:59]
	v_mfma_f32_16x16x32_bf16 v[44:47], v[154:157], v[194:197], v[44:47]
	v_mfma_f32_16x16x32_bf16 v[40:43], v[162:165], v[194:197], v[40:43]
	v_mfma_f32_16x16x32_bf16 v[28:31], v[154:157], v[202:205], v[28:31]
	v_mfma_f32_16x16x32_bf16 v[24:27], v[162:165], v[202:205], v[24:27]
	v_mfma_f32_16x16x32_bf16 v[12:15], v[154:157], v[210:213], v[12:15]
	v_mfma_f32_16x16x32_bf16 v[8:11], v[162:165], v[210:213], v[8:11]
	s_setprio 0
	s_setprio 1
	v_mfma_f32_16x16x32_bf16 v[52:55], v[166:169], v[182:185], v[52:55]
	v_mfma_f32_16x16x32_bf16 v[48:51], v[174:177], v[182:185], v[48:51]
	v_mfma_f32_16x16x32_bf16 v[36:39], v[166:169], v[190:193], v[36:39]
	v_mfma_f32_16x16x32_bf16 v[32:35], v[174:177], v[190:193], v[32:35]
	v_mfma_f32_16x16x32_bf16 v[20:23], v[166:169], v[198:201], v[20:23]
	v_mfma_f32_16x16x32_bf16 v[16:19], v[174:177], v[198:201], v[16:19]
	v_mfma_f32_16x16x32_bf16 v[4:7], v[166:169], v[206:209], v[4:7]
	v_mfma_f32_16x16x32_bf16 v[0:3], v[174:177], v[206:209], v[0:3]
	v_mfma_f32_16x16x32_bf16 v[52:55], v[170:173], v[186:189], v[52:55]
	v_mfma_f32_16x16x32_bf16 v[48:51], v[178:181], v[186:189], v[48:51]
	v_mfma_f32_16x16x32_bf16 v[36:39], v[170:173], v[194:197], v[36:39]
	v_mfma_f32_16x16x32_bf16 v[32:35], v[178:181], v[194:197], v[32:35]
	v_mfma_f32_16x16x32_bf16 v[20:23], v[170:173], v[202:205], v[20:23]
	v_mfma_f32_16x16x32_bf16 v[16:19], v[178:181], v[202:205], v[16:19]
	v_mfma_f32_16x16x32_bf16 v[4:7], v[170:173], v[210:213], v[4:7]
	v_mfma_f32_16x16x32_bf16 v[0:3], v[178:181], v[210:213], v[0:3]
	s_barrier
	s_setprio 0
	s_add_i32 s67, s67, 2
	s_add_u32 s65, s65, 0x10000
	s_addc_u32 s66, s66, 0
	s_add_u32 s24, s24, 0x100
	s_addc_u32 s25, s25, 0
	s_cmp_gt_u32 s67, 29
	s_cbranch_scc0 .LBB0_499
	s_and_b64 vcc, exec, s[28:29]
	s_cbranch_vccz .LBB0_502
	s_barrier

; #define PG8_STAGE(bufoff, gbase, voff) do { _Pragma("unroll") for (int _i = 0; _i < 2; ++_i) \
;         __builtin_amdgcn_global_load_lds((const unsigned*)((const char*)(gbase) + (voff)[_i]), (LAS unsigned*)(lds + (bufoff) + ldsw + _i * 8192), 16, 0, 0); } while (0)
; #define PG8_LDA(dst, b, h) do { _Pragma("unroll") for (int m = 0; m < 4; ++m) _Pragma("unroll") for (int k = 0; k < 2; ++k) dst[m][k] = *(const LAS bf16x8*)(lds + PG8_SA(b, h) + aoff + m * 2048 + k * 1024); } while (0)
; #define PG8_LDB(dst, b, h) do { _Pragma("unroll") for (int n = 0; n < 2; ++n) _Pragma("unroll") for (int k = 0; k < 2; ++k) dst[n][k] = *(const LAS bf16x8*)(lds + PG8_SB(b, h) + boff + n * 2048 + k * 1024); } while (0)
; template <class Epi, class Sched, bool ALIGN_EPI>
; __device__ __forceinline__ void gemm_phase(LAS unsigned char* lds, const Gemm g, const Sched& S, const Epi& E, const int wid) {
;     ...
;         for (int t = 0; t < nt; t += 2) {
;             const bool last = (t == nt - 2);
;             if constexpr (Epi::HAS_PRE) { if (last) X.pre = E.pre(cur, tid); }
;             const char* a1 = cA + (size_t)(t + 1) * kstepA;
;             const char* a2 = last ? nA : cA + (size_t)(t + 2) * kstepA; const char* b2 = last ? nB : cB + (size_t)(t + 2) * kstep;
;             const char* a3 = a2 + kstepA; const char* b3 = b2 + kstep;
;             PG8_LDB(B0, 0, 0); PG8_LDB(B1, 0, 1); PG8_SCHED; PG8_LDA(At, 0, 0); PG8_STAGE(PG8_SA(1, 1), a1 + hstepA, voffA);
;             PG8_WAIT_V(8); PG8_WAIT_L(0); PG8_BAR; PG8_MMA(0, 0, At, B0); PG8_MMA(0, 1, At, B1); PG8_BAR; PG8_SCHED;
;             PG8_LDA(At, 0, 1); PG8_STAGE(PG8_SB(0, 0), b2, voffB); PG8_STAGE(PG8_SB(0, 1), b2 + hstepB, voffB); PG8_STAGE(PG8_SA(0, 0), a2, voffA);
;             PG8_WAIT_V(8); PG8_WAIT_L(0); PG8_BAR; PG8_MMA(1, 0, At, B0); PG8_MMA(1, 1, At, B1); PG8_BAR; PG8_SCHED;
;             PG8_LDB(B0, 1, 0); PG8_LDB(B1, 1, 1); PG8_SCHED; PG8_LDA(At, 1, 0); PG8_STAGE(PG8_SA(0, 1), a2 + hstepA, voffA);
;             PG8_WAIT_V(8); PG8_WAIT_L(0); PG8_BAR; PG8_MMA(0, 0, At, B0); PG8_MMA(0, 1, At, B1); PG8_BAR; PG8_SCHED;
;             PG8_LDA(At, 1, 1); PG8_STAGE(PG8_SB(1, 0), b3, voffB); PG8_STAGE(PG8_SB(1, 1), b3 + hstepB, voffB); PG8_STAGE(PG8_SA(1, 0), a3, voffA);
;             PG8_WAIT_V(8); PG8_WAIT_L(0); PG8_BAR; PG8_MMA(1, 0, At, B0); PG8_MMA(1, 1, At, B1); PG8_BAR; PG8_SCHED;
.LBB0_579:
	ds_read_b128 v[120:123], v184
	ds_read_b128 v[132:135], v184 offset:1024
	ds_read_b128 v[136:139], v184 offset:2048
	ds_read_b128 v[140:143], v184 offset:3072
	ds_read_b128 v[144:147], v185
	ds_read_b128 v[148:151], v185 offset:1024
	ds_read_b128 v[152:155], v185 offset:2048
	ds_read_b128 v[176:179], v185 offset:3072
	s_add_u32 s38, s58, 0xfff00080
	s_addc_u32 s39, s59, -1
	s_cmp_eq_u32 s57, 60
	s_cselect_b32 s63, s23, s39
	s_cselect_b32 s62, s35, s38
	s_cselect_b32 s61, s21, s55
	s_cselect_b32 s60, s52, s53
	s_add_i32 m0, s4, 0xc000
	ds_read_b128 v[188:191], v186
	ds_read_b128 v[192:195], v186 offset:1024
	ds_read_b128 v[196:199], v186 offset:2048
	ds_read_b128 v[200:203], v186 offset:3072
	ds_read_b128 v[204:207], v186 offset:4096
	ds_read_b128 v[208:211], v186 offset:5120
	ds_read_b128 v[212:215], v186 offset:6144
	ds_read_b128 v[216:219], v186 offset:7168
	global_load_lds_dwordx4 v168, s[58:59]
	s_add_i32 m0, s4, 0xe000
	s_nop 0
	global_load_lds_dwordx4 v170, s[58:59]
	s_waitcnt vmcnt(8)
	s_waitcnt lgkmcnt(0)
	s_setprio 1
	s_barrier
	v_mfma_f32_16x16x32_bf16 v[128:131], v[120:123], v[188:191], v[128:131]
	v_mfma_f32_16x16x32_bf16 v[124:127], v[136:139], v[188:191], v[124:127]
	v_mfma_f32_16x16x32_bf16 v[108:111], v[120:123], v[196:199], v[108:111]
	v_mfma_f32_16x16x32_bf16 v[104:107], v[136:139], v[196:199], v[104:107]
	v_mfma_f32_16x16x32_bf16 v[92:95], v[120:123], v[204:207], v[92:95]
	v_mfma_f32_16x16x32_bf16 v[88:91], v[136:139], v[204:207], v[88:91]
	v_mfma_f32_16x16x32_bf16 v[76:79], v[120:123], v[212:215], v[76:79]
	v_mfma_f32_16x16x32_bf16 v[72:75], v[136:139], v[212:215], v[72:75]
	v_mfma_f32_16x16x32_bf16 v[128:131], v[132:135], v[192:195], v[128:131]
	v_mfma_f32_16x16x32_bf16 v[124:127], v[140:143], v[192:195], v[124:127]
	v_mfma_f32_16x16x32_bf16 v[108:111], v[132:135], v[200:203], v[108:111]
	v_mfma_f32_16x16x32_bf16 v[104:107], v[140:143], v[200:203], v[104:107]
	v_mfma_f32_16x16x32_bf16 v[92:95], v[132:135], v[208:211], v[92:95]
	v_mfma_f32_16x16x32_bf16 v[88:91], v[140:143], v[208:211], v[88:91]
	v_mfma_f32_16x16x32_bf16 v[76:79], v[132:135], v[216:219], v[76:79]
	v_mfma_f32_16x16x32_bf16 v[72:75], v[140:143], v[216:219], v[72:75]
	s_setprio 0
	s_setprio 1
	v_mfma_f32_16x16x32_bf16 v[116:119], v[144:147], v[188:191], v[116:119]
	v_mfma_f32_16x16x32_bf16 v[112:115], v[152:155], v[188:191], v[112:115]
	v_mfma_f32_16x16x32_bf16 v[100:103], v[144:147], v[196:199], v[100:103]
	v_mfma_f32_16x16x32_bf16 v[96:99], v[152:155], v[196:199], v[96:99]
	v_mfma_f32_16x16x32_bf16 v[84:87], v[144:147], v[204:207], v[84:87]
	v_mfma_f32_16x16x32_bf16 v[80:83], v[152:155], v[204:207], v[80:83]
	v_mfma_f32_16x16x32_bf16 v[68:71], v[144:147], v[212:215], v[68:71]
	v_mfma_f32_16x16x32_bf16 v[64:67], v[152:155], v[212:215], v[64:67]
	v_mfma_f32_16x16x32_bf16 v[116:119], v[148:151], v[192:195], v[116:119]
	v_mfma_f32_16x16x32_bf16 v[112:115], v[176:179], v[192:195], v[112:115]
	v_mfma_f32_16x16x32_bf16 v[100:103], v[148:151], v[200:203], v[100:103]
	v_mfma_f32_16x16x32_bf16 v[96:99], v[176:179], v[200:203], v[96:99]
	v_mfma_f32_16x16x32_bf16 v[84:87], v[148:151], v[208:211], v[84:87]
	v_mfma_f32_16x16x32_bf16 v[80:83], v[176:179], v[208:211], v[80:83]
	v_mfma_f32_16x16x32_bf16 v[68:71], v[148:151], v[216:219], v[68:71]
	v_mfma_f32_16x16x32_bf16 v[64:67], v[176:179], v[216:219], v[64:67]
	s_barrier
	s_setprio 0
	s_add_i32 s38, s66, s3
	s_mov_b32 m0, s38
	ds_read_b128 v[188:191], v186 offset:16384
	ds_read_b128 v[192:195], v186 offset:17408
	ds_read_b128 v[196:199], v186 offset:18432
	ds_read_b128 v[200:203], v186 offset:19456
	ds_read_b128 v[204:207], v186 offset:20480
	ds_read_b128 v[208:211], v186 offset:21504
	ds_read_b128 v[212:215], v186 offset:22528
	ds_read_b128 v[216:219], v186 offset:23552
	global_load_lds_dwordx4 v158, s[60:61]
	s_add_i32 m0, s38, 0x2000
	s_add_u32 s70, s60, 0x1000
	s_addc_u32 s71, s61, 0
	s_add_i32 s38, s67, s3
	global_load_lds_dwordx4 v162, s[60:61]
	s_mov_b32 m0, s38
	v_lshl_add_u64 v[220:221], s[62:63], 0, v[160:161]
	global_load_lds_dwordx4 v158, s[70:71]
	s_add_i32 m0, s38, 0x2000
	s_nop 0
	global_load_lds_dwordx4 v162, s[70:71]
	v_lshl_add_u64 v[180:181], s[62:63], 0, v[156:157]
	s_mov_b32 m0, s4
	s_nop 0
	global_load_lds_dwordx4 v[180:181], off
	s_mov_b32 m0, s5
	s_nop 0
	global_load_lds_dwordx4 v[220:221], off
	s_waitcnt vmcnt(8)
	s_waitcnt lgkmcnt(0)
	s_setprio 1
	s_barrier
	v_mfma_f32_16x16x32_bf16 v[60:63], v[120:123], v[188:191], v[60:63]
	v_mfma_f32_16x16x32_bf16 v[56:59], v[136:139], v[188:191], v[56:59]
	v_mfma_f32_16x16x32_bf16 v[44:47], v[120:123], v[196:199], v[44:47]
	v_mfma_f32_16x16x32_bf16 v[40:43], v[136:139], v[196:199], v[40:43]
	v_mfma_f32_16x16x32_bf16 v[28:31], v[120:123], v[204:207], v[28:31]
	v_mfma_f32_16x16x32_bf16 v[24:27], v[136:139], v[204:207], v[24:27]
	v_mfma_f32_16x16x32_bf16 v[12:15], v[120:123], v[212:215], v[12:15]
	v_mfma_f32_16x16x32_bf16 v[8:11], v[136:139], v[212:215], v[8:11]
	v_mfma_f32_16x16x32_bf16 v[60:63], v[132:135], v[192:195], v[60:63]
	v_mfma_f32_16x16x32_bf16 v[56:59], v[140:143], v[192:195], v[56:59]
	v_mfma_f32_16x16x32_bf16 v[44:47], v[132:135], v[200:203], v[44:47]
	v_mfma_f32_16x16x32_bf16 v[40:43], v[140:143], v[200:203], v[40:43]
	v_mfma_f32_16x16x32_bf16 v[28:31], v[132:135], v[208:211], v[28:31]
	v_mfma_f32_16x16x32_bf16 v[24:27], v[140:143], v[208:211], v[24:27]
	v_mfma_f32_16x16x32_bf16 v[12:15], v[132:135], v[216:219], v[12:15]
	v_mfma_f32_16x16x32_bf16 v[8:11], v[140:143], v[216:219], v[8:11]
	s_setprio 0
	s_setprio 1
	v_mfma_f32_16x16x32_bf16 v[52:55], v[144:147], v[188:191], v[52:55]
	v_mfma_f32_16x16x32_bf16 v[48:51], v[152:155], v[188:191], v[48:51]
	v_mfma_f32_16x16x32_bf16 v[36:39], v[144:147], v[196:199], v[36:39]
	v_mfma_f32_16x16x32_bf16 v[32:35], v[152:155], v[196:199], v[32:35]
	v_mfma_f32_16x16x32_bf16 v[20:23], v[144:147], v[204:207], v[20:23]
	v_mfma_f32_16x16x32_bf16 v[16:19], v[152:155], v[204:207], v[16:19]
	v_mfma_f32_16x16x32_bf16 v[4:7], v[144:147], v[212:215], v[4:7]
	v_mfma_f32_16x16x32_bf16 v[0:3], v[152:155], v[212:215], v[0:3]
	v_mfma_f32_16x16x32_bf16 v[52:55], v[148:151], v[192:195], v[52:55]
	v_mfma_f32_16x16x32_bf16 v[48:51], v[176:179], v[192:195], v[48:51]
	v_mfma_f32_16x16x32_bf16 v[36:39], v[148:151], v[200:203], v[36:39]
	v_mfma_f32_16x16x32_bf16 v[32:35], v[176:179], v[200:203], v[32:35]
	v_mfma_f32_16x16x32_bf16 v[20:23], v[148:151], v[208:211], v[20:23]
	v_mfma_f32_16x16x32_bf16 v[16:19], v[176:179], v[208:211], v[16:19]
	v_mfma_f32_16x16x32_bf16 v[4:7], v[148:151], v[216:219], v[4:7]
	v_mfma_f32_16x16x32_bf16 v[0:3], v[176:179], v[216:219], v[0:3]
	s_barrier
; #define PG8_STAGE(bufoff, gbase, voff) do { _Pragma("unroll") for (int _i = 0; _i < 2; ++_i) \
;         __builtin_amdgcn_global_load_lds((const unsigned*)((const char*)(gbase) + (voff)[_i]), (LAS unsigned*)(lds + (bufoff) + ldsw + _i * 8192), 16, 0, 0); } while (0)
; #define PG8_LDA(dst, b, h) do { _Pragma("unroll") for (int m = 0; m < 4; ++m) _Pragma("unroll") for (int k = 0; k < 2; ++k) dst[m][k] = *(const LAS bf16x8*)(lds + PG8_SA(b, h) + aoff + m * 2048 + k * 1024); } while (0)
; #define PG8_LDB(dst, b, h) do { _Pragma("unroll") for (int n = 0; n < 2; ++n) _Pragma("unroll") for (int k = 0; k < 2; ++k) dst[n][k] = *(const LAS bf16x8*)(lds + PG8_SB(b, h) + boff + n * 2048 + k * 1024); } while (0)
; #define PG8_MMA(ai, bj, At, Bt) do { __builtin_amdgcn_s_setprio(1); _Pragma("unroll") for (int m = 0; m < 4; ++m) _Pragma("unroll") for (int n = 0; n < 2; ++n) _Pragma("unroll") for (int k = 0; k < 2; ++k) \
;         acc[ai][bj][m][n] = __builtin_amdgcn_mfma_f32_16x16x32_bf16(Bt[n][k], At[m][k], acc[ai][bj][m][n], 0, 0, 0); __builtin_amdgcn_s_setprio(0); } while (0)
; #define PG8_WAIT_V(n) asm volatile("s_waitcnt vmcnt(" #n ")" ::: "memory")
; #define PG8_WAIT_L(n) asm volatile("s_waitcnt lgkmcnt(" #n ")" ::: "memory")
; #define PG8_BAR __builtin_amdgcn_s_barrier()
; #define PG8_SCHED __builtin_amdgcn_sched_barrier(0)
; template <class Epi, class Sched, bool ALIGN_EPI>
; __device__ __forceinline__ void gemm_phase(LAS unsigned char* lds, const Gemm g, const Sched& S, const Epi& E, const int wid) {
;     ...
;             PG8_LDB(B0, 1, 0); PG8_LDB(B1, 1, 1); PG8_SCHED; PG8_LDA(At, 1, 0); PG8_STAGE(PG8_SA(0, 1), a2 + hstepA, voffA);
;             PG8_WAIT_V(8); PG8_WAIT_L(0); PG8_BAR; PG8_MMA(0, 0, At, B0); PG8_MMA(0, 1, At, B1); PG8_BAR; PG8_SCHED;
;             PG8_LDA(At, 1, 1); PG8_STAGE(PG8_SB(1, 0), b3, voffB); PG8_STAGE(PG8_SB(1, 1), b3 + hstepB, voffB); PG8_STAGE(PG8_SA(1, 0), a3, voffA);
;             PG8_WAIT_V(8); PG8_WAIT_L(0); PG8_BAR; PG8_MMA(1, 0, At, B0); PG8_MMA(1, 1, At, B1); PG8_BAR; PG8_SCHED;
;         }
;         if constexpr (ALIGN_EPI) { if (wr == 0) PG8_BAR; }
	s_setprio 0
	s_add_i32 s38, 0, 0x18000
	s_add_i32 s39, 0, 0x1c000
	v_add_u32_e32 v140, s38, v182
	v_add_u32_e32 v164, s39, v182
	ds_read_b128 v[120:123], v140
	ds_read_b128 v[132:135], v140 offset:1024
	ds_read_b128 v[136:139], v140 offset:2048
	ds_read_b128 v[140:143], v140 offset:3072
	ds_read_b128 v[144:147], v164
	ds_read_b128 v[148:151], v164 offset:1024
	ds_read_b128 v[152:155], v164 offset:2048
	ds_read_b128 v[176:179], v164 offset:3072
	s_add_u32 s62, s62, 0x100000
	s_addc_u32 s63, s63, 0
	s_mov_b32 m0, s44
	ds_read_b128 v[188:191], v186 offset:32768
	ds_read_b128 v[192:195], v186 offset:33792
	ds_read_b128 v[196:199], v186 offset:34816
	ds_read_b128 v[200:203], v186 offset:35840
	ds_read_b128 v[204:207], v186 offset:36864
	ds_read_b128 v[208:211], v186 offset:37888
	ds_read_b128 v[212:215], v186 offset:38912
	ds_read_b128 v[216:219], v186 offset:39936
	global_load_lds_dwordx4 v156, s[62:63]
	s_mov_b32 m0, s45
	s_nop 0
	global_load_lds_dwordx4 v160, s[62:63]
	s_waitcnt vmcnt(8)
	s_waitcnt lgkmcnt(0)
	s_setprio 1
	s_barrier
	v_mfma_f32_16x16x32_bf16 v[128:131], v[120:123], v[188:191], v[128:131]
	v_mfma_f32_16x16x32_bf16 v[124:127], v[136:139], v[188:191], v[124:127]
	v_mfma_f32_16x16x32_bf16 v[108:111], v[120:123], v[196:199], v[108:111]
	v_mfma_f32_16x16x32_bf16 v[104:107], v[136:139], v[196:199], v[104:107]
	v_mfma_f32_16x16x32_bf16 v[92:95], v[120:123], v[204:207], v[92:95]
	v_mfma_f32_16x16x32_bf16 v[88:91], v[136:139], v[204:207], v[88:91]
	v_mfma_f32_16x16x32_bf16 v[76:79], v[120:123], v[212:215], v[76:79]
	v_mfma_f32_16x16x32_bf16 v[72:75], v[136:139], v[212:215], v[72:75]
	v_mfma_f32_16x16x32_bf16 v[128:131], v[132:135], v[192:195], v[128:131]
	v_mfma_f32_16x16x32_bf16 v[124:127], v[140:143], v[192:195], v[124:127]
	v_mfma_f32_16x16x32_bf16 v[108:111], v[132:135], v[200:203], v[108:111]
	v_mfma_f32_16x16x32_bf16 v[104:107], v[140:143], v[200:203], v[104:107]
	v_mfma_f32_16x16x32_bf16 v[92:95], v[132:135], v[208:211], v[92:95]
	v_mfma_f32_16x16x32_bf16 v[88:91], v[140:143], v[208:211], v[88:91]
	v_mfma_f32_16x16x32_bf16 v[76:79], v[132:135], v[216:219], v[76:79]
	v_mfma_f32_16x16x32_bf16 v[72:75], v[140:143], v[216:219], v[72:75]
	s_setprio 0
	s_setprio 1
	v_mfma_f32_16x16x32_bf16 v[116:119], v[144:147], v[188:191], v[116:119]
	v_mfma_f32_16x16x32_bf16 v[112:115], v[152:155], v[188:191], v[112:115]
	v_mfma_f32_16x16x32_bf16 v[100:103], v[144:147], v[196:199], v[100:103]
	v_mfma_f32_16x16x32_bf16 v[96:99], v[152:155], v[196:199], v[96:99]
	v_mfma_f32_16x16x32_bf16 v[84:87], v[144:147], v[204:207], v[84:87]
	v_mfma_f32_16x16x32_bf16 v[80:83], v[152:155], v[204:207], v[80:83]
	v_mfma_f32_16x16x32_bf16 v[68:71], v[144:147], v[212:215], v[68:71]
	v_mfma_f32_16x16x32_bf16 v[64:67], v[152:155], v[212:215], v[64:67]
	v_mfma_f32_16x16x32_bf16 v[116:119], v[148:151], v[192:195], v[116:119]
	v_mfma_f32_16x16x32_bf16 v[112:115], v[176:179], v[192:195], v[112:115]
	v_mfma_f32_16x16x32_bf16 v[100:103], v[148:151], v[200:203], v[100:103]
	v_mfma_f32_16x16x32_bf16 v[96:99], v[176:179], v[200:203], v[96:99]
	v_mfma_f32_16x16x32_bf16 v[84:87], v[148:151], v[208:211], v[84:87]
	v_mfma_f32_16x16x32_bf16 v[80:83], v[176:179], v[208:211], v[80:83]
	v_mfma_f32_16x16x32_bf16 v[68:71], v[148:151], v[216:219], v[68:71]
	v_mfma_f32_16x16x32_bf16 v[64:67], v[176:179], v[216:219], v[64:67]
	s_barrier
	s_setprio 0
	s_add_u32 s62, s60, 0x8000
	s_addc_u32 s63, s61, 0
	s_add_i32 s38, s38, s3
	s_mov_b32 m0, s38
	ds_read_b128 v[188:191], v186 offset:49152
	ds_read_b128 v[192:195], v186 offset:50176
	ds_read_b128 v[196:199], v186 offset:51200
	ds_read_b128 v[200:203], v186 offset:52224
	ds_read_b128 v[204:207], v186 offset:53248
	ds_read_b128 v[208:211], v186 offset:54272
	ds_read_b128 v[212:215], v186 offset:55296
	ds_read_b128 v[216:219], v186 offset:56320
	global_load_lds_dwordx4 v158, s[62:63]
	s_add_i32 m0, s38, 0x2000
	s_add_u32 s60, s60, 0x9000
	s_addc_u32 s61, s61, 0
	s_add_i32 s38, s39, s3
	global_load_lds_dwordx4 v162, s[62:63]
	s_mov_b32 m0, s38
	v_lshl_add_u64 v[180:181], v[180:181], 0, s[16:17]
	global_load_lds_dwordx4 v158, s[60:61]
	s_add_i32 m0, s38, 0x2000
	s_nop 0
	global_load_lds_dwordx4 v162, s[60:61]
	s_mov_b32 m0, s64
	s_nop 0
	global_load_lds_dwordx4 v[180:181], off
	v_lshl_add_u64 v[180:181], v[220:221], 0, s[16:17]
	s_mov_b32 m0, s65
	s_nop 0
	global_load_lds_dwordx4 v[180:181], off
	s_waitcnt vmcnt(8)
	s_waitcnt lgkmcnt(0)
	s_setprio 1
	s_barrier
	v_mfma_f32_16x16x32_bf16 v[60:63], v[120:123], v[188:191], v[60:63]
	v_mfma_f32_16x16x32_bf16 v[56:59], v[136:139], v[188:191], v[56:59]
	v_mfma_f32_16x16x32_bf16 v[44:47], v[120:123], v[196:199], v[44:47]
	v_mfma_f32_16x16x32_bf16 v[40:43], v[136:139], v[196:199], v[40:43]
	v_mfma_f32_16x16x32_bf16 v[28:31], v[120:123], v[204:207], v[28:31]
	v_mfma_f32_16x16x32_bf16 v[24:27], v[136:139], v[204:207], v[24:27]
	v_mfma_f32_16x16x32_bf16 v[12:15], v[120:123], v[212:215], v[12:15]
	v_mfma_f32_16x16x32_bf16 v[8:11], v[136:139], v[212:215], v[8:11]
	v_mfma_f32_16x16x32_bf16 v[60:63], v[132:135], v[192:195], v[60:63]
	v_mfma_f32_16x16x32_bf16 v[56:59], v[140:143], v[192:195], v[56:59]
	v_mfma_f32_16x16x32_bf16 v[44:47], v[132:135], v[200:203], v[44:47]
	v_mfma_f32_16x16x32_bf16 v[40:43], v[140:143], v[200:203], v[40:43]
	v_mfma_f32_16x16x32_bf16 v[28:31], v[132:135], v[208:211], v[28:31]
	v_mfma_f32_16x16x32_bf16 v[24:27], v[140:143], v[208:211], v[24:27]
	v_mfma_f32_16x16x32_bf16 v[12:15], v[132:135], v[216:219], v[12:15]
	v_mfma_f32_16x16x32_bf16 v[8:11], v[140:143], v[216:219], v[8:11]
	s_setprio 0
	s_setprio 1
	v_mfma_f32_16x16x32_bf16 v[52:55], v[144:147], v[188:191], v[52:55]
	v_mfma_f32_16x16x32_bf16 v[48:51], v[152:155], v[188:191], v[48:51]
	v_mfma_f32_16x16x32_bf16 v[36:39], v[144:147], v[196:199], v[36:39]
	v_mfma_f32_16x16x32_bf16 v[32:35], v[152:155], v[196:199], v[32:35]
	v_mfma_f32_16x16x32_bf16 v[20:23], v[144:147], v[204:207], v[20:23]
	v_mfma_f32_16x16x32_bf16 v[16:19], v[152:155], v[204:207], v[16:19]
	v_mfma_f32_16x16x32_bf16 v[4:7], v[144:147], v[212:215], v[4:7]
	v_mfma_f32_16x16x32_bf16 v[0:3], v[152:155], v[212:215], v[0:3]
	v_mfma_f32_16x16x32_bf16 v[52:55], v[148:151], v[192:195], v[52:55]
	v_mfma_f32_16x16x32_bf16 v[48:51], v[176:179], v[192:195], v[48:51]
	v_mfma_f32_16x16x32_bf16 v[36:39], v[148:151], v[200:203], v[36:39]
	v_mfma_f32_16x16x32_bf16 v[32:35], v[176:179], v[200:203], v[32:35]
	v_mfma_f32_16x16x32_bf16 v[20:23], v[148:151], v[208:211], v[20:23]
	v_mfma_f32_16x16x32_bf16 v[16:19], v[176:179], v[208:211], v[16:19]
	v_mfma_f32_16x16x32_bf16 v[4:7], v[148:151], v[216:219], v[4:7]
	v_mfma_f32_16x16x32_bf16 v[0:3], v[176:179], v[216:219], v[0:3]
	s_barrier
	s_setprio 0
	s_add_i32 s57, s57, 2
	s_add_u32 s53, s53, 0x10000
	s_addc_u32 s55, s55, 0
	s_add_u32 s58, s58, 0x100
	s_addc_u32 s59, s59, 0
	s_cmp_gt_u32 s57, 61
	s_cbranch_scc0 .LBB0_579
	s_and_b64 vcc, exec, s[28:29]
	s_cbranch_vccz .LBB0_582
	s_barrier

; #define PG8_STAGE(bufoff, gbase, voff) do { _Pragma("unroll") for (int _i = 0; _i < 2; ++_i) \
;         __builtin_amdgcn_global_load_lds((const unsigned*)((const char*)(gbase) + (voff)[_i]), (LAS unsigned*)(lds + (bufoff) + ldsw + _i * 8192), 16, 0, 0); } while (0)
; #define PG8_LDA(dst, b, h) do { _Pragma("unroll") for (int m = 0; m < 4; ++m) _Pragma("unroll") for (int k = 0; k < 2; ++k) dst[m][k] = *(const LAS bf16x8*)(lds + PG8_SA(b, h) + aoff + m * 2048 + k * 1024); } while (0)
; #define PG8_LDB(dst, b, h) do { _Pragma("unroll") for (int n = 0; n < 2; ++n) _Pragma("unroll") for (int k = 0; k < 2; ++k) dst[n][k] = *(const LAS bf16x8*)(lds + PG8_SB(b, h) + boff + n * 2048 + k * 1024); } while (0)
; #define PG8_MMA(ai, bj, At, Bt) do { __builtin_amdgcn_s_setprio(1); _Pragma("unroll") for (int m = 0; m < 4; ++m) _Pragma("unroll") for (int n = 0; n < 2; ++n) _Pragma("unroll") for (int k = 0; k < 2; ++k) \
;         acc[ai][bj][m][n] = __builtin_amdgcn_mfma_f32_16x16x32_bf16(Bt[n][k], At[m][k], acc[ai][bj][m][n], 0, 0, 0); __builtin_amdgcn_s_setprio(0); } while (0)
; #define PG8_WAIT_V(n) asm volatile("s_waitcnt vmcnt(" #n ")" ::: "memory")
; #define PG8_WAIT_L(n) asm volatile("s_waitcnt lgkmcnt(" #n ")" ::: "memory")
; #define PG8_BAR __builtin_amdgcn_s_barrier()
; #define PG8_SCHED __builtin_amdgcn_sched_barrier(0)
; template <class Epi, class Sched, bool ALIGN_EPI>
; __device__ __forceinline__ void gemm_phase(LAS unsigned char* lds, const Gemm g, const Sched& S, const Epi& E, const int wid) {
;     ...
;             PG8_LDB(B0, 0, 0); PG8_LDB(B1, 0, 1); PG8_SCHED; PG8_LDA(At, 0, 0); PG8_STAGE(PG8_SA(1, 1), a1 + hstepA, voffA);
;             PG8_WAIT_V(8); PG8_WAIT_L(0); PG8_BAR; PG8_MMA(0, 0, At, B0); PG8_MMA(0, 1, At, B1); PG8_BAR; PG8_SCHED;
;             PG8_LDA(At, 0, 1); PG8_STAGE(PG8_SB(0, 0), b2, voffB); PG8_STAGE(PG8_SB(0, 1), b2 + hstepB, voffB); PG8_STAGE(PG8_SA(0, 0), a2, voffA);
;             PG8_WAIT_V(8); PG8_WAIT_L(0); PG8_BAR; PG8_MMA(1, 0, At, B0); PG8_MMA(1, 1, At, B1); PG8_BAR; PG8_SCHED;
.LBB0_687:
	s_add_u32 s38, s18, 0x4000
	s_addc_u32 s39, s19, 0
	s_and_b64 s[62:63], s[64:65], exec
	s_cselect_b32 s66, s35, s38
	s_cselect_b32 s67, s27, s39
	s_add_u32 s62, s66, 0x8000
	s_addc_u32 s63, s67, 0
	s_add_i32 s38, 0, 0x10000
	v_add_u32_e32 v138, s38, v160
	ds_read_b128 v[130:133], v138
	ds_read_b128 v[134:137], v138 offset:1024
	ds_read_b128 v[170:173], v138 offset:2048
	ds_read_b128 v[174:177], v138 offset:3072
	v_add_u32_e32 v138, s53, v160
	ds_read_b128 v[178:181], v138
	ds_read_b128 v[182:185], v138 offset:1024
	ds_read_b128 v[186:189], v138 offset:2048
	ds_read_b128 v[190:193], v138 offset:3072
	s_and_b64 s[64:65], s[64:65], exec
	s_cselect_b32 s65, s25, s70
	s_cselect_b32 s64, s61, s69
	s_add_i32 m0, s23, 0xc000
	ds_read_b128 v[194:197], v166
	ds_read_b128 v[198:201], v166 offset:1024
	ds_read_b128 v[202:205], v166 offset:2048
	ds_read_b128 v[206:209], v166 offset:3072
	ds_read_b128 v[210:213], v166 offset:4096
	ds_read_b128 v[214:217], v166 offset:5120
	ds_read_b128 v[218:221], v166 offset:6144
	ds_read_b128 v[222:225], v166 offset:7168
	global_load_lds_dwordx4 v150, s[18:19]
	s_add_i32 m0, s23, 0xe000
	s_nop 0
	global_load_lds_dwordx4 v152, s[18:19]
	s_waitcnt vmcnt(8)
	s_waitcnt lgkmcnt(0)
	s_setprio 1
	s_barrier
	v_mfma_f32_16x16x32_bf16 v[124:127], v[130:133], v[194:197], v[124:127]
	v_mfma_f32_16x16x32_bf16 v[120:123], v[170:173], v[194:197], v[120:123]
	v_mfma_f32_16x16x32_bf16 v[108:111], v[130:133], v[202:205], v[108:111]
	v_mfma_f32_16x16x32_bf16 v[104:107], v[170:173], v[202:205], v[104:107]
	v_mfma_f32_16x16x32_bf16 v[92:95], v[130:133], v[210:213], v[92:95]
	v_mfma_f32_16x16x32_bf16 v[88:91], v[170:173], v[210:213], v[88:91]
	v_mfma_f32_16x16x32_bf16 v[76:79], v[130:133], v[218:221], v[76:79]
	v_mfma_f32_16x16x32_bf16 v[72:75], v[170:173], v[218:221], v[72:75]
	v_mfma_f32_16x16x32_bf16 v[124:127], v[134:137], v[198:201], v[124:127]
	v_mfma_f32_16x16x32_bf16 v[120:123], v[174:177], v[198:201], v[120:123]
	v_mfma_f32_16x16x32_bf16 v[108:111], v[134:137], v[206:209], v[108:111]
	v_mfma_f32_16x16x32_bf16 v[104:107], v[174:177], v[206:209], v[104:107]
	v_mfma_f32_16x16x32_bf16 v[92:95], v[134:137], v[214:217], v[92:95]
	v_mfma_f32_16x16x32_bf16 v[88:91], v[174:177], v[214:217], v[88:91]
	v_mfma_f32_16x16x32_bf16 v[76:79], v[134:137], v[222:225], v[76:79]
	v_mfma_f32_16x16x32_bf16 v[72:75], v[174:177], v[222:225], v[72:75]
	s_setprio 0
	s_setprio 1
	v_mfma_f32_16x16x32_bf16 v[116:119], v[178:181], v[194:197], v[116:119]
	v_mfma_f32_16x16x32_bf16 v[112:115], v[186:189], v[194:197], v[112:115]
	v_mfma_f32_16x16x32_bf16 v[100:103], v[178:181], v[202:205], v[100:103]
	v_mfma_f32_16x16x32_bf16 v[96:99], v[186:189], v[202:205], v[96:99]
	v_mfma_f32_16x16x32_bf16 v[84:87], v[178:181], v[210:213], v[84:87]
	v_mfma_f32_16x16x32_bf16 v[80:83], v[186:189], v[210:213], v[80:83]
	v_mfma_f32_16x16x32_bf16 v[68:71], v[178:181], v[218:221], v[68:71]
	v_mfma_f32_16x16x32_bf16 v[64:67], v[186:189], v[218:221], v[64:67]
	v_mfma_f32_16x16x32_bf16 v[116:119], v[182:185], v[198:201], v[116:119]
	v_mfma_f32_16x16x32_bf16 v[112:115], v[190:193], v[198:201], v[112:115]
	v_mfma_f32_16x16x32_bf16 v[100:103], v[182:185], v[206:209], v[100:103]
	v_mfma_f32_16x16x32_bf16 v[96:99], v[190:193], v[206:209], v[96:99]
	v_mfma_f32_16x16x32_bf16 v[84:87], v[182:185], v[214:217], v[84:87]
	v_mfma_f32_16x16x32_bf16 v[80:83], v[190:193], v[214:217], v[80:83]
	v_mfma_f32_16x16x32_bf16 v[68:71], v[182:185], v[222:225], v[68:71]
	v_mfma_f32_16x16x32_bf16 v[64:67], v[190:193], v[222:225], v[64:67]
	s_barrier
	s_setprio 0
	s_add_i32 s38, s38, s3
	s_mov_b32 m0, s38
	ds_read_b128 v[194:197], v166 offset:16384
	ds_read_b128 v[198:201], v166 offset:17408
	ds_read_b128 v[202:205], v166 offset:18432
	ds_read_b128 v[206:209], v166 offset:19456
	ds_read_b128 v[210:213], v166 offset:20480
	ds_read_b128 v[214:217], v166 offset:21504
	ds_read_b128 v[218:221], v166 offset:22528
	ds_read_b128 v[222:225], v166 offset:23552
	global_load_lds_dwordx4 v144, s[64:65]
	s_add_i32 m0, s38, 0x2000
	s_add_u32 s72, s64, 0x1000
	s_addc_u32 s73, s65, 0
	s_add_i32 s38, s53, s3
	global_load_lds_dwordx4 v140, s[64:65]
	s_mov_b32 m0, s38
	s_nop 0
	global_load_lds_dwordx4 v144, s[72:73]
	s_add_i32 m0, s38, 0x2000
	s_nop 0
	global_load_lds_dwordx4 v140, s[72:73]
	s_mov_b32 m0, s23
	s_nop 0
	global_load_lds_dwordx4 v146, s[66:67]
	s_mov_b32 m0, s30
	s_nop 0
	global_load_lds_dwordx4 v142, s[66:67]
	s_waitcnt vmcnt(8)
	s_waitcnt lgkmcnt(0)
	s_setprio 1
	s_barrier
	v_mfma_f32_16x16x32_bf16 v[60:63], v[130:133], v[194:197], v[60:63]
	v_mfma_f32_16x16x32_bf16 v[56:59], v[170:173], v[194:197], v[56:59]
	v_mfma_f32_16x16x32_bf16 v[44:47], v[130:133], v[202:205], v[44:47]
	v_mfma_f32_16x16x32_bf16 v[40:43], v[170:173], v[202:205], v[40:43]
	v_mfma_f32_16x16x32_bf16 v[28:31], v[130:133], v[210:213], v[28:31]
	v_mfma_f32_16x16x32_bf16 v[24:27], v[170:173], v[210:213], v[24:27]
	v_mfma_f32_16x16x32_bf16 v[12:15], v[130:133], v[218:221], v[12:15]
	v_mfma_f32_16x16x32_bf16 v[8:11], v[170:173], v[218:221], v[8:11]
	v_mfma_f32_16x16x32_bf16 v[60:63], v[134:137], v[198:201], v[60:63]
	v_mfma_f32_16x16x32_bf16 v[56:59], v[174:177], v[198:201], v[56:59]
	v_mfma_f32_16x16x32_bf16 v[44:47], v[134:137], v[206:209], v[44:47]
	v_mfma_f32_16x16x32_bf16 v[40:43], v[174:177], v[206:209], v[40:43]
	v_mfma_f32_16x16x32_bf16 v[28:31], v[134:137], v[214:217], v[28:31]
	v_mfma_f32_16x16x32_bf16 v[24:27], v[174:177], v[214:217], v[24:27]
	v_mfma_f32_16x16x32_bf16 v[12:15], v[134:137], v[222:225], v[12:15]
	v_mfma_f32_16x16x32_bf16 v[8:11], v[174:177], v[222:225], v[8:11]
	s_setprio 0
	s_setprio 1
	v_mfma_f32_16x16x32_bf16 v[52:55], v[178:181], v[194:197], v[52:55]
	v_mfma_f32_16x16x32_bf16 v[48:51], v[186:189], v[194:197], v[48:51]
	v_mfma_f32_16x16x32_bf16 v[36:39], v[178:181], v[202:205], v[36:39]
	v_mfma_f32_16x16x32_bf16 v[32:35], v[186:189], v[202:205], v[32:35]
	v_mfma_f32_16x16x32_bf16 v[20:23], v[178:181], v[210:213], v[20:23]
	v_mfma_f32_16x16x32_bf16 v[16:19], v[186:189], v[210:213], v[16:19]
	v_mfma_f32_16x16x32_bf16 v[4:7], v[178:181], v[218:221], v[4:7]
	v_mfma_f32_16x16x32_bf16 v[0:3], v[186:189], v[218:221], v[0:3]
	v_mfma_f32_16x16x32_bf16 v[52:55], v[182:185], v[198:201], v[52:55]
	v_mfma_f32_16x16x32_bf16 v[48:51], v[190:193], v[198:201], v[48:51]
	v_mfma_f32_16x16x32_bf16 v[36:39], v[182:185], v[206:209], v[36:39]
	v_mfma_f32_16x16x32_bf16 v[32:35], v[190:193], v[206:209], v[32:35]
	v_mfma_f32_16x16x32_bf16 v[20:23], v[182:185], v[214:217], v[20:23]
	v_mfma_f32_16x16x32_bf16 v[16:19], v[190:193], v[214:217], v[16:19]
	v_mfma_f32_16x16x32_bf16 v[4:7], v[182:185], v[222:225], v[4:7]
	v_mfma_f32_16x16x32_bf16 v[0:3], v[190:193], v[222:225], v[0:3]
	s_barrier
; #define PG8_STAGE(bufoff, gbase, voff) do { _Pragma("unroll") for (int _i = 0; _i < 2; ++_i) \
;         __builtin_amdgcn_global_load_lds((const unsigned*)((const char*)(gbase) + (voff)[_i]), (LAS unsigned*)(lds + (bufoff) + ldsw + _i * 8192), 16, 0, 0); } while (0)
; #define PG8_LDA(dst, b, h) do { _Pragma("unroll") for (int m = 0; m < 4; ++m) _Pragma("unroll") for (int k = 0; k < 2; ++k) dst[m][k] = *(const LAS bf16x8*)(lds + PG8_SA(b, h) + aoff + m * 2048 + k * 1024); } while (0)
; #define PG8_LDB(dst, b, h) do { _Pragma("unroll") for (int n = 0; n < 2; ++n) _Pragma("unroll") for (int k = 0; k < 2; ++k) dst[n][k] = *(const LAS bf16x8*)(lds + PG8_SB(b, h) + boff + n * 2048 + k * 1024); } while (0)
; #define PG8_MMA(ai, bj, At, Bt) do { __builtin_amdgcn_s_setprio(1); _Pragma("unroll") for (int m = 0; m < 4; ++m) _Pragma("unroll") for (int n = 0; n < 2; ++n) _Pragma("unroll") for (int k = 0; k < 2; ++k) \
;         acc[ai][bj][m][n] = __builtin_amdgcn_mfma_f32_16x16x32_bf16(Bt[n][k], At[m][k], acc[ai][bj][m][n], 0, 0, 0); __builtin_amdgcn_s_setprio(0); } while (0)
; #define PG8_WAIT_V(n) asm volatile("s_waitcnt vmcnt(" #n ")" ::: "memory")
; #define PG8_WAIT_L(n) asm volatile("s_waitcnt lgkmcnt(" #n ")" ::: "memory")
; #define PG8_BAR __builtin_amdgcn_s_barrier()
; #define PG8_SCHED __builtin_amdgcn_sched_barrier(0)
; template <class Epi, class Sched, bool ALIGN_EPI>
; __device__ __forceinline__ void gemm_phase(LAS unsigned char* lds, const Gemm g, const Sched& S, const Epi& E, const int wid) {
;     ...
;             PG8_LDB(B0, 1, 0); PG8_LDB(B1, 1, 1); PG8_SCHED; PG8_LDA(At, 1, 0); PG8_STAGE(PG8_SA(0, 1), a2 + hstepA, voffA);
;             PG8_WAIT_V(8); PG8_WAIT_L(0); PG8_BAR; PG8_MMA(0, 0, At, B0); PG8_MMA(0, 1, At, B1); PG8_BAR; PG8_SCHED;
;             PG8_LDA(At, 1, 1); PG8_STAGE(PG8_SB(1, 0), b3, voffB); PG8_STAGE(PG8_SB(1, 1), b3 + hstepB, voffB); PG8_STAGE(PG8_SA(1, 0), a3, voffA);
;             PG8_WAIT_V(8); PG8_WAIT_L(0); PG8_BAR; PG8_MMA(1, 0, At, B0); PG8_MMA(1, 1, At, B1); PG8_BAR; PG8_SCHED;
;         }
;         if constexpr (ALIGN_EPI) { if (wr == 0) PG8_BAR; }
	s_setprio 0
	s_add_i32 s38, 0, 0x18000
	v_add_u32_e32 v138, s38, v160
	s_add_i32 s39, 0, 0x1c000
	ds_read_b128 v[130:133], v138
	ds_read_b128 v[134:137], v138 offset:1024
	ds_read_b128 v[170:173], v138 offset:2048
	ds_read_b128 v[174:177], v138 offset:3072
	v_add_u32_e32 v138, s39, v160
	ds_read_b128 v[178:181], v138
	ds_read_b128 v[182:185], v138 offset:1024
	ds_read_b128 v[186:189], v138 offset:2048
	ds_read_b128 v[190:193], v138 offset:3072
	s_add_u32 s66, s66, 0x4000
	s_addc_u32 s67, s67, 0
	s_mov_b32 m0, s31
	ds_read_b128 v[194:197], v166 offset:32768
	ds_read_b128 v[198:201], v166 offset:33792
	ds_read_b128 v[202:205], v166 offset:34816
	ds_read_b128 v[206:209], v166 offset:35840
	ds_read_b128 v[210:213], v166 offset:36864
	ds_read_b128 v[214:217], v166 offset:37888
	ds_read_b128 v[218:221], v166 offset:38912
	ds_read_b128 v[222:225], v166 offset:39936
	global_load_lds_dwordx4 v146, s[66:67]
	s_mov_b32 m0, s43
	s_nop 0
	global_load_lds_dwordx4 v142, s[66:67]
	s_waitcnt vmcnt(8)
	s_waitcnt lgkmcnt(0)
	s_setprio 1
	s_barrier
	v_mfma_f32_16x16x32_bf16 v[124:127], v[130:133], v[194:197], v[124:127]
	v_mfma_f32_16x16x32_bf16 v[120:123], v[170:173], v[194:197], v[120:123]
	v_mfma_f32_16x16x32_bf16 v[108:111], v[130:133], v[202:205], v[108:111]
	v_mfma_f32_16x16x32_bf16 v[104:107], v[170:173], v[202:205], v[104:107]
	v_mfma_f32_16x16x32_bf16 v[92:95], v[130:133], v[210:213], v[92:95]
	v_mfma_f32_16x16x32_bf16 v[88:91], v[170:173], v[210:213], v[88:91]
	v_mfma_f32_16x16x32_bf16 v[76:79], v[130:133], v[218:221], v[76:79]
	v_mfma_f32_16x16x32_bf16 v[72:75], v[170:173], v[218:221], v[72:75]
	v_mfma_f32_16x16x32_bf16 v[124:127], v[134:137], v[198:201], v[124:127]
	v_mfma_f32_16x16x32_bf16 v[120:123], v[174:177], v[198:201], v[120:123]
	v_mfma_f32_16x16x32_bf16 v[108:111], v[134:137], v[206:209], v[108:111]
	v_mfma_f32_16x16x32_bf16 v[104:107], v[174:177], v[206:209], v[104:107]
	v_mfma_f32_16x16x32_bf16 v[92:95], v[134:137], v[214:217], v[92:95]
	v_mfma_f32_16x16x32_bf16 v[88:91], v[174:177], v[214:217], v[88:91]
	v_mfma_f32_16x16x32_bf16 v[76:79], v[134:137], v[222:225], v[76:79]
	v_mfma_f32_16x16x32_bf16 v[72:75], v[174:177], v[222:225], v[72:75]
	s_setprio 0
	s_setprio 1
	v_mfma_f32_16x16x32_bf16 v[116:119], v[178:181], v[194:197], v[116:119]
	v_mfma_f32_16x16x32_bf16 v[112:115], v[186:189], v[194:197], v[112:115]
	v_mfma_f32_16x16x32_bf16 v[100:103], v[178:181], v[202:205], v[100:103]
	v_mfma_f32_16x16x32_bf16 v[96:99], v[186:189], v[202:205], v[96:99]
	v_mfma_f32_16x16x32_bf16 v[84:87], v[178:181], v[210:213], v[84:87]
	v_mfma_f32_16x16x32_bf16 v[80:83], v[186:189], v[210:213], v[80:83]
	v_mfma_f32_16x16x32_bf16 v[68:71], v[178:181], v[218:221], v[68:71]
	v_mfma_f32_16x16x32_bf16 v[64:67], v[186:189], v[218:221], v[64:67]
	v_mfma_f32_16x16x32_bf16 v[116:119], v[182:185], v[198:201], v[116:119]
	v_mfma_f32_16x16x32_bf16 v[112:115], v[190:193], v[198:201], v[112:115]
	v_mfma_f32_16x16x32_bf16 v[100:103], v[182:185], v[206:209], v[100:103]
	v_mfma_f32_16x16x32_bf16 v[96:99], v[190:193], v[206:209], v[96:99]
	v_mfma_f32_16x16x32_bf16 v[84:87], v[182:185], v[214:217], v[84:87]
	v_mfma_f32_16x16x32_bf16 v[80:83], v[190:193], v[214:217], v[80:83]
	v_mfma_f32_16x16x32_bf16 v[68:71], v[182:185], v[222:225], v[68:71]
	v_mfma_f32_16x16x32_bf16 v[64:67], v[190:193], v[222:225], v[64:67]
	s_barrier
	s_setprio 0
	s_add_u32 s66, s64, 0x8000
	s_addc_u32 s67, s65, 0
	s_add_i32 s38, s38, s3
	s_mov_b32 m0, s38
	ds_read_b128 v[194:197], v166 offset:49152
	ds_read_b128 v[198:201], v166 offset:50176
	ds_read_b128 v[202:205], v166 offset:51200
	ds_read_b128 v[206:209], v166 offset:52224
	ds_read_b128 v[210:213], v166 offset:53248
	ds_read_b128 v[214:217], v166 offset:54272
	ds_read_b128 v[218:221], v166 offset:55296
	ds_read_b128 v[222:225], v166 offset:56320
	global_load_lds_dwordx4 v144, s[66:67]
	s_add_i32 m0, s38, 0x2000
	s_add_u32 s64, s64, 0x9000
	s_addc_u32 s65, s65, 0
	s_add_i32 s38, s39, s3
	global_load_lds_dwordx4 v140, s[66:67]
	s_mov_b32 m0, s38
	s_nop 0
	global_load_lds_dwordx4 v144, s[64:65]
	s_add_i32 m0, s38, 0x2000
	s_nop 0
	global_load_lds_dwordx4 v140, s[64:65]
	s_mov_b32 m0, s47
	s_nop 0
	global_load_lds_dwordx4 v146, s[62:63]
	s_mov_b32 m0, s49
	s_nop 0
	global_load_lds_dwordx4 v142, s[62:63]
	s_waitcnt vmcnt(8)
	s_waitcnt lgkmcnt(0)
	s_setprio 1
	s_barrier
	v_mfma_f32_16x16x32_bf16 v[60:63], v[130:133], v[194:197], v[60:63]
	v_mfma_f32_16x16x32_bf16 v[56:59], v[170:173], v[194:197], v[56:59]
	v_mfma_f32_16x16x32_bf16 v[44:47], v[130:133], v[202:205], v[44:47]
	v_mfma_f32_16x16x32_bf16 v[40:43], v[170:173], v[202:205], v[40:43]
	v_mfma_f32_16x16x32_bf16 v[28:31], v[130:133], v[210:213], v[28:31]
	v_mfma_f32_16x16x32_bf16 v[24:27], v[170:173], v[210:213], v[24:27]
	v_mfma_f32_16x16x32_bf16 v[12:15], v[130:133], v[218:221], v[12:15]
	v_mfma_f32_16x16x32_bf16 v[8:11], v[170:173], v[218:221], v[8:11]
	v_mfma_f32_16x16x32_bf16 v[60:63], v[134:137], v[198:201], v[60:63]
	v_mfma_f32_16x16x32_bf16 v[56:59], v[174:177], v[198:201], v[56:59]
	v_mfma_f32_16x16x32_bf16 v[44:47], v[134:137], v[206:209], v[44:47]
	v_mfma_f32_16x16x32_bf16 v[40:43], v[174:177], v[206:209], v[40:43]
	v_mfma_f32_16x16x32_bf16 v[28:31], v[134:137], v[214:217], v[28:31]
	v_mfma_f32_16x16x32_bf16 v[24:27], v[174:177], v[214:217], v[24:27]
	v_mfma_f32_16x16x32_bf16 v[12:15], v[134:137], v[222:225], v[12:15]
	v_mfma_f32_16x16x32_bf16 v[8:11], v[174:177], v[222:225], v[8:11]
	s_setprio 0
	s_setprio 1
	v_mfma_f32_16x16x32_bf16 v[52:55], v[178:181], v[194:197], v[52:55]
	v_mfma_f32_16x16x32_bf16 v[48:51], v[186:189], v[194:197], v[48:51]
	v_mfma_f32_16x16x32_bf16 v[36:39], v[178:181], v[202:205], v[36:39]
	v_mfma_f32_16x16x32_bf16 v[32:35], v[186:189], v[202:205], v[32:35]
	v_mfma_f32_16x16x32_bf16 v[20:23], v[178:181], v[210:213], v[20:23]
	v_mfma_f32_16x16x32_bf16 v[16:19], v[186:189], v[210:213], v[16:19]
	v_mfma_f32_16x16x32_bf16 v[4:7], v[178:181], v[218:221], v[4:7]
	v_mfma_f32_16x16x32_bf16 v[0:3], v[186:189], v[218:221], v[0:3]
	v_mfma_f32_16x16x32_bf16 v[52:55], v[182:185], v[198:201], v[52:55]
	v_mfma_f32_16x16x32_bf16 v[48:51], v[190:193], v[198:201], v[48:51]
	v_mfma_f32_16x16x32_bf16 v[36:39], v[182:185], v[206:209], v[36:39]
	v_mfma_f32_16x16x32_bf16 v[32:35], v[190:193], v[206:209], v[32:35]
	v_mfma_f32_16x16x32_bf16 v[20:23], v[182:185], v[214:217], v[20:23]
	v_mfma_f32_16x16x32_bf16 v[16:19], v[190:193], v[214:217], v[16:19]
	v_mfma_f32_16x16x32_bf16 v[4:7], v[182:185], v[222:225], v[4:7]
	v_mfma_f32_16x16x32_bf16 v[0:3], v[190:193], v[222:225], v[0:3]
	s_barrier
	s_setprio 0
	s_add_i32 s71, s71, 2
	s_add_u32 s18, s18, 0x10000
	s_addc_u32 s19, s19, 0
	s_add_u32 s69, s69, 0x10000
	s_addc_u32 s70, s70, 0
	s_cmp_gt_u32 s71, 61
	s_cbranch_scc1 .LBB0_690

; #define PG8_STAGE(bufoff, gbase, voff) do { _Pragma("unroll") for (int _i = 0; _i < 2; ++_i) \
;         __builtin_amdgcn_global_load_lds((const unsigned*)((const char*)(gbase) + (voff)[_i]), (LAS unsigned*)(lds + (bufoff) + ldsw + _i * 8192), 16, 0, 0); } while (0)
; #define PG8_LDA(dst, b, h) do { _Pragma("unroll") for (int m = 0; m < 4; ++m) _Pragma("unroll") for (int k = 0; k < 2; ++k) dst[m][k] = *(const LAS bf16x8*)(lds + PG8_SA(b, h) + aoff + m * 2048 + k * 1024); } while (0)
; #define PG8_LDB(dst, b, h) do { _Pragma("unroll") for (int n = 0; n < 2; ++n) _Pragma("unroll") for (int k = 0; k < 2; ++k) dst[n][k] = *(const LAS bf16x8*)(lds + PG8_SB(b, h) + boff + n * 2048 + k * 1024); } while (0)
; #define PG8_MMA(ai, bj, At, Bt) do { __builtin_amdgcn_s_setprio(1); _Pragma("unroll") for (int m = 0; m < 4; ++m) _Pragma("unroll") for (int n = 0; n < 2; ++n) _Pragma("unroll") for (int k = 0; k < 2; ++k) \
;         acc[ai][bj][m][n] = __builtin_amdgcn_mfma_f32_16x16x32_bf16(Bt[n][k], At[m][k], acc[ai][bj][m][n], 0, 0, 0); __builtin_amdgcn_s_setprio(0); } while (0)
; #define PG8_WAIT_V(n) asm volatile("s_waitcnt vmcnt(" #n ")" ::: "memory")
; #define PG8_WAIT_L(n) asm volatile("s_waitcnt lgkmcnt(" #n ")" ::: "memory")
; #define PG8_BAR __builtin_amdgcn_s_barrier()
; #define PG8_SCHED __builtin_amdgcn_sched_barrier(0)
; template <class Epi, class Sched, bool ALIGN_EPI>
; __device__ __forceinline__ void gemm_phase(LAS unsigned char* lds, const Gemm g, const Sched& S, const Epi& E, const int wid) {
;     ...
;             PG8_LDB(B0, 0, 0); PG8_LDB(B1, 0, 1); PG8_SCHED; PG8_LDA(At, 0, 0); PG8_STAGE(PG8_SA(1, 1), a1 + hstepA, voffA);
;             PG8_WAIT_V(8); PG8_WAIT_L(0); PG8_BAR; PG8_MMA(0, 0, At, B0); PG8_MMA(0, 1, At, B1); PG8_BAR; PG8_SCHED;
;             PG8_LDA(At, 0, 1); PG8_STAGE(PG8_SB(0, 0), b2, voffB); PG8_STAGE(PG8_SB(0, 1), b2 + hstepB, voffB); PG8_STAGE(PG8_SA(0, 0), a2, voffA);
;             PG8_WAIT_V(8); PG8_WAIT_L(0); PG8_BAR; PG8_MMA(1, 0, At, B0); PG8_MMA(1, 1, At, B1); PG8_BAR; PG8_SCHED;
.LBB0_791:
	ds_read_b128 v[72:75], v202
	ds_read_b128 v[76:79], v202 offset:1024
	ds_read_b128 v[136:139], v202 offset:2048
	ds_read_b128 v[140:143], v202 offset:3072
	ds_read_b128 v[144:147], v203
	ds_read_b128 v[148:151], v203 offset:1024
	ds_read_b128 v[152:155], v203 offset:2048
	ds_read_b128 v[178:181], v203 offset:3072
	s_add_u32 s38, s20, 0x4000
	s_addc_u32 s39, s21, 0
	s_cmpk_eq_i32 s53, 0xfc
	s_cselect_b32 s76, s5, s38
	s_cselect_b32 s77, s4, s39
	s_cselect_b32 s74, s31, s35
	s_cselect_b32 s75, s30, s52
	s_add_u32 s72, s76, 0x8000
	s_addc_u32 s73, s77, 0
	s_add_i32 m0, s45, 0xc000
	ds_read_b128 v[182:185], v204
	ds_read_b128 v[186:189], v204 offset:1024
	ds_read_b128 v[190:193], v204 offset:2048
	ds_read_b128 v[194:197], v204 offset:3072
	ds_read_b128 v[208:211], v204 offset:4096
	ds_read_b128 v[212:215], v204 offset:5120
	ds_read_b128 v[216:219], v204 offset:6144
	ds_read_b128 v[220:223], v204 offset:7168
	global_load_lds_dwordx4 v168, s[20:21]
	s_add_i32 m0, s45, 0xe000
	s_nop 0
	global_load_lds_dwordx4 v170, s[20:21]
	s_waitcnt vmcnt(8)
	s_waitcnt lgkmcnt(0)
	s_setprio 1
	s_barrier
	v_mfma_f32_16x16x32_bf16 v[132:135], v[72:75], v[182:185], v[132:135]
	v_mfma_f32_16x16x32_bf16 v[128:131], v[136:139], v[182:185], v[128:131]
	v_mfma_f32_16x16x32_bf16 v[116:119], v[72:75], v[190:193], v[116:119]
	v_mfma_f32_16x16x32_bf16 v[112:115], v[136:139], v[190:193], v[112:115]
	v_mfma_f32_16x16x32_bf16 v[100:103], v[72:75], v[208:211], v[100:103]
	v_mfma_f32_16x16x32_bf16 v[96:99], v[136:139], v[208:211], v[96:99]
	v_mfma_f32_16x16x32_bf16 v[84:87], v[72:75], v[216:219], v[84:87]
	v_mfma_f32_16x16x32_bf16 v[80:83], v[136:139], v[216:219], v[80:83]
	v_mfma_f32_16x16x32_bf16 v[132:135], v[76:79], v[186:189], v[132:135]
	v_mfma_f32_16x16x32_bf16 v[128:131], v[140:143], v[186:189], v[128:131]
	v_mfma_f32_16x16x32_bf16 v[116:119], v[76:79], v[194:197], v[116:119]
	v_mfma_f32_16x16x32_bf16 v[112:115], v[140:143], v[194:197], v[112:115]
	v_mfma_f32_16x16x32_bf16 v[100:103], v[76:79], v[212:215], v[100:103]
	v_mfma_f32_16x16x32_bf16 v[96:99], v[140:143], v[212:215], v[96:99]
	v_mfma_f32_16x16x32_bf16 v[84:87], v[76:79], v[220:223], v[84:87]
	v_mfma_f32_16x16x32_bf16 v[80:83], v[140:143], v[220:223], v[80:83]
	s_setprio 0
	s_setprio 1
	v_mfma_f32_16x16x32_bf16 v[124:127], v[144:147], v[182:185], v[124:127]
	v_mfma_f32_16x16x32_bf16 v[120:123], v[152:155], v[182:185], v[120:123]
	v_mfma_f32_16x16x32_bf16 v[108:111], v[144:147], v[190:193], v[108:111]
	v_mfma_f32_16x16x32_bf16 v[104:107], v[152:155], v[190:193], v[104:107]
	v_mfma_f32_16x16x32_bf16 v[92:95], v[144:147], v[208:211], v[92:95]
	v_mfma_f32_16x16x32_bf16 v[88:91], v[152:155], v[208:211], v[88:91]
	v_mfma_f32_16x16x32_bf16 v[68:71], v[144:147], v[216:219], v[68:71]
	v_mfma_f32_16x16x32_bf16 v[64:67], v[152:155], v[216:219], v[64:67]
	v_mfma_f32_16x16x32_bf16 v[124:127], v[148:151], v[186:189], v[124:127]
	v_mfma_f32_16x16x32_bf16 v[120:123], v[178:181], v[186:189], v[120:123]
	v_mfma_f32_16x16x32_bf16 v[108:111], v[148:151], v[194:197], v[108:111]
	v_mfma_f32_16x16x32_bf16 v[104:107], v[178:181], v[194:197], v[104:107]
	v_mfma_f32_16x16x32_bf16 v[92:95], v[148:151], v[212:215], v[92:95]
	v_mfma_f32_16x16x32_bf16 v[88:91], v[178:181], v[212:215], v[88:91]
	v_mfma_f32_16x16x32_bf16 v[68:71], v[148:151], v[220:223], v[68:71]
	v_mfma_f32_16x16x32_bf16 v[64:67], v[178:181], v[220:223], v[64:67]
	s_barrier
	s_setprio 0
	s_add_i32 s38, s81, s3
	s_mov_b32 m0, s38
	ds_read_b128 v[182:185], v204 offset:16384
	ds_read_b128 v[186:189], v204 offset:17408
	ds_read_b128 v[190:193], v204 offset:18432
	ds_read_b128 v[194:197], v204 offset:19456
	ds_read_b128 v[208:211], v204 offset:20480
	ds_read_b128 v[212:215], v204 offset:21504
	ds_read_b128 v[216:219], v204 offset:22528
	ds_read_b128 v[220:223], v204 offset:23552
	global_load_lds_dwordx4 v158, s[74:75]
	s_add_i32 m0, s38, 0x2000
	s_add_u32 s54, s74, 0x1000
	s_addc_u32 s55, s75, 0
	s_add_i32 s38, s85, s3
	global_load_lds_dwordx4 v162, s[74:75]
	s_mov_b32 m0, s38
	s_nop 0
	global_load_lds_dwordx4 v158, s[54:55]
	s_add_i32 m0, s38, 0x2000
	s_nop 0
	global_load_lds_dwordx4 v162, s[54:55]
	s_mov_b32 m0, s45
	s_nop 0
	global_load_lds_dwordx4 v156, s[76:77]
	s_mov_b32 m0, s46
	s_nop 0
	global_load_lds_dwordx4 v160, s[76:77]
	s_waitcnt vmcnt(8)
	s_waitcnt lgkmcnt(0)
	s_setprio 1
	s_barrier
	v_mfma_f32_16x16x32_bf16 v[60:63], v[72:75], v[182:185], v[60:63]
	v_mfma_f32_16x16x32_bf16 v[56:59], v[136:139], v[182:185], v[56:59]
	v_mfma_f32_16x16x32_bf16 v[44:47], v[72:75], v[190:193], v[44:47]
	v_mfma_f32_16x16x32_bf16 v[40:43], v[136:139], v[190:193], v[40:43]
	v_mfma_f32_16x16x32_bf16 v[28:31], v[72:75], v[208:211], v[28:31]
	v_mfma_f32_16x16x32_bf16 v[24:27], v[136:139], v[208:211], v[24:27]
	v_mfma_f32_16x16x32_bf16 v[12:15], v[72:75], v[216:219], v[12:15]
	v_mfma_f32_16x16x32_bf16 v[8:11], v[136:139], v[216:219], v[8:11]
	v_mfma_f32_16x16x32_bf16 v[60:63], v[76:79], v[186:189], v[60:63]
	v_mfma_f32_16x16x32_bf16 v[56:59], v[140:143], v[186:189], v[56:59]
	v_mfma_f32_16x16x32_bf16 v[44:47], v[76:79], v[194:197], v[44:47]
	v_mfma_f32_16x16x32_bf16 v[40:43], v[140:143], v[194:197], v[40:43]
	v_mfma_f32_16x16x32_bf16 v[28:31], v[76:79], v[212:215], v[28:31]
	v_mfma_f32_16x16x32_bf16 v[24:27], v[140:143], v[212:215], v[24:27]
	v_mfma_f32_16x16x32_bf16 v[12:15], v[76:79], v[220:223], v[12:15]
	v_mfma_f32_16x16x32_bf16 v[8:11], v[140:143], v[220:223], v[8:11]
	s_setprio 0
	s_setprio 1
	v_mfma_f32_16x16x32_bf16 v[52:55], v[144:147], v[182:185], v[52:55]
	v_mfma_f32_16x16x32_bf16 v[48:51], v[152:155], v[182:185], v[48:51]
	v_mfma_f32_16x16x32_bf16 v[36:39], v[144:147], v[190:193], v[36:39]
	v_mfma_f32_16x16x32_bf16 v[32:35], v[152:155], v[190:193], v[32:35]
	v_mfma_f32_16x16x32_bf16 v[20:23], v[144:147], v[208:211], v[20:23]
	v_mfma_f32_16x16x32_bf16 v[16:19], v[152:155], v[208:211], v[16:19]
	v_mfma_f32_16x16x32_bf16 v[4:7], v[144:147], v[216:219], v[4:7]
	v_mfma_f32_16x16x32_bf16 v[0:3], v[152:155], v[216:219], v[0:3]
	v_mfma_f32_16x16x32_bf16 v[52:55], v[148:151], v[186:189], v[52:55]
	v_mfma_f32_16x16x32_bf16 v[48:51], v[178:181], v[186:189], v[48:51]
	v_mfma_f32_16x16x32_bf16 v[36:39], v[148:151], v[194:197], v[36:39]
	v_mfma_f32_16x16x32_bf16 v[32:35], v[178:181], v[194:197], v[32:35]
	v_mfma_f32_16x16x32_bf16 v[20:23], v[148:151], v[212:215], v[20:23]
	v_mfma_f32_16x16x32_bf16 v[16:19], v[178:181], v[212:215], v[16:19]
	v_mfma_f32_16x16x32_bf16 v[4:7], v[148:151], v[220:223], v[4:7]
	v_mfma_f32_16x16x32_bf16 v[0:3], v[178:181], v[220:223], v[0:3]
	s_barrier
; #define PG8_STAGE(bufoff, gbase, voff) do { _Pragma("unroll") for (int _i = 0; _i < 2; ++_i) \
;         __builtin_amdgcn_global_load_lds((const unsigned*)((const char*)(gbase) + (voff)[_i]), (LAS unsigned*)(lds + (bufoff) + ldsw + _i * 8192), 16, 0, 0); } while (0)
; #define PG8_LDA(dst, b, h) do { _Pragma("unroll") for (int m = 0; m < 4; ++m) _Pragma("unroll") for (int k = 0; k < 2; ++k) dst[m][k] = *(const LAS bf16x8*)(lds + PG8_SA(b, h) + aoff + m * 2048 + k * 1024); } while (0)
; #define PG8_LDB(dst, b, h) do { _Pragma("unroll") for (int n = 0; n < 2; ++n) _Pragma("unroll") for (int k = 0; k < 2; ++k) dst[n][k] = *(const LAS bf16x8*)(lds + PG8_SB(b, h) + boff + n * 2048 + k * 1024); } while (0)
; #define PG8_MMA(ai, bj, At, Bt) do { __builtin_amdgcn_s_setprio(1); _Pragma("unroll") for (int m = 0; m < 4; ++m) _Pragma("unroll") for (int n = 0; n < 2; ++n) _Pragma("unroll") for (int k = 0; k < 2; ++k) \
;         acc[ai][bj][m][n] = __builtin_amdgcn_mfma_f32_16x16x32_bf16(Bt[n][k], At[m][k], acc[ai][bj][m][n], 0, 0, 0); __builtin_amdgcn_s_setprio(0); } while (0)
; #define PG8_WAIT_V(n) asm volatile("s_waitcnt vmcnt(" #n ")" ::: "memory")
; #define PG8_WAIT_L(n) asm volatile("s_waitcnt lgkmcnt(" #n ")" ::: "memory")
; #define PG8_BAR __builtin_amdgcn_s_barrier()
; #define PG8_SCHED __builtin_amdgcn_sched_barrier(0)
; template <class Epi, class Sched, bool ALIGN_EPI>
; __device__ __forceinline__ void gemm_phase(LAS unsigned char* lds, const Gemm g, const Sched& S, const Epi& E, const int wid) {
;     ...
;             PG8_LDB(B0, 1, 0); PG8_LDB(B1, 1, 1); PG8_SCHED; PG8_LDA(At, 1, 0); PG8_STAGE(PG8_SA(0, 1), a2 + hstepA, voffA);
;             PG8_WAIT_V(8); PG8_WAIT_L(0); PG8_BAR; PG8_MMA(0, 0, At, B0); PG8_MMA(0, 1, At, B1); PG8_BAR; PG8_SCHED;
;             PG8_LDA(At, 1, 1); PG8_STAGE(PG8_SB(1, 0), b3, voffB); PG8_STAGE(PG8_SB(1, 1), b3 + hstepB, voffB); PG8_STAGE(PG8_SA(1, 0), a3, voffA);
;             PG8_WAIT_V(8); PG8_WAIT_L(0); PG8_BAR; PG8_MMA(1, 0, At, B0); PG8_MMA(1, 1, At, B1); PG8_BAR; PG8_SCHED;
;         }
;         if constexpr (ALIGN_EPI) { if (wr == 0) PG8_BAR; }
	s_setprio 0
	s_add_i32 s38, 0, 0x18000
	s_add_i32 s39, 0, 0x1c000
	v_add_u32_e32 v140, s38, v198
	v_add_u32_e32 v164, s39, v198
	ds_read_b128 v[72:75], v140
	ds_read_b128 v[76:79], v140 offset:1024
	ds_read_b128 v[136:139], v140 offset:2048
	ds_read_b128 v[140:143], v140 offset:3072
	ds_read_b128 v[144:147], v164
	ds_read_b128 v[148:151], v164 offset:1024
	ds_read_b128 v[152:155], v164 offset:2048
	ds_read_b128 v[178:181], v164 offset:3072
	s_add_u32 s54, s76, 0x4000
	s_addc_u32 s55, s77, 0
	s_mov_b32 m0, s47
	ds_read_b128 v[182:185], v204 offset:32768
	ds_read_b128 v[186:189], v204 offset:33792
	ds_read_b128 v[190:193], v204 offset:34816
	ds_read_b128 v[194:197], v204 offset:35840
	ds_read_b128 v[208:211], v204 offset:36864
	ds_read_b128 v[212:215], v204 offset:37888
	ds_read_b128 v[216:219], v204 offset:38912
	ds_read_b128 v[220:223], v204 offset:39936
	global_load_lds_dwordx4 v156, s[54:55]
	s_mov_b32 m0, s49
	s_nop 0
	global_load_lds_dwordx4 v160, s[54:55]
	s_waitcnt vmcnt(8)
	s_waitcnt lgkmcnt(0)
	s_setprio 1
	s_barrier
	v_mfma_f32_16x16x32_bf16 v[132:135], v[72:75], v[182:185], v[132:135]
	v_mfma_f32_16x16x32_bf16 v[128:131], v[136:139], v[182:185], v[128:131]
	v_mfma_f32_16x16x32_bf16 v[116:119], v[72:75], v[190:193], v[116:119]
	v_mfma_f32_16x16x32_bf16 v[112:115], v[136:139], v[190:193], v[112:115]
	v_mfma_f32_16x16x32_bf16 v[100:103], v[72:75], v[208:211], v[100:103]
	v_mfma_f32_16x16x32_bf16 v[96:99], v[136:139], v[208:211], v[96:99]
	v_mfma_f32_16x16x32_bf16 v[84:87], v[72:75], v[216:219], v[84:87]
	v_mfma_f32_16x16x32_bf16 v[80:83], v[136:139], v[216:219], v[80:83]
	v_mfma_f32_16x16x32_bf16 v[132:135], v[76:79], v[186:189], v[132:135]
	v_mfma_f32_16x16x32_bf16 v[128:131], v[140:143], v[186:189], v[128:131]
	v_mfma_f32_16x16x32_bf16 v[116:119], v[76:79], v[194:197], v[116:119]
	v_mfma_f32_16x16x32_bf16 v[112:115], v[140:143], v[194:197], v[112:115]
	v_mfma_f32_16x16x32_bf16 v[100:103], v[76:79], v[212:215], v[100:103]
	v_mfma_f32_16x16x32_bf16 v[96:99], v[140:143], v[212:215], v[96:99]
	v_mfma_f32_16x16x32_bf16 v[84:87], v[76:79], v[220:223], v[84:87]
	v_mfma_f32_16x16x32_bf16 v[80:83], v[140:143], v[220:223], v[80:83]
	s_setprio 0
	s_setprio 1
	v_mfma_f32_16x16x32_bf16 v[124:127], v[144:147], v[182:185], v[124:127]
	v_mfma_f32_16x16x32_bf16 v[120:123], v[152:155], v[182:185], v[120:123]
	v_mfma_f32_16x16x32_bf16 v[108:111], v[144:147], v[190:193], v[108:111]
	v_mfma_f32_16x16x32_bf16 v[104:107], v[152:155], v[190:193], v[104:107]
	v_mfma_f32_16x16x32_bf16 v[92:95], v[144:147], v[208:211], v[92:95]
	v_mfma_f32_16x16x32_bf16 v[88:91], v[152:155], v[208:211], v[88:91]
	v_mfma_f32_16x16x32_bf16 v[68:71], v[144:147], v[216:219], v[68:71]
	v_mfma_f32_16x16x32_bf16 v[64:67], v[152:155], v[216:219], v[64:67]
	v_mfma_f32_16x16x32_bf16 v[124:127], v[148:151], v[186:189], v[124:127]
	v_mfma_f32_16x16x32_bf16 v[120:123], v[178:181], v[186:189], v[120:123]
	v_mfma_f32_16x16x32_bf16 v[108:111], v[148:151], v[194:197], v[108:111]
	v_mfma_f32_16x16x32_bf16 v[104:107], v[178:181], v[194:197], v[104:107]
	v_mfma_f32_16x16x32_bf16 v[92:95], v[148:151], v[212:215], v[92:95]
	v_mfma_f32_16x16x32_bf16 v[88:91], v[178:181], v[212:215], v[88:91]
	v_mfma_f32_16x16x32_bf16 v[68:71], v[148:151], v[220:223], v[68:71]
	v_mfma_f32_16x16x32_bf16 v[64:67], v[178:181], v[220:223], v[64:67]
	s_barrier
	s_setprio 0
	s_add_u32 s54, s74, 0x8000
	s_addc_u32 s55, s75, 0
	s_add_i32 s38, s38, s3
	s_mov_b32 m0, s38
	ds_read_b128 v[182:185], v204 offset:49152
	ds_read_b128 v[186:189], v204 offset:50176
	ds_read_b128 v[190:193], v204 offset:51200
	ds_read_b128 v[194:197], v204 offset:52224
	ds_read_b128 v[208:211], v204 offset:53248
	ds_read_b128 v[212:215], v204 offset:54272
	ds_read_b128 v[216:219], v204 offset:55296
	ds_read_b128 v[220:223], v204 offset:56320
	global_load_lds_dwordx4 v158, s[54:55]
	s_add_i32 m0, s38, 0x2000
	s_nop 0
	global_load_lds_dwordx4 v162, s[54:55]
	s_add_u32 s54, s74, 0x9000
	s_addc_u32 s55, s75, 0
	s_add_i32 s38, s39, s3
	s_mov_b32 m0, s38
	s_nop 0
	global_load_lds_dwordx4 v158, s[54:55]
	s_add_i32 m0, s38, 0x2000
	s_nop 0
	global_load_lds_dwordx4 v162, s[54:55]
	s_mov_b32 m0, s78
	s_nop 0
	global_load_lds_dwordx4 v156, s[72:73]
	s_mov_b32 m0, s79
	s_nop 0
	global_load_lds_dwordx4 v160, s[72:73]
	s_waitcnt vmcnt(8)
	s_waitcnt lgkmcnt(0)
	s_setprio 1
	s_barrier
	v_mfma_f32_16x16x32_bf16 v[60:63], v[72:75], v[182:185], v[60:63]
	v_mfma_f32_16x16x32_bf16 v[56:59], v[136:139], v[182:185], v[56:59]
	v_mfma_f32_16x16x32_bf16 v[44:47], v[72:75], v[190:193], v[44:47]
	v_mfma_f32_16x16x32_bf16 v[40:43], v[136:139], v[190:193], v[40:43]
	v_mfma_f32_16x16x32_bf16 v[28:31], v[72:75], v[208:211], v[28:31]
	v_mfma_f32_16x16x32_bf16 v[24:27], v[136:139], v[208:211], v[24:27]
	v_mfma_f32_16x16x32_bf16 v[12:15], v[72:75], v[216:219], v[12:15]
	v_mfma_f32_16x16x32_bf16 v[8:11], v[136:139], v[216:219], v[8:11]
	v_mfma_f32_16x16x32_bf16 v[60:63], v[76:79], v[186:189], v[60:63]
	v_mfma_f32_16x16x32_bf16 v[56:59], v[140:143], v[186:189], v[56:59]
	v_mfma_f32_16x16x32_bf16 v[44:47], v[76:79], v[194:197], v[44:47]
	v_mfma_f32_16x16x32_bf16 v[40:43], v[140:143], v[194:197], v[40:43]
	v_mfma_f32_16x16x32_bf16 v[28:31], v[76:79], v[212:215], v[28:31]
	v_mfma_f32_16x16x32_bf16 v[24:27], v[140:143], v[212:215], v[24:27]
	v_mfma_f32_16x16x32_bf16 v[12:15], v[76:79], v[220:223], v[12:15]
	v_mfma_f32_16x16x32_bf16 v[8:11], v[140:143], v[220:223], v[8:11]
	s_setprio 0
	s_setprio 1
	v_mfma_f32_16x16x32_bf16 v[52:55], v[144:147], v[182:185], v[52:55]
	v_mfma_f32_16x16x32_bf16 v[48:51], v[152:155], v[182:185], v[48:51]
	v_mfma_f32_16x16x32_bf16 v[36:39], v[144:147], v[190:193], v[36:39]
	v_mfma_f32_16x16x32_bf16 v[32:35], v[152:155], v[190:193], v[32:35]
	v_mfma_f32_16x16x32_bf16 v[20:23], v[144:147], v[208:211], v[20:23]
	v_mfma_f32_16x16x32_bf16 v[16:19], v[152:155], v[208:211], v[16:19]
	v_mfma_f32_16x16x32_bf16 v[4:7], v[144:147], v[216:219], v[4:7]
	v_mfma_f32_16x16x32_bf16 v[0:3], v[152:155], v[216:219], v[0:3]
	v_mfma_f32_16x16x32_bf16 v[52:55], v[148:151], v[186:189], v[52:55]
	v_mfma_f32_16x16x32_bf16 v[48:51], v[178:181], v[186:189], v[48:51]
	v_mfma_f32_16x16x32_bf16 v[36:39], v[148:151], v[194:197], v[36:39]
	v_mfma_f32_16x16x32_bf16 v[32:35], v[178:181], v[194:197], v[32:35]
	v_mfma_f32_16x16x32_bf16 v[20:23], v[148:151], v[212:215], v[20:23]
	v_mfma_f32_16x16x32_bf16 v[16:19], v[178:181], v[212:215], v[16:19]
	v_mfma_f32_16x16x32_bf16 v[4:7], v[148:151], v[220:223], v[4:7]
	v_mfma_f32_16x16x32_bf16 v[0:3], v[178:181], v[220:223], v[0:3]
	s_barrier
	s_setprio 0
	s_add_i32 s53, s53, 2
	s_add_u32 s35, s35, 0x10000
	s_addc_u32 s52, s52, 0
	s_add_u32 s20, s20, 0x10000
	s_addc_u32 s21, s21, 0
	s_cmpk_gt_u32 s53, 0xfd
	s_cbranch_scc0 .LBB0_791
	s_and_b64 vcc, exec, s[28:29]
	s_cbranch_vccz .LBB0_794
	s_barrier

; #define PG8_STAGE(bufoff, gbase, voff) do { _Pragma("unroll") for (int _i = 0; _i < 2; ++_i) \
;         __builtin_amdgcn_global_load_lds((const unsigned*)((const char*)(gbase) + (voff)[_i]), (LAS unsigned*)(lds + (bufoff) + ldsw + _i * 8192), 16, 0, 0); } while (0)
; #define PG8_LDA(dst, b, h) do { _Pragma("unroll") for (int m = 0; m < 4; ++m) _Pragma("unroll") for (int k = 0; k < 2; ++k) dst[m][k] = *(const LAS bf16x8*)(lds + PG8_SA(b, h) + aoff + m * 2048 + k * 1024); } while (0)
; #define PG8_LDB(dst, b, h) do { _Pragma("unroll") for (int n = 0; n < 2; ++n) _Pragma("unroll") for (int k = 0; k < 2; ++k) dst[n][k] = *(const LAS bf16x8*)(lds + PG8_SB(b, h) + boff + n * 2048 + k * 1024); } while (0)
; #define PG8_MMA(ai, bj, At, Bt) do { __builtin_amdgcn_s_setprio(1); _Pragma("unroll") for (int m = 0; m < 4; ++m) _Pragma("unroll") for (int n = 0; n < 2; ++n) _Pragma("unroll") for (int k = 0; k < 2; ++k) \
;         acc[ai][bj][m][n] = __builtin_amdgcn_mfma_f32_16x16x32_bf16(Bt[n][k], At[m][k], acc[ai][bj][m][n], 0, 0, 0); __builtin_amdgcn_s_setprio(0); } while (0)
; #define PG8_WAIT_V(n) asm volatile("s_waitcnt vmcnt(" #n ")" ::: "memory")
; #define PG8_WAIT_L(n) asm volatile("s_waitcnt lgkmcnt(" #n ")" ::: "memory")
; #define PG8_BAR __builtin_amdgcn_s_barrier()
; #define PG8_SCHED __builtin_amdgcn_sched_barrier(0)
; template <class Epi, class Sched, bool ALIGN_EPI>
; __device__ __forceinline__ void gemm_phase(LAS unsigned char* lds, const Gemm g, const Sched& S, const Epi& E, const int wid) {
;     ...
;             PG8_LDB(B0, 0, 0); PG8_LDB(B1, 0, 1); PG8_SCHED; PG8_LDA(At, 0, 0); PG8_STAGE(PG8_SA(1, 1), a1 + hstepA, voffA);
;             PG8_WAIT_V(8); PG8_WAIT_L(0); PG8_BAR; PG8_MMA(0, 0, At, B0); PG8_MMA(0, 1, At, B1); PG8_BAR; PG8_SCHED;
;             PG8_LDA(At, 0, 1); PG8_STAGE(PG8_SB(0, 0), b2, voffB); PG8_STAGE(PG8_SB(0, 1), b2 + hstepB, voffB); PG8_STAGE(PG8_SA(0, 0), a2, voffA);
;             PG8_WAIT_V(8); PG8_WAIT_L(0); PG8_BAR; PG8_MMA(1, 0, At, B0); PG8_MMA(1, 1, At, B1); PG8_BAR; PG8_SCHED;
.LBB0_920:
	v_add_u32_e32 v142, s89, v170
	s_waitcnt lgkmcnt(0)
	ds_read_b128 v[130:133], v142
	ds_read_b128 v[134:137], v142 offset:1024
	ds_read_b128 v[138:141], v142 offset:2048
	ds_read_b128 v[182:185], v142 offset:3072
	v_add_u32_e32 v142, s90, v170
	s_add_u32 s38, s68, 0x4000
	ds_read_b128 v[186:189], v142
	ds_read_b128 v[190:193], v142 offset:1024
	ds_read_b128 v[194:197], v142 offset:2048
	ds_read_b128 v[198:201], v142 offset:3072
	s_addc_u32 s39, s69, 0
	s_and_b64 s[70:71], s[72:73], exec
	s_cselect_b32 s74, s5, s38
	s_cselect_b32 s75, s4, s39
	s_add_u32 s70, s74, 0x8000
	s_addc_u32 s71, s75, 0
	s_and_b64 s[72:73], s[72:73], exec
	s_cselect_b32 s73, s19, s35
	s_cselect_b32 s72, s30, s31
	s_add_i32 m0, s44, 0xc000
	ds_read_b128 v[202:205], v177
	ds_read_b128 v[206:209], v177 offset:1024
	ds_read_b128 v[210:213], v177 offset:2048
	ds_read_b128 v[214:217], v177 offset:3072
	ds_read_b128 v[218:221], v177 offset:4096
	ds_read_b128 v[222:225], v177 offset:5120
	ds_read_b128 v[226:229], v177 offset:6144
	ds_read_b128 v[230:233], v177 offset:7168
	global_load_lds_dwordx4 v158, s[68:69]
	s_add_i32 m0, s44, 0xe000
	s_nop 0
	global_load_lds_dwordx4 v160, s[68:69]
	s_waitcnt vmcnt(8)
	s_waitcnt lgkmcnt(0)
	s_setprio 1
	s_barrier
	v_mfma_f32_16x16x32_bf16 v[124:127], v[130:133], v[202:205], v[124:127]
	v_mfma_f32_16x16x32_bf16 v[120:123], v[138:141], v[202:205], v[120:123]
	v_mfma_f32_16x16x32_bf16 v[108:111], v[130:133], v[210:213], v[108:111]
	v_mfma_f32_16x16x32_bf16 v[104:107], v[138:141], v[210:213], v[104:107]
	v_mfma_f32_16x16x32_bf16 v[92:95], v[130:133], v[218:221], v[92:95]
	v_mfma_f32_16x16x32_bf16 v[88:91], v[138:141], v[218:221], v[88:91]
	v_mfma_f32_16x16x32_bf16 v[76:79], v[130:133], v[226:229], v[76:79]
	v_mfma_f32_16x16x32_bf16 v[72:75], v[138:141], v[226:229], v[72:75]
	v_mfma_f32_16x16x32_bf16 v[124:127], v[134:137], v[206:209], v[124:127]
	v_mfma_f32_16x16x32_bf16 v[120:123], v[182:185], v[206:209], v[120:123]
	v_mfma_f32_16x16x32_bf16 v[108:111], v[134:137], v[214:217], v[108:111]
	v_mfma_f32_16x16x32_bf16 v[104:107], v[182:185], v[214:217], v[104:107]
	v_mfma_f32_16x16x32_bf16 v[92:95], v[134:137], v[222:225], v[92:95]
	v_mfma_f32_16x16x32_bf16 v[88:91], v[182:185], v[222:225], v[88:91]
	v_mfma_f32_16x16x32_bf16 v[76:79], v[134:137], v[230:233], v[76:79]
	v_mfma_f32_16x16x32_bf16 v[72:75], v[182:185], v[230:233], v[72:75]
	s_setprio 0
	s_setprio 1
	v_mfma_f32_16x16x32_bf16 v[116:119], v[186:189], v[202:205], v[116:119]
	v_mfma_f32_16x16x32_bf16 v[112:115], v[194:197], v[202:205], v[112:115]
	v_mfma_f32_16x16x32_bf16 v[100:103], v[186:189], v[210:213], v[100:103]
	v_mfma_f32_16x16x32_bf16 v[96:99], v[194:197], v[210:213], v[96:99]
	v_mfma_f32_16x16x32_bf16 v[84:87], v[186:189], v[218:221], v[84:87]
	v_mfma_f32_16x16x32_bf16 v[80:83], v[194:197], v[218:221], v[80:83]
	v_mfma_f32_16x16x32_bf16 v[68:71], v[186:189], v[226:229], v[68:71]
	v_mfma_f32_16x16x32_bf16 v[64:67], v[194:197], v[226:229], v[64:67]
	v_mfma_f32_16x16x32_bf16 v[116:119], v[190:193], v[206:209], v[116:119]
	v_mfma_f32_16x16x32_bf16 v[112:115], v[198:201], v[206:209], v[112:115]
	v_mfma_f32_16x16x32_bf16 v[100:103], v[190:193], v[214:217], v[100:103]
	v_mfma_f32_16x16x32_bf16 v[96:99], v[198:201], v[214:217], v[96:99]
	v_mfma_f32_16x16x32_bf16 v[84:87], v[190:193], v[222:225], v[84:87]
	v_mfma_f32_16x16x32_bf16 v[80:83], v[198:201], v[222:225], v[80:83]
	v_mfma_f32_16x16x32_bf16 v[68:71], v[190:193], v[230:233], v[68:71]
	v_mfma_f32_16x16x32_bf16 v[64:67], v[198:201], v[230:233], v[64:67]
	s_barrier
	s_setprio 0
	s_add_i32 s38, s89, s3
	s_mov_b32 m0, s38
	ds_read_b128 v[202:205], v177 offset:16384
	ds_read_b128 v[206:209], v177 offset:17408
	ds_read_b128 v[210:213], v177 offset:18432
	ds_read_b128 v[214:217], v177 offset:19456
	ds_read_b128 v[218:221], v177 offset:20480
	ds_read_b128 v[222:225], v177 offset:21504
	ds_read_b128 v[226:229], v177 offset:22528
	ds_read_b128 v[230:233], v177 offset:23552
	global_load_lds_dwordx4 v146, s[72:73]
	s_add_i32 m0, s38, 0x2000
	s_add_u32 s94, s72, 0x1000
	s_addc_u32 s95, s73, 0
	s_add_i32 s38, s90, s3
	global_load_lds_dwordx4 v150, s[72:73]
	s_mov_b32 m0, s38
	s_nop 0
	global_load_lds_dwordx4 v146, s[94:95]
	s_add_i32 m0, s38, 0x2000
	s_nop 0
	global_load_lds_dwordx4 v150, s[94:95]
	s_mov_b32 m0, s44
	s_nop 0
	global_load_lds_dwordx4 v144, s[74:75]
	s_mov_b32 m0, s45
	s_nop 0
	global_load_lds_dwordx4 v148, s[74:75]
	s_waitcnt vmcnt(8)
	s_waitcnt lgkmcnt(0)
	s_setprio 1
	s_barrier
	v_mfma_f32_16x16x32_bf16 v[60:63], v[130:133], v[202:205], v[60:63]
	v_mfma_f32_16x16x32_bf16 v[56:59], v[138:141], v[202:205], v[56:59]
	v_mfma_f32_16x16x32_bf16 v[44:47], v[130:133], v[210:213], v[44:47]
	v_mfma_f32_16x16x32_bf16 v[40:43], v[138:141], v[210:213], v[40:43]
	v_mfma_f32_16x16x32_bf16 v[28:31], v[130:133], v[218:221], v[28:31]
	v_mfma_f32_16x16x32_bf16 v[24:27], v[138:141], v[218:221], v[24:27]
	v_mfma_f32_16x16x32_bf16 v[12:15], v[130:133], v[226:229], v[12:15]
	v_mfma_f32_16x16x32_bf16 v[8:11], v[138:141], v[226:229], v[8:11]
	v_mfma_f32_16x16x32_bf16 v[60:63], v[134:137], v[206:209], v[60:63]
	v_mfma_f32_16x16x32_bf16 v[56:59], v[182:185], v[206:209], v[56:59]
	v_mfma_f32_16x16x32_bf16 v[44:47], v[134:137], v[214:217], v[44:47]
	v_mfma_f32_16x16x32_bf16 v[40:43], v[182:185], v[214:217], v[40:43]
	v_mfma_f32_16x16x32_bf16 v[28:31], v[134:137], v[222:225], v[28:31]
	v_mfma_f32_16x16x32_bf16 v[24:27], v[182:185], v[222:225], v[24:27]
	v_mfma_f32_16x16x32_bf16 v[12:15], v[134:137], v[230:233], v[12:15]
	v_mfma_f32_16x16x32_bf16 v[8:11], v[182:185], v[230:233], v[8:11]
	s_setprio 0
	s_setprio 1
	v_mfma_f32_16x16x32_bf16 v[52:55], v[186:189], v[202:205], v[52:55]
	v_mfma_f32_16x16x32_bf16 v[48:51], v[194:197], v[202:205], v[48:51]
	v_mfma_f32_16x16x32_bf16 v[36:39], v[186:189], v[210:213], v[36:39]
	v_mfma_f32_16x16x32_bf16 v[32:35], v[194:197], v[210:213], v[32:35]
	v_mfma_f32_16x16x32_bf16 v[20:23], v[186:189], v[218:221], v[20:23]
	v_mfma_f32_16x16x32_bf16 v[16:19], v[194:197], v[218:221], v[16:19]
	v_mfma_f32_16x16x32_bf16 v[4:7], v[186:189], v[226:229], v[4:7]
	v_mfma_f32_16x16x32_bf16 v[0:3], v[194:197], v[226:229], v[0:3]
	v_mfma_f32_16x16x32_bf16 v[52:55], v[190:193], v[206:209], v[52:55]
	v_mfma_f32_16x16x32_bf16 v[48:51], v[198:201], v[206:209], v[48:51]
	v_mfma_f32_16x16x32_bf16 v[36:39], v[190:193], v[214:217], v[36:39]
	v_mfma_f32_16x16x32_bf16 v[32:35], v[198:201], v[214:217], v[32:35]
	v_mfma_f32_16x16x32_bf16 v[20:23], v[190:193], v[222:225], v[20:23]
	v_mfma_f32_16x16x32_bf16 v[16:19], v[198:201], v[222:225], v[16:19]
	v_mfma_f32_16x16x32_bf16 v[4:7], v[190:193], v[230:233], v[4:7]
	v_mfma_f32_16x16x32_bf16 v[0:3], v[198:201], v[230:233], v[0:3]
	s_barrier
; #define PG8_STAGE(bufoff, gbase, voff) do { _Pragma("unroll") for (int _i = 0; _i < 2; ++_i) \
;         __builtin_amdgcn_global_load_lds((const unsigned*)((const char*)(gbase) + (voff)[_i]), (LAS unsigned*)(lds + (bufoff) + ldsw + _i * 8192), 16, 0, 0); } while (0)
; #define PG8_LDA(dst, b, h) do { _Pragma("unroll") for (int m = 0; m < 4; ++m) _Pragma("unroll") for (int k = 0; k < 2; ++k) dst[m][k] = *(const LAS bf16x8*)(lds + PG8_SA(b, h) + aoff + m * 2048 + k * 1024); } while (0)
; #define PG8_LDB(dst, b, h) do { _Pragma("unroll") for (int n = 0; n < 2; ++n) _Pragma("unroll") for (int k = 0; k < 2; ++k) dst[n][k] = *(const LAS bf16x8*)(lds + PG8_SB(b, h) + boff + n * 2048 + k * 1024); } while (0)
; #define PG8_MMA(ai, bj, At, Bt) do { __builtin_amdgcn_s_setprio(1); _Pragma("unroll") for (int m = 0; m < 4; ++m) _Pragma("unroll") for (int n = 0; n < 2; ++n) _Pragma("unroll") for (int k = 0; k < 2; ++k) \
;         acc[ai][bj][m][n] = __builtin_amdgcn_mfma_f32_16x16x32_bf16(Bt[n][k], At[m][k], acc[ai][bj][m][n], 0, 0, 0); __builtin_amdgcn_s_setprio(0); } while (0)
; #define PG8_WAIT_V(n) asm volatile("s_waitcnt vmcnt(" #n ")" ::: "memory")
; #define PG8_WAIT_L(n) asm volatile("s_waitcnt lgkmcnt(" #n ")" ::: "memory")
; #define PG8_BAR __builtin_amdgcn_s_barrier()
; #define PG8_SCHED __builtin_amdgcn_sched_barrier(0)
; template <class Epi, class Sched, bool ALIGN_EPI>
; __device__ __forceinline__ void gemm_phase(LAS unsigned char* lds, const Gemm g, const Sched& S, const Epi& E, const int wid) {
;     ...
;             PG8_LDB(B0, 1, 0); PG8_LDB(B1, 1, 1); PG8_SCHED; PG8_LDA(At, 1, 0); PG8_STAGE(PG8_SA(0, 1), a2 + hstepA, voffA);
;             PG8_WAIT_V(8); PG8_WAIT_L(0); PG8_BAR; PG8_MMA(0, 0, At, B0); PG8_MMA(0, 1, At, B1); PG8_BAR; PG8_SCHED;
;             PG8_LDA(At, 1, 1); PG8_STAGE(PG8_SB(1, 0), b3, voffB); PG8_STAGE(PG8_SB(1, 1), b3 + hstepB, voffB); PG8_STAGE(PG8_SA(1, 0), a3, voffA);
;             PG8_WAIT_V(8); PG8_WAIT_L(0); PG8_BAR; PG8_MMA(1, 0, At, B0); PG8_MMA(1, 1, At, B1); PG8_BAR; PG8_SCHED;
;         }
;         if constexpr (ALIGN_EPI) { if (wr == 0) PG8_BAR; }
	s_setprio 0
	s_add_i32 s38, 0, 0x18000
	v_add_u32_e32 v142, s38, v170
	s_add_i32 s39, 0, 0x1c000
	ds_read_b128 v[130:133], v142
	ds_read_b128 v[134:137], v142 offset:1024
	ds_read_b128 v[138:141], v142 offset:2048
	ds_read_b128 v[182:185], v142 offset:3072
	v_add_u32_e32 v142, s39, v170
	ds_read_b128 v[186:189], v142
	ds_read_b128 v[190:193], v142 offset:1024
	ds_read_b128 v[194:197], v142 offset:2048
	ds_read_b128 v[198:201], v142 offset:3072
	s_add_u32 s74, s74, 0x4000
	s_addc_u32 s75, s75, 0
	s_mov_b32 m0, s46
	ds_read_b128 v[202:205], v177 offset:32768
	ds_read_b128 v[206:209], v177 offset:33792
	ds_read_b128 v[210:213], v177 offset:34816
	ds_read_b128 v[214:217], v177 offset:35840
	ds_read_b128 v[218:221], v177 offset:36864
	ds_read_b128 v[222:225], v177 offset:37888
	ds_read_b128 v[226:229], v177 offset:38912
	ds_read_b128 v[230:233], v177 offset:39936
	global_load_lds_dwordx4 v144, s[74:75]
	s_mov_b32 m0, s47
	s_nop 0
	global_load_lds_dwordx4 v148, s[74:75]
	s_waitcnt vmcnt(8)
	s_waitcnt lgkmcnt(0)
	s_setprio 1
	s_barrier
	v_mfma_f32_16x16x32_bf16 v[124:127], v[130:133], v[202:205], v[124:127]
	v_mfma_f32_16x16x32_bf16 v[120:123], v[138:141], v[202:205], v[120:123]
	v_mfma_f32_16x16x32_bf16 v[108:111], v[130:133], v[210:213], v[108:111]
	v_mfma_f32_16x16x32_bf16 v[104:107], v[138:141], v[210:213], v[104:107]
	v_mfma_f32_16x16x32_bf16 v[92:95], v[130:133], v[218:221], v[92:95]
	v_mfma_f32_16x16x32_bf16 v[88:91], v[138:141], v[218:221], v[88:91]
	v_mfma_f32_16x16x32_bf16 v[76:79], v[130:133], v[226:229], v[76:79]
	v_mfma_f32_16x16x32_bf16 v[72:75], v[138:141], v[226:229], v[72:75]
	v_mfma_f32_16x16x32_bf16 v[124:127], v[134:137], v[206:209], v[124:127]
	v_mfma_f32_16x16x32_bf16 v[120:123], v[182:185], v[206:209], v[120:123]
	v_mfma_f32_16x16x32_bf16 v[108:111], v[134:137], v[214:217], v[108:111]
	v_mfma_f32_16x16x32_bf16 v[104:107], v[182:185], v[214:217], v[104:107]
	v_mfma_f32_16x16x32_bf16 v[92:95], v[134:137], v[222:225], v[92:95]
	v_mfma_f32_16x16x32_bf16 v[88:91], v[182:185], v[222:225], v[88:91]
	v_mfma_f32_16x16x32_bf16 v[76:79], v[134:137], v[230:233], v[76:79]
	v_mfma_f32_16x16x32_bf16 v[72:75], v[182:185], v[230:233], v[72:75]
	s_setprio 0
	s_setprio 1
	v_mfma_f32_16x16x32_bf16 v[116:119], v[186:189], v[202:205], v[116:119]
	v_mfma_f32_16x16x32_bf16 v[112:115], v[194:197], v[202:205], v[112:115]
	v_mfma_f32_16x16x32_bf16 v[100:103], v[186:189], v[210:213], v[100:103]
	v_mfma_f32_16x16x32_bf16 v[96:99], v[194:197], v[210:213], v[96:99]
	v_mfma_f32_16x16x32_bf16 v[84:87], v[186:189], v[218:221], v[84:87]
	v_mfma_f32_16x16x32_bf16 v[80:83], v[194:197], v[218:221], v[80:83]
	v_mfma_f32_16x16x32_bf16 v[68:71], v[186:189], v[226:229], v[68:71]
	v_mfma_f32_16x16x32_bf16 v[64:67], v[194:197], v[226:229], v[64:67]
	v_mfma_f32_16x16x32_bf16 v[116:119], v[190:193], v[206:209], v[116:119]
	v_mfma_f32_16x16x32_bf16 v[112:115], v[198:201], v[206:209], v[112:115]
	v_mfma_f32_16x16x32_bf16 v[100:103], v[190:193], v[214:217], v[100:103]
	v_mfma_f32_16x16x32_bf16 v[96:99], v[198:201], v[214:217], v[96:99]
	v_mfma_f32_16x16x32_bf16 v[84:87], v[190:193], v[222:225], v[84:87]
	v_mfma_f32_16x16x32_bf16 v[80:83], v[198:201], v[222:225], v[80:83]
	v_mfma_f32_16x16x32_bf16 v[68:71], v[190:193], v[230:233], v[68:71]
	v_mfma_f32_16x16x32_bf16 v[64:67], v[198:201], v[230:233], v[64:67]
	s_barrier
	s_setprio 0
	s_add_u32 s74, s72, 0x8000
	s_addc_u32 s75, s73, 0
	s_add_i32 s38, s38, s3
	s_mov_b32 m0, s38
	ds_read_b128 v[202:205], v177 offset:49152
	ds_read_b128 v[206:209], v177 offset:50176
	ds_read_b128 v[210:213], v177 offset:51200
	ds_read_b128 v[214:217], v177 offset:52224
	ds_read_b128 v[218:221], v177 offset:53248
	ds_read_b128 v[222:225], v177 offset:54272
	ds_read_b128 v[226:229], v177 offset:55296
	ds_read_b128 v[230:233], v177 offset:56320
	global_load_lds_dwordx4 v146, s[74:75]
	s_add_i32 m0, s38, 0x2000
	s_add_u32 s72, s72, 0x9000
	s_addc_u32 s73, s73, 0
	s_add_i32 s38, s39, s3
	global_load_lds_dwordx4 v150, s[74:75]
	s_mov_b32 m0, s38
	s_nop 0
	global_load_lds_dwordx4 v146, s[72:73]
	s_add_i32 m0, s38, 0x2000
	s_nop 0
	global_load_lds_dwordx4 v150, s[72:73]
	s_mov_b32 m0, s79
	s_nop 0
	global_load_lds_dwordx4 v144, s[70:71]
	s_mov_b32 m0, s80
	s_nop 0
	global_load_lds_dwordx4 v148, s[70:71]
	s_waitcnt vmcnt(8)
	s_waitcnt lgkmcnt(0)
	s_setprio 1
	s_barrier
	v_mfma_f32_16x16x32_bf16 v[60:63], v[130:133], v[202:205], v[60:63]
	v_mfma_f32_16x16x32_bf16 v[56:59], v[138:141], v[202:205], v[56:59]
	v_mfma_f32_16x16x32_bf16 v[44:47], v[130:133], v[210:213], v[44:47]
	v_mfma_f32_16x16x32_bf16 v[40:43], v[138:141], v[210:213], v[40:43]
	v_mfma_f32_16x16x32_bf16 v[28:31], v[130:133], v[218:221], v[28:31]
	v_mfma_f32_16x16x32_bf16 v[24:27], v[138:141], v[218:221], v[24:27]
	v_mfma_f32_16x16x32_bf16 v[12:15], v[130:133], v[226:229], v[12:15]
	v_mfma_f32_16x16x32_bf16 v[8:11], v[138:141], v[226:229], v[8:11]
	v_mfma_f32_16x16x32_bf16 v[60:63], v[134:137], v[206:209], v[60:63]
	v_mfma_f32_16x16x32_bf16 v[56:59], v[182:185], v[206:209], v[56:59]
	v_mfma_f32_16x16x32_bf16 v[44:47], v[134:137], v[214:217], v[44:47]
	v_mfma_f32_16x16x32_bf16 v[40:43], v[182:185], v[214:217], v[40:43]
	v_mfma_f32_16x16x32_bf16 v[28:31], v[134:137], v[222:225], v[28:31]
	v_mfma_f32_16x16x32_bf16 v[24:27], v[182:185], v[222:225], v[24:27]
	v_mfma_f32_16x16x32_bf16 v[12:15], v[134:137], v[230:233], v[12:15]
	v_mfma_f32_16x16x32_bf16 v[8:11], v[182:185], v[230:233], v[8:11]
	s_setprio 0
	s_setprio 1
	v_mfma_f32_16x16x32_bf16 v[52:55], v[186:189], v[202:205], v[52:55]
	v_mfma_f32_16x16x32_bf16 v[48:51], v[194:197], v[202:205], v[48:51]
	v_mfma_f32_16x16x32_bf16 v[36:39], v[186:189], v[210:213], v[36:39]
	v_mfma_f32_16x16x32_bf16 v[32:35], v[194:197], v[210:213], v[32:35]
	v_mfma_f32_16x16x32_bf16 v[20:23], v[186:189], v[218:221], v[20:23]
	v_mfma_f32_16x16x32_bf16 v[16:19], v[194:197], v[218:221], v[16:19]
	v_mfma_f32_16x16x32_bf16 v[4:7], v[186:189], v[226:229], v[4:7]
	v_mfma_f32_16x16x32_bf16 v[0:3], v[194:197], v[226:229], v[0:3]
	v_mfma_f32_16x16x32_bf16 v[52:55], v[190:193], v[206:209], v[52:55]
	v_mfma_f32_16x16x32_bf16 v[48:51], v[198:201], v[206:209], v[48:51]
	v_mfma_f32_16x16x32_bf16 v[36:39], v[190:193], v[214:217], v[36:39]
	v_mfma_f32_16x16x32_bf16 v[32:35], v[198:201], v[214:217], v[32:35]
	v_mfma_f32_16x16x32_bf16 v[20:23], v[190:193], v[222:225], v[20:23]
	v_mfma_f32_16x16x32_bf16 v[16:19], v[198:201], v[222:225], v[16:19]
	v_mfma_f32_16x16x32_bf16 v[4:7], v[190:193], v[230:233], v[4:7]
	v_mfma_f32_16x16x32_bf16 v[0:3], v[198:201], v[230:233], v[0:3]
	s_barrier
	s_setprio 0
	s_add_i32 s54, s54, 2
	s_add_u32 s68, s68, 0x10000
	s_addc_u32 s69, s69, 0
	s_add_u32 s31, s31, 0x10000
	s_addc_u32 s35, s35, 0
	s_cmp_gt_u32 s54, 61
	s_cbranch_scc1 .LBB0_923

; #define PG8_STAGE(bufoff, gbase, voff) do { _Pragma("unroll") for (int _i = 0; _i < 2; ++_i) \
;         __builtin_amdgcn_global_load_lds((const unsigned*)((const char*)(gbase) + (voff)[_i]), (LAS unsigned*)(lds + (bufoff) + ldsw + _i * 8192), 16, 0, 0); } while (0)
; #define PG8_LDA(dst, b, h) do { _Pragma("unroll") for (int m = 0; m < 4; ++m) _Pragma("unroll") for (int k = 0; k < 2; ++k) dst[m][k] = *(const LAS bf16x8*)(lds + PG8_SA(b, h) + aoff + m * 2048 + k * 1024); } while (0)
; #define PG8_LDB(dst, b, h) do { _Pragma("unroll") for (int n = 0; n < 2; ++n) _Pragma("unroll") for (int k = 0; k < 2; ++k) dst[n][k] = *(const LAS bf16x8*)(lds + PG8_SB(b, h) + boff + n * 2048 + k * 1024); } while (0)
; #define PG8_MMA(ai, bj, At, Bt) do { __builtin_amdgcn_s_setprio(1); _Pragma("unroll") for (int m = 0; m < 4; ++m) _Pragma("unroll") for (int n = 0; n < 2; ++n) _Pragma("unroll") for (int k = 0; k < 2; ++k) \
;         acc[ai][bj][m][n] = __builtin_amdgcn_mfma_f32_16x16x32_bf16(Bt[n][k], At[m][k], acc[ai][bj][m][n], 0, 0, 0); __builtin_amdgcn_s_setprio(0); } while (0)
; #define PG8_WAIT_V(n) asm volatile("s_waitcnt vmcnt(" #n ")" ::: "memory")
; #define PG8_WAIT_L(n) asm volatile("s_waitcnt lgkmcnt(" #n ")" ::: "memory")
; #define PG8_BAR __builtin_amdgcn_s_barrier()
; #define PG8_SCHED __builtin_amdgcn_sched_barrier(0)
; template <class Epi, class Sched, bool ALIGN_EPI>
; __device__ __forceinline__ void gemm_phase(LAS unsigned char* lds, const Gemm g, const Sched& S, const Epi& E, const int wid) {
;     ...
;             PG8_LDB(B0, 0, 0); PG8_LDB(B1, 0, 1); PG8_SCHED; PG8_LDA(At, 0, 0); PG8_STAGE(PG8_SA(1, 1), a1 + hstepA, voffA);
;             PG8_WAIT_V(8); PG8_WAIT_L(0); PG8_BAR; PG8_MMA(0, 0, At, B0); PG8_MMA(0, 1, At, B1); PG8_BAR; PG8_SCHED;
;             PG8_LDA(At, 0, 1); PG8_STAGE(PG8_SB(0, 0), b2, voffB); PG8_STAGE(PG8_SB(0, 1), b2 + hstepB, voffB); PG8_STAGE(PG8_SA(0, 0), a2, voffA);
;             PG8_WAIT_V(8); PG8_WAIT_L(0); PG8_BAR; PG8_MMA(1, 0, At, B0); PG8_MMA(1, 1, At, B1); PG8_BAR; PG8_SCHED;
.LBB0_1438:
	ds_read_b128 v[72:75], v202
	ds_read_b128 v[76:79], v202 offset:1024
	ds_read_b128 v[136:139], v202 offset:2048
	ds_read_b128 v[140:143], v202 offset:3072
	ds_read_b128 v[144:147], v203
	ds_read_b128 v[148:151], v203 offset:1024
	ds_read_b128 v[152:155], v203 offset:2048
	ds_read_b128 v[178:181], v203 offset:3072
	s_add_u32 s38, s20, 0xfff00080
	s_addc_u32 s39, s21, -1
	s_cmp_eq_u32 s55, 60
	s_cselect_b32 s71, s4, s39
	s_cselect_b32 s70, s5, s38
	s_cselect_b32 s69, s30, s54
	s_cselect_b32 s68, s31, s35
	s_add_i32 m0, s44, 0xc000
	ds_read_b128 v[182:185], v204
	ds_read_b128 v[186:189], v204 offset:1024
	ds_read_b128 v[190:193], v204 offset:2048
	ds_read_b128 v[194:197], v204 offset:3072
	ds_read_b128 v[208:211], v204 offset:4096
	ds_read_b128 v[212:215], v204 offset:5120
	ds_read_b128 v[216:219], v204 offset:6144
	ds_read_b128 v[220:223], v204 offset:7168
	global_load_lds_dwordx4 v168, s[20:21]
	s_add_i32 m0, s44, 0xe000
	s_nop 0
	global_load_lds_dwordx4 v170, s[20:21]
	s_waitcnt vmcnt(8)
	s_waitcnt lgkmcnt(0)
	s_setprio 1
	s_barrier
	v_mfma_f32_16x16x32_bf16 v[132:135], v[72:75], v[182:185], v[132:135]
	v_mfma_f32_16x16x32_bf16 v[128:131], v[136:139], v[182:185], v[128:131]
	v_mfma_f32_16x16x32_bf16 v[116:119], v[72:75], v[190:193], v[116:119]
	v_mfma_f32_16x16x32_bf16 v[112:115], v[136:139], v[190:193], v[112:115]
	v_mfma_f32_16x16x32_bf16 v[100:103], v[72:75], v[208:211], v[100:103]
	v_mfma_f32_16x16x32_bf16 v[96:99], v[136:139], v[208:211], v[96:99]
	v_mfma_f32_16x16x32_bf16 v[84:87], v[72:75], v[216:219], v[84:87]
	v_mfma_f32_16x16x32_bf16 v[80:83], v[136:139], v[216:219], v[80:83]
	v_mfma_f32_16x16x32_bf16 v[132:135], v[76:79], v[186:189], v[132:135]
	v_mfma_f32_16x16x32_bf16 v[128:131], v[140:143], v[186:189], v[128:131]
	v_mfma_f32_16x16x32_bf16 v[116:119], v[76:79], v[194:197], v[116:119]
	v_mfma_f32_16x16x32_bf16 v[112:115], v[140:143], v[194:197], v[112:115]
	v_mfma_f32_16x16x32_bf16 v[100:103], v[76:79], v[212:215], v[100:103]
	v_mfma_f32_16x16x32_bf16 v[96:99], v[140:143], v[212:215], v[96:99]
	v_mfma_f32_16x16x32_bf16 v[84:87], v[76:79], v[220:223], v[84:87]
	v_mfma_f32_16x16x32_bf16 v[80:83], v[140:143], v[220:223], v[80:83]
	s_setprio 0
	s_setprio 1
	v_mfma_f32_16x16x32_bf16 v[124:127], v[144:147], v[182:185], v[124:127]
	v_mfma_f32_16x16x32_bf16 v[120:123], v[152:155], v[182:185], v[120:123]
	v_mfma_f32_16x16x32_bf16 v[108:111], v[144:147], v[190:193], v[108:111]
	v_mfma_f32_16x16x32_bf16 v[104:107], v[152:155], v[190:193], v[104:107]
	v_mfma_f32_16x16x32_bf16 v[92:95], v[144:147], v[208:211], v[92:95]
	v_mfma_f32_16x16x32_bf16 v[88:91], v[152:155], v[208:211], v[88:91]
	v_mfma_f32_16x16x32_bf16 v[68:71], v[144:147], v[216:219], v[68:71]
	v_mfma_f32_16x16x32_bf16 v[64:67], v[152:155], v[216:219], v[64:67]
	v_mfma_f32_16x16x32_bf16 v[124:127], v[148:151], v[186:189], v[124:127]
	v_mfma_f32_16x16x32_bf16 v[120:123], v[178:181], v[186:189], v[120:123]
	v_mfma_f32_16x16x32_bf16 v[108:111], v[148:151], v[194:197], v[108:111]
	v_mfma_f32_16x16x32_bf16 v[104:107], v[178:181], v[194:197], v[104:107]
	v_mfma_f32_16x16x32_bf16 v[92:95], v[148:151], v[212:215], v[92:95]
	v_mfma_f32_16x16x32_bf16 v[88:91], v[178:181], v[212:215], v[88:91]
	v_mfma_f32_16x16x32_bf16 v[68:71], v[148:151], v[220:223], v[68:71]
	v_mfma_f32_16x16x32_bf16 v[64:67], v[178:181], v[220:223], v[64:67]
	s_barrier
	s_setprio 0
	s_add_i32 s38, s75, s3
	s_mov_b32 m0, s38
	ds_read_b128 v[182:185], v204 offset:16384
	ds_read_b128 v[186:189], v204 offset:17408
	ds_read_b128 v[190:193], v204 offset:18432
	ds_read_b128 v[194:197], v204 offset:19456
	ds_read_b128 v[208:211], v204 offset:20480
	ds_read_b128 v[212:215], v204 offset:21504
	ds_read_b128 v[216:219], v204 offset:22528
	ds_read_b128 v[220:223], v204 offset:23552
	global_load_lds_dwordx4 v158, s[68:69]
	s_add_i32 m0, s38, 0x2000
	s_add_u32 s38, s68, 0x1000
	s_addc_u32 s39, s69, 0
	s_add_i32 s57, s76, s3
	global_load_lds_dwordx4 v162, s[68:69]
	s_mov_b32 m0, s57
	v_lshl_add_u64 v[226:227], s[70:71], 0, v[160:161]
	global_load_lds_dwordx4 v158, s[38:39]
	s_add_i32 m0, s57, 0x2000
	s_nop 0
	global_load_lds_dwordx4 v162, s[38:39]
	v_lshl_add_u64 v[224:225], s[70:71], 0, v[156:157]
	s_mov_b32 m0, s44
	s_nop 0
	global_load_lds_dwordx4 v[224:225], off
	s_mov_b32 m0, s45
	s_nop 0
	global_load_lds_dwordx4 v[226:227], off
	s_waitcnt vmcnt(8)
	s_waitcnt lgkmcnt(0)
	s_setprio 1
	s_barrier
	v_mfma_f32_16x16x32_bf16 v[60:63], v[72:75], v[182:185], v[60:63]
	v_mfma_f32_16x16x32_bf16 v[56:59], v[136:139], v[182:185], v[56:59]
	v_mfma_f32_16x16x32_bf16 v[44:47], v[72:75], v[190:193], v[44:47]
	v_mfma_f32_16x16x32_bf16 v[40:43], v[136:139], v[190:193], v[40:43]
	v_mfma_f32_16x16x32_bf16 v[28:31], v[72:75], v[208:211], v[28:31]
	v_mfma_f32_16x16x32_bf16 v[24:27], v[136:139], v[208:211], v[24:27]
	v_mfma_f32_16x16x32_bf16 v[12:15], v[72:75], v[216:219], v[12:15]
	v_mfma_f32_16x16x32_bf16 v[8:11], v[136:139], v[216:219], v[8:11]
	v_mfma_f32_16x16x32_bf16 v[60:63], v[76:79], v[186:189], v[60:63]
	v_mfma_f32_16x16x32_bf16 v[56:59], v[140:143], v[186:189], v[56:59]
	v_mfma_f32_16x16x32_bf16 v[44:47], v[76:79], v[194:197], v[44:47]
	v_mfma_f32_16x16x32_bf16 v[40:43], v[140:143], v[194:197], v[40:43]
	v_mfma_f32_16x16x32_bf16 v[28:31], v[76:79], v[212:215], v[28:31]
	v_mfma_f32_16x16x32_bf16 v[24:27], v[140:143], v[212:215], v[24:27]
	v_mfma_f32_16x16x32_bf16 v[12:15], v[76:79], v[220:223], v[12:15]
	v_mfma_f32_16x16x32_bf16 v[8:11], v[140:143], v[220:223], v[8:11]
	s_setprio 0
	s_setprio 1
	v_mfma_f32_16x16x32_bf16 v[52:55], v[144:147], v[182:185], v[52:55]
	v_mfma_f32_16x16x32_bf16 v[48:51], v[152:155], v[182:185], v[48:51]
	v_mfma_f32_16x16x32_bf16 v[36:39], v[144:147], v[190:193], v[36:39]
	v_mfma_f32_16x16x32_bf16 v[32:35], v[152:155], v[190:193], v[32:35]
	v_mfma_f32_16x16x32_bf16 v[20:23], v[144:147], v[208:211], v[20:23]
	v_mfma_f32_16x16x32_bf16 v[16:19], v[152:155], v[208:211], v[16:19]
	v_mfma_f32_16x16x32_bf16 v[4:7], v[144:147], v[216:219], v[4:7]
	v_mfma_f32_16x16x32_bf16 v[0:3], v[152:155], v[216:219], v[0:3]
	v_mfma_f32_16x16x32_bf16 v[52:55], v[148:151], v[186:189], v[52:55]
	v_mfma_f32_16x16x32_bf16 v[48:51], v[178:181], v[186:189], v[48:51]
	v_mfma_f32_16x16x32_bf16 v[36:39], v[148:151], v[194:197], v[36:39]
	v_mfma_f32_16x16x32_bf16 v[32:35], v[178:181], v[194:197], v[32:35]
	v_mfma_f32_16x16x32_bf16 v[20:23], v[148:151], v[212:215], v[20:23]
	v_mfma_f32_16x16x32_bf16 v[16:19], v[178:181], v[212:215], v[16:19]
	v_mfma_f32_16x16x32_bf16 v[4:7], v[148:151], v[220:223], v[4:7]
	v_mfma_f32_16x16x32_bf16 v[0:3], v[178:181], v[220:223], v[0:3]
	s_barrier
; #define PG8_STAGE(bufoff, gbase, voff) do { _Pragma("unroll") for (int _i = 0; _i < 2; ++_i) \
;         __builtin_amdgcn_global_load_lds((const unsigned*)((const char*)(gbase) + (voff)[_i]), (LAS unsigned*)(lds + (bufoff) + ldsw + _i * 8192), 16, 0, 0); } while (0)
; #define PG8_LDA(dst, b, h) do { _Pragma("unroll") for (int m = 0; m < 4; ++m) _Pragma("unroll") for (int k = 0; k < 2; ++k) dst[m][k] = *(const LAS bf16x8*)(lds + PG8_SA(b, h) + aoff + m * 2048 + k * 1024); } while (0)
; #define PG8_LDB(dst, b, h) do { _Pragma("unroll") for (int n = 0; n < 2; ++n) _Pragma("unroll") for (int k = 0; k < 2; ++k) dst[n][k] = *(const LAS bf16x8*)(lds + PG8_SB(b, h) + boff + n * 2048 + k * 1024); } while (0)
; #define PG8_MMA(ai, bj, At, Bt) do { __builtin_amdgcn_s_setprio(1); _Pragma("unroll") for (int m = 0; m < 4; ++m) _Pragma("unroll") for (int n = 0; n < 2; ++n) _Pragma("unroll") for (int k = 0; k < 2; ++k) \
;         acc[ai][bj][m][n] = __builtin_amdgcn_mfma_f32_16x16x32_bf16(Bt[n][k], At[m][k], acc[ai][bj][m][n], 0, 0, 0); __builtin_amdgcn_s_setprio(0); } while (0)
; #define PG8_WAIT_V(n) asm volatile("s_waitcnt vmcnt(" #n ")" ::: "memory")
; #define PG8_WAIT_L(n) asm volatile("s_waitcnt lgkmcnt(" #n ")" ::: "memory")
; #define PG8_BAR __builtin_amdgcn_s_barrier()
; #define PG8_SCHED __builtin_amdgcn_sched_barrier(0)
; template <class Epi, class Sched, bool ALIGN_EPI>
; __device__ __forceinline__ void gemm_phase(LAS unsigned char* lds, const Gemm g, const Sched& S, const Epi& E, const int wid) {
;     ...
;             PG8_LDB(B0, 1, 0); PG8_LDB(B1, 1, 1); PG8_SCHED; PG8_LDA(At, 1, 0); PG8_STAGE(PG8_SA(0, 1), a2 + hstepA, voffA);
;             PG8_WAIT_V(8); PG8_WAIT_L(0); PG8_BAR; PG8_MMA(0, 0, At, B0); PG8_MMA(0, 1, At, B1); PG8_BAR; PG8_SCHED;
;             PG8_LDA(At, 1, 1); PG8_STAGE(PG8_SB(1, 0), b3, voffB); PG8_STAGE(PG8_SB(1, 1), b3 + hstepB, voffB); PG8_STAGE(PG8_SA(1, 0), a3, voffA);
;             PG8_WAIT_V(8); PG8_WAIT_L(0); PG8_BAR; PG8_MMA(1, 0, At, B0); PG8_MMA(1, 1, At, B1); PG8_BAR; PG8_SCHED;
;         }
;         if constexpr (ALIGN_EPI) { if (wr == 0) PG8_BAR; }
	s_setprio 0
	s_add_i32 s57, 0, 0x18000
	s_add_i32 s59, 0, 0x1c000
	v_add_u32_e32 v140, s57, v198
	v_add_u32_e32 v164, s59, v198
	ds_read_b128 v[72:75], v140
	ds_read_b128 v[76:79], v140 offset:1024
	ds_read_b128 v[136:139], v140 offset:2048
	ds_read_b128 v[140:143], v140 offset:3072
	ds_read_b128 v[144:147], v164
	ds_read_b128 v[148:151], v164 offset:1024
	ds_read_b128 v[152:155], v164 offset:2048
	ds_read_b128 v[178:181], v164 offset:3072
	s_add_u32 s38, s70, 0x100000
	s_addc_u32 s39, s71, 0
	s_mov_b32 m0, s46
	ds_read_b128 v[182:185], v204 offset:32768
	ds_read_b128 v[186:189], v204 offset:33792
	ds_read_b128 v[190:193], v204 offset:34816
	ds_read_b128 v[194:197], v204 offset:35840
	ds_read_b128 v[208:211], v204 offset:36864
	ds_read_b128 v[212:215], v204 offset:37888
	ds_read_b128 v[216:219], v204 offset:38912
	ds_read_b128 v[220:223], v204 offset:39936
	global_load_lds_dwordx4 v156, s[38:39]
	s_mov_b32 m0, s47
	s_nop 0
	global_load_lds_dwordx4 v160, s[38:39]
	s_waitcnt vmcnt(8)
	s_waitcnt lgkmcnt(0)
	s_setprio 1
	s_barrier
	v_mfma_f32_16x16x32_bf16 v[132:135], v[72:75], v[182:185], v[132:135]
	v_mfma_f32_16x16x32_bf16 v[128:131], v[136:139], v[182:185], v[128:131]
	v_mfma_f32_16x16x32_bf16 v[116:119], v[72:75], v[190:193], v[116:119]
	v_mfma_f32_16x16x32_bf16 v[112:115], v[136:139], v[190:193], v[112:115]
	v_mfma_f32_16x16x32_bf16 v[100:103], v[72:75], v[208:211], v[100:103]
	v_mfma_f32_16x16x32_bf16 v[96:99], v[136:139], v[208:211], v[96:99]
	v_mfma_f32_16x16x32_bf16 v[84:87], v[72:75], v[216:219], v[84:87]
	v_mfma_f32_16x16x32_bf16 v[80:83], v[136:139], v[216:219], v[80:83]
	v_mfma_f32_16x16x32_bf16 v[132:135], v[76:79], v[186:189], v[132:135]
	v_mfma_f32_16x16x32_bf16 v[128:131], v[140:143], v[186:189], v[128:131]
	v_mfma_f32_16x16x32_bf16 v[116:119], v[76:79], v[194:197], v[116:119]
	v_mfma_f32_16x16x32_bf16 v[112:115], v[140:143], v[194:197], v[112:115]
	v_mfma_f32_16x16x32_bf16 v[100:103], v[76:79], v[212:215], v[100:103]
	v_mfma_f32_16x16x32_bf16 v[96:99], v[140:143], v[212:215], v[96:99]
	v_mfma_f32_16x16x32_bf16 v[84:87], v[76:79], v[220:223], v[84:87]
	v_mfma_f32_16x16x32_bf16 v[80:83], v[140:143], v[220:223], v[80:83]
	s_setprio 0
	s_setprio 1
	v_mfma_f32_16x16x32_bf16 v[124:127], v[144:147], v[182:185], v[124:127]
	v_mfma_f32_16x16x32_bf16 v[120:123], v[152:155], v[182:185], v[120:123]
	v_mfma_f32_16x16x32_bf16 v[108:111], v[144:147], v[190:193], v[108:111]
	v_mfma_f32_16x16x32_bf16 v[104:107], v[152:155], v[190:193], v[104:107]
	v_mfma_f32_16x16x32_bf16 v[92:95], v[144:147], v[208:211], v[92:95]
	v_mfma_f32_16x16x32_bf16 v[88:91], v[152:155], v[208:211], v[88:91]
	v_mfma_f32_16x16x32_bf16 v[68:71], v[144:147], v[216:219], v[68:71]
	v_mfma_f32_16x16x32_bf16 v[64:67], v[152:155], v[216:219], v[64:67]
	v_mfma_f32_16x16x32_bf16 v[124:127], v[148:151], v[186:189], v[124:127]
	v_mfma_f32_16x16x32_bf16 v[120:123], v[178:181], v[186:189], v[120:123]
	v_mfma_f32_16x16x32_bf16 v[108:111], v[148:151], v[194:197], v[108:111]
	v_mfma_f32_16x16x32_bf16 v[104:107], v[178:181], v[194:197], v[104:107]
	v_mfma_f32_16x16x32_bf16 v[92:95], v[148:151], v[212:215], v[92:95]
	v_mfma_f32_16x16x32_bf16 v[88:91], v[178:181], v[212:215], v[88:91]
	v_mfma_f32_16x16x32_bf16 v[68:71], v[148:151], v[220:223], v[68:71]
	v_mfma_f32_16x16x32_bf16 v[64:67], v[178:181], v[220:223], v[64:67]
	s_barrier
	s_setprio 0
	s_add_u32 s38, s68, 0x8000
	s_addc_u32 s39, s69, 0
	s_add_i32 s57, s57, s3
	s_mov_b32 m0, s57
	ds_read_b128 v[182:185], v204 offset:49152
	ds_read_b128 v[186:189], v204 offset:50176
	ds_read_b128 v[190:193], v204 offset:51200
	ds_read_b128 v[194:197], v204 offset:52224
	ds_read_b128 v[208:211], v204 offset:53248
	ds_read_b128 v[212:215], v204 offset:54272
	ds_read_b128 v[216:219], v204 offset:55296
	ds_read_b128 v[220:223], v204 offset:56320
	global_load_lds_dwordx4 v158, s[38:39]
	s_add_i32 m0, s57, 0x2000
	s_nop 0
	global_load_lds_dwordx4 v162, s[38:39]
	s_add_u32 s38, s68, 0x9000
	s_addc_u32 s39, s69, 0
	s_add_i32 s57, s59, s3
	s_mov_b32 m0, s57
	v_lshl_add_u64 v[224:225], v[224:225], 0, s[48:49]
	global_load_lds_dwordx4 v158, s[38:39]
	s_add_i32 m0, s57, 0x2000
	s_nop 0
	global_load_lds_dwordx4 v162, s[38:39]
	s_mov_b32 m0, s72
	s_nop 0
	global_load_lds_dwordx4 v[224:225], off
	v_lshl_add_u64 v[224:225], v[226:227], 0, s[48:49]
	s_mov_b32 m0, s73
	s_nop 0
	global_load_lds_dwordx4 v[224:225], off
	s_waitcnt vmcnt(8)
	s_waitcnt lgkmcnt(0)
	s_setprio 1
	s_barrier
	v_mfma_f32_16x16x32_bf16 v[60:63], v[72:75], v[182:185], v[60:63]
	v_mfma_f32_16x16x32_bf16 v[56:59], v[136:139], v[182:185], v[56:59]
	v_mfma_f32_16x16x32_bf16 v[44:47], v[72:75], v[190:193], v[44:47]
	v_mfma_f32_16x16x32_bf16 v[40:43], v[136:139], v[190:193], v[40:43]
	v_mfma_f32_16x16x32_bf16 v[28:31], v[72:75], v[208:211], v[28:31]
	v_mfma_f32_16x16x32_bf16 v[24:27], v[136:139], v[208:211], v[24:27]
	v_mfma_f32_16x16x32_bf16 v[12:15], v[72:75], v[216:219], v[12:15]
	v_mfma_f32_16x16x32_bf16 v[8:11], v[136:139], v[216:219], v[8:11]
	v_mfma_f32_16x16x32_bf16 v[60:63], v[76:79], v[186:189], v[60:63]
	v_mfma_f32_16x16x32_bf16 v[56:59], v[140:143], v[186:189], v[56:59]
	v_mfma_f32_16x16x32_bf16 v[44:47], v[76:79], v[194:197], v[44:47]
	v_mfma_f32_16x16x32_bf16 v[40:43], v[140:143], v[194:197], v[40:43]
	v_mfma_f32_16x16x32_bf16 v[28:31], v[76:79], v[212:215], v[28:31]
	v_mfma_f32_16x16x32_bf16 v[24:27], v[140:143], v[212:215], v[24:27]
	v_mfma_f32_16x16x32_bf16 v[12:15], v[76:79], v[220:223], v[12:15]
	v_mfma_f32_16x16x32_bf16 v[8:11], v[140:143], v[220:223], v[8:11]
	s_setprio 0
	s_setprio 1
	v_mfma_f32_16x16x32_bf16 v[52:55], v[144:147], v[182:185], v[52:55]
	v_mfma_f32_16x16x32_bf16 v[48:51], v[152:155], v[182:185], v[48:51]
	v_mfma_f32_16x16x32_bf16 v[36:39], v[144:147], v[190:193], v[36:39]
	v_mfma_f32_16x16x32_bf16 v[32:35], v[152:155], v[190:193], v[32:35]
	v_mfma_f32_16x16x32_bf16 v[20:23], v[144:147], v[208:211], v[20:23]
	v_mfma_f32_16x16x32_bf16 v[16:19], v[152:155], v[208:211], v[16:19]
	v_mfma_f32_16x16x32_bf16 v[4:7], v[144:147], v[216:219], v[4:7]
	v_mfma_f32_16x16x32_bf16 v[0:3], v[152:155], v[216:219], v[0:3]
	v_mfma_f32_16x16x32_bf16 v[52:55], v[148:151], v[186:189], v[52:55]
	v_mfma_f32_16x16x32_bf16 v[48:51], v[178:181], v[186:189], v[48:51]
	v_mfma_f32_16x16x32_bf16 v[36:39], v[148:151], v[194:197], v[36:39]
	v_mfma_f32_16x16x32_bf16 v[32:35], v[178:181], v[194:197], v[32:35]
	v_mfma_f32_16x16x32_bf16 v[20:23], v[148:151], v[212:215], v[20:23]
	v_mfma_f32_16x16x32_bf16 v[16:19], v[178:181], v[212:215], v[16:19]
	v_mfma_f32_16x16x32_bf16 v[4:7], v[148:151], v[220:223], v[4:7]
	v_mfma_f32_16x16x32_bf16 v[0:3], v[178:181], v[220:223], v[0:3]
	s_barrier
	s_setprio 0
	s_add_i32 s55, s55, 2
	s_add_u32 s20, s20, 0x100
	s_addc_u32 s21, s21, 0
	s_add_u32 s35, s35, 0x10000
	s_addc_u32 s54, s54, 0
	s_cmp_gt_u32 s55, 61
	s_cbranch_scc0 .LBB0_1438
	s_and_b64 vcc, exec, s[28:29]
	s_cbranch_vccz .LBB0_1441
	s_barrier

; #define PG8_STAGE(bufoff, gbase, voff) do { _Pragma("unroll") for (int _i = 0; _i < 2; ++_i) \
;         __builtin_amdgcn_global_load_lds((const unsigned*)((const char*)(gbase) + (voff)[_i]), (LAS unsigned*)(lds + (bufoff) + ldsw + _i * 8192), 16, 0, 0); } while (0)
; #define PG8_LDA(dst, b, h) do { _Pragma("unroll") for (int m = 0; m < 4; ++m) _Pragma("unroll") for (int k = 0; k < 2; ++k) dst[m][k] = *(const LAS bf16x8*)(lds + PG8_SA(b, h) + aoff + m * 2048 + k * 1024); } while (0)
; #define PG8_LDB(dst, b, h) do { _Pragma("unroll") for (int n = 0; n < 2; ++n) _Pragma("unroll") for (int k = 0; k < 2; ++k) dst[n][k] = *(const LAS bf16x8*)(lds + PG8_SB(b, h) + boff + n * 2048 + k * 1024); } while (0)
; #define PG8_MMA(ai, bj, At, Bt) do { __builtin_amdgcn_s_setprio(1); _Pragma("unroll") for (int m = 0; m < 4; ++m) _Pragma("unroll") for (int n = 0; n < 2; ++n) _Pragma("unroll") for (int k = 0; k < 2; ++k) \
;         acc[ai][bj][m][n] = __builtin_amdgcn_mfma_f32_16x16x32_bf16(Bt[n][k], At[m][k], acc[ai][bj][m][n], 0, 0, 0); __builtin_amdgcn_s_setprio(0); } while (0)
; #define PG8_WAIT_V(n) asm volatile("s_waitcnt vmcnt(" #n ")" ::: "memory")
; #define PG8_WAIT_L(n) asm volatile("s_waitcnt lgkmcnt(" #n ")" ::: "memory")
; #define PG8_BAR __builtin_amdgcn_s_barrier()
; #define PG8_SCHED __builtin_amdgcn_sched_barrier(0)
; template <class Epi, class Sched, bool ALIGN_EPI>
; __device__ __forceinline__ void gemm_phase(LAS unsigned char* lds, const Gemm g, const Sched& S, const Epi& E, const int wid) {
;     ...
;             PG8_LDB(B0, 0, 0); PG8_LDB(B1, 0, 1); PG8_SCHED; PG8_LDA(At, 0, 0); PG8_STAGE(PG8_SA(1, 1), a1 + hstepA, voffA);
;             PG8_WAIT_V(8); PG8_WAIT_L(0); PG8_BAR; PG8_MMA(0, 0, At, B0); PG8_MMA(0, 1, At, B1); PG8_BAR; PG8_SCHED;
;             PG8_LDA(At, 0, 1); PG8_STAGE(PG8_SB(0, 0), b2, voffB); PG8_STAGE(PG8_SB(0, 1), b2 + hstepB, voffB); PG8_STAGE(PG8_SA(0, 0), a2, voffA);
;             PG8_WAIT_V(8); PG8_WAIT_L(0); PG8_BAR; PG8_MMA(1, 0, At, B0); PG8_MMA(1, 1, At, B1); PG8_BAR; PG8_SCHED;
.LBB0_1568:
	v_add_u32_e32 v138, s63, v160
	ds_read_b128 v[130:133], v138
	ds_read_b128 v[134:137], v138 offset:1024
	ds_read_b128 v[170:173], v138 offset:2048
	ds_read_b128 v[174:177], v138 offset:3072
	v_add_u32_e32 v138, s64, v160
	s_add_u32 s56, s16, 0x4000
	ds_read_b128 v[178:181], v138
	ds_read_b128 v[182:185], v138 offset:1024
	ds_read_b128 v[186:189], v138 offset:2048
	ds_read_b128 v[190:193], v138 offset:3072
	s_addc_u32 s57, s17, 0
	s_and_b64 s[38:39], s[58:59], exec
	s_cselect_b32 s60, s35, s56
	s_cselect_b32 s61, s27, s57
	s_add_u32 s56, s60, 0x8000
	s_addc_u32 s57, s61, 0
	s_and_b64 s[38:39], s[58:59], exec
	s_cselect_b32 s59, s25, s69
	s_cselect_b32 s58, s53, s68
	s_add_i32 m0, s31, 0xc000
	ds_read_b128 v[194:197], v166
	ds_read_b128 v[198:201], v166 offset:1024
	ds_read_b128 v[202:205], v166 offset:2048
	ds_read_b128 v[206:209], v166 offset:3072
	ds_read_b128 v[210:213], v166 offset:4096
	ds_read_b128 v[214:217], v166 offset:5120
	ds_read_b128 v[218:221], v166 offset:6144
	ds_read_b128 v[222:225], v166 offset:7168
	global_load_lds_dwordx4 v150, s[16:17]
	s_add_i32 m0, s31, 0xe000
	s_nop 0
	global_load_lds_dwordx4 v152, s[16:17]
	s_waitcnt vmcnt(8)
	s_waitcnt lgkmcnt(0)
	s_setprio 1
	s_barrier
	v_mfma_f32_16x16x32_bf16 v[124:127], v[130:133], v[194:197], v[124:127]
	v_mfma_f32_16x16x32_bf16 v[120:123], v[170:173], v[194:197], v[120:123]
	v_mfma_f32_16x16x32_bf16 v[108:111], v[130:133], v[202:205], v[108:111]
	v_mfma_f32_16x16x32_bf16 v[104:107], v[170:173], v[202:205], v[104:107]
	v_mfma_f32_16x16x32_bf16 v[92:95], v[130:133], v[210:213], v[92:95]
	v_mfma_f32_16x16x32_bf16 v[88:91], v[170:173], v[210:213], v[88:91]
	v_mfma_f32_16x16x32_bf16 v[76:79], v[130:133], v[218:221], v[76:79]
	v_mfma_f32_16x16x32_bf16 v[72:75], v[170:173], v[218:221], v[72:75]
	v_mfma_f32_16x16x32_bf16 v[124:127], v[134:137], v[198:201], v[124:127]
	v_mfma_f32_16x16x32_bf16 v[120:123], v[174:177], v[198:201], v[120:123]
	v_mfma_f32_16x16x32_bf16 v[108:111], v[134:137], v[206:209], v[108:111]
	v_mfma_f32_16x16x32_bf16 v[104:107], v[174:177], v[206:209], v[104:107]
	v_mfma_f32_16x16x32_bf16 v[92:95], v[134:137], v[214:217], v[92:95]
	v_mfma_f32_16x16x32_bf16 v[88:91], v[174:177], v[214:217], v[88:91]
	v_mfma_f32_16x16x32_bf16 v[76:79], v[134:137], v[222:225], v[76:79]
	v_mfma_f32_16x16x32_bf16 v[72:75], v[174:177], v[222:225], v[72:75]
	s_setprio 0
	s_setprio 1
	v_mfma_f32_16x16x32_bf16 v[116:119], v[178:181], v[194:197], v[116:119]
	v_mfma_f32_16x16x32_bf16 v[112:115], v[186:189], v[194:197], v[112:115]
	v_mfma_f32_16x16x32_bf16 v[100:103], v[178:181], v[202:205], v[100:103]
	v_mfma_f32_16x16x32_bf16 v[96:99], v[186:189], v[202:205], v[96:99]
	v_mfma_f32_16x16x32_bf16 v[84:87], v[178:181], v[210:213], v[84:87]
	v_mfma_f32_16x16x32_bf16 v[80:83], v[186:189], v[210:213], v[80:83]
	v_mfma_f32_16x16x32_bf16 v[68:71], v[178:181], v[218:221], v[68:71]
	v_mfma_f32_16x16x32_bf16 v[64:67], v[186:189], v[218:221], v[64:67]
	v_mfma_f32_16x16x32_bf16 v[116:119], v[182:185], v[198:201], v[116:119]
	v_mfma_f32_16x16x32_bf16 v[112:115], v[190:193], v[198:201], v[112:115]
	v_mfma_f32_16x16x32_bf16 v[100:103], v[182:185], v[206:209], v[100:103]
	v_mfma_f32_16x16x32_bf16 v[96:99], v[190:193], v[206:209], v[96:99]
	v_mfma_f32_16x16x32_bf16 v[84:87], v[182:185], v[214:217], v[84:87]
	v_mfma_f32_16x16x32_bf16 v[80:83], v[190:193], v[214:217], v[80:83]
	v_mfma_f32_16x16x32_bf16 v[68:71], v[182:185], v[222:225], v[68:71]
	v_mfma_f32_16x16x32_bf16 v[64:67], v[190:193], v[222:225], v[64:67]
	s_barrier
	s_setprio 0
	s_add_i32 s38, s63, s3
	s_mov_b32 m0, s38
	ds_read_b128 v[194:197], v166 offset:16384
	ds_read_b128 v[198:201], v166 offset:17408
	ds_read_b128 v[202:205], v166 offset:18432
	ds_read_b128 v[206:209], v166 offset:19456
	ds_read_b128 v[210:213], v166 offset:20480
	ds_read_b128 v[214:217], v166 offset:21504
	ds_read_b128 v[218:221], v166 offset:22528
	ds_read_b128 v[222:225], v166 offset:23552
	global_load_lds_dwordx4 v144, s[58:59]
	s_add_i32 m0, s38, 0x2000
	s_add_u32 s38, s58, 0x1000
	s_addc_u32 s39, s59, 0
	s_add_i32 s71, s64, s3
	global_load_lds_dwordx4 v140, s[58:59]
	s_mov_b32 m0, s71
	s_nop 0
	global_load_lds_dwordx4 v144, s[38:39]
	s_add_i32 m0, s71, 0x2000
	s_nop 0
	global_load_lds_dwordx4 v140, s[38:39]
	s_mov_b32 m0, s31
	s_nop 0
	global_load_lds_dwordx4 v146, s[60:61]
	s_mov_b32 m0, s42
	s_nop 0
	global_load_lds_dwordx4 v142, s[60:61]
	s_waitcnt vmcnt(8)
	s_waitcnt lgkmcnt(0)
	s_setprio 1
	s_barrier
	v_mfma_f32_16x16x32_bf16 v[60:63], v[130:133], v[194:197], v[60:63]
	v_mfma_f32_16x16x32_bf16 v[56:59], v[170:173], v[194:197], v[56:59]
	v_mfma_f32_16x16x32_bf16 v[44:47], v[130:133], v[202:205], v[44:47]
	v_mfma_f32_16x16x32_bf16 v[40:43], v[170:173], v[202:205], v[40:43]
	v_mfma_f32_16x16x32_bf16 v[28:31], v[130:133], v[210:213], v[28:31]
	v_mfma_f32_16x16x32_bf16 v[24:27], v[170:173], v[210:213], v[24:27]
	v_mfma_f32_16x16x32_bf16 v[12:15], v[130:133], v[218:221], v[12:15]
	v_mfma_f32_16x16x32_bf16 v[8:11], v[170:173], v[218:221], v[8:11]
	v_mfma_f32_16x16x32_bf16 v[60:63], v[134:137], v[198:201], v[60:63]
	v_mfma_f32_16x16x32_bf16 v[56:59], v[174:177], v[198:201], v[56:59]
	v_mfma_f32_16x16x32_bf16 v[44:47], v[134:137], v[206:209], v[44:47]
	v_mfma_f32_16x16x32_bf16 v[40:43], v[174:177], v[206:209], v[40:43]
	v_mfma_f32_16x16x32_bf16 v[28:31], v[134:137], v[214:217], v[28:31]
	v_mfma_f32_16x16x32_bf16 v[24:27], v[174:177], v[214:217], v[24:27]
	v_mfma_f32_16x16x32_bf16 v[12:15], v[134:137], v[222:225], v[12:15]
	v_mfma_f32_16x16x32_bf16 v[8:11], v[174:177], v[222:225], v[8:11]
	s_setprio 0
	s_setprio 1
	v_mfma_f32_16x16x32_bf16 v[52:55], v[178:181], v[194:197], v[52:55]
	v_mfma_f32_16x16x32_bf16 v[48:51], v[186:189], v[194:197], v[48:51]
	v_mfma_f32_16x16x32_bf16 v[36:39], v[178:181], v[202:205], v[36:39]
	v_mfma_f32_16x16x32_bf16 v[32:35], v[186:189], v[202:205], v[32:35]
	v_mfma_f32_16x16x32_bf16 v[20:23], v[178:181], v[210:213], v[20:23]
	v_mfma_f32_16x16x32_bf16 v[16:19], v[186:189], v[210:213], v[16:19]
	v_mfma_f32_16x16x32_bf16 v[4:7], v[178:181], v[218:221], v[4:7]
	v_mfma_f32_16x16x32_bf16 v[0:3], v[186:189], v[218:221], v[0:3]
	v_mfma_f32_16x16x32_bf16 v[52:55], v[182:185], v[198:201], v[52:55]
	v_mfma_f32_16x16x32_bf16 v[48:51], v[190:193], v[198:201], v[48:51]
	v_mfma_f32_16x16x32_bf16 v[36:39], v[182:185], v[206:209], v[36:39]
	v_mfma_f32_16x16x32_bf16 v[32:35], v[190:193], v[206:209], v[32:35]
	v_mfma_f32_16x16x32_bf16 v[20:23], v[182:185], v[214:217], v[20:23]
	v_mfma_f32_16x16x32_bf16 v[16:19], v[190:193], v[214:217], v[16:19]
	v_mfma_f32_16x16x32_bf16 v[4:7], v[182:185], v[222:225], v[4:7]
	v_mfma_f32_16x16x32_bf16 v[0:3], v[190:193], v[222:225], v[0:3]
	s_barrier
; #define PG8_STAGE(bufoff, gbase, voff) do { _Pragma("unroll") for (int _i = 0; _i < 2; ++_i) \
;         __builtin_amdgcn_global_load_lds((const unsigned*)((const char*)(gbase) + (voff)[_i]), (LAS unsigned*)(lds + (bufoff) + ldsw + _i * 8192), 16, 0, 0); } while (0)
; #define PG8_LDA(dst, b, h) do { _Pragma("unroll") for (int m = 0; m < 4; ++m) _Pragma("unroll") for (int k = 0; k < 2; ++k) dst[m][k] = *(const LAS bf16x8*)(lds + PG8_SA(b, h) + aoff + m * 2048 + k * 1024); } while (0)
; #define PG8_LDB(dst, b, h) do { _Pragma("unroll") for (int n = 0; n < 2; ++n) _Pragma("unroll") for (int k = 0; k < 2; ++k) dst[n][k] = *(const LAS bf16x8*)(lds + PG8_SB(b, h) + boff + n * 2048 + k * 1024); } while (0)
; #define PG8_MMA(ai, bj, At, Bt) do { __builtin_amdgcn_s_setprio(1); _Pragma("unroll") for (int m = 0; m < 4; ++m) _Pragma("unroll") for (int n = 0; n < 2; ++n) _Pragma("unroll") for (int k = 0; k < 2; ++k) \
;         acc[ai][bj][m][n] = __builtin_amdgcn_mfma_f32_16x16x32_bf16(Bt[n][k], At[m][k], acc[ai][bj][m][n], 0, 0, 0); __builtin_amdgcn_s_setprio(0); } while (0)
; #define PG8_WAIT_V(n) asm volatile("s_waitcnt vmcnt(" #n ")" ::: "memory")
; #define PG8_WAIT_L(n) asm volatile("s_waitcnt lgkmcnt(" #n ")" ::: "memory")
; #define PG8_BAR __builtin_amdgcn_s_barrier()
; #define PG8_SCHED __builtin_amdgcn_sched_barrier(0)
; template <class Epi, class Sched, bool ALIGN_EPI>
; __device__ __forceinline__ void gemm_phase(LAS unsigned char* lds, const Gemm g, const Sched& S, const Epi& E, const int wid) {
;     ...
;             PG8_LDB(B0, 1, 0); PG8_LDB(B1, 1, 1); PG8_SCHED; PG8_LDA(At, 1, 0); PG8_STAGE(PG8_SA(0, 1), a2 + hstepA, voffA);
;             PG8_WAIT_V(8); PG8_WAIT_L(0); PG8_BAR; PG8_MMA(0, 0, At, B0); PG8_MMA(0, 1, At, B1); PG8_BAR; PG8_SCHED;
;             PG8_LDA(At, 1, 1); PG8_STAGE(PG8_SB(1, 0), b3, voffB); PG8_STAGE(PG8_SB(1, 1), b3 + hstepB, voffB); PG8_STAGE(PG8_SA(1, 0), a3, voffA);
;             PG8_WAIT_V(8); PG8_WAIT_L(0); PG8_BAR; PG8_MMA(1, 0, At, B0); PG8_MMA(1, 1, At, B1); PG8_BAR; PG8_SCHED;
;         }
;         if constexpr (ALIGN_EPI) { if (wr == 0) PG8_BAR; }
	s_setprio 0
	s_add_i32 s71, 0, 0x18000
	v_add_u32_e32 v138, s71, v160
	s_add_i32 s72, 0, 0x1c000
	ds_read_b128 v[130:133], v138
	ds_read_b128 v[134:137], v138 offset:1024
	ds_read_b128 v[170:173], v138 offset:2048
	ds_read_b128 v[174:177], v138 offset:3072
	v_add_u32_e32 v138, s72, v160
	ds_read_b128 v[178:181], v138
	ds_read_b128 v[182:185], v138 offset:1024
	ds_read_b128 v[186:189], v138 offset:2048
	ds_read_b128 v[190:193], v138 offset:3072
	s_add_u32 s38, s60, 0x4000
	s_addc_u32 s39, s61, 0
	s_mov_b32 m0, s43
	ds_read_b128 v[194:197], v166 offset:32768
	ds_read_b128 v[198:201], v166 offset:33792
	ds_read_b128 v[202:205], v166 offset:34816
	ds_read_b128 v[206:209], v166 offset:35840
	ds_read_b128 v[210:213], v166 offset:36864
	ds_read_b128 v[214:217], v166 offset:37888
	ds_read_b128 v[218:221], v166 offset:38912
	ds_read_b128 v[222:225], v166 offset:39936
	global_load_lds_dwordx4 v146, s[38:39]
	s_mov_b32 m0, s44
	s_nop 0
	global_load_lds_dwordx4 v142, s[38:39]
	s_waitcnt vmcnt(8)
	s_waitcnt lgkmcnt(0)
	s_setprio 1
	s_barrier
	v_mfma_f32_16x16x32_bf16 v[124:127], v[130:133], v[194:197], v[124:127]
	v_mfma_f32_16x16x32_bf16 v[120:123], v[170:173], v[194:197], v[120:123]
	v_mfma_f32_16x16x32_bf16 v[108:111], v[130:133], v[202:205], v[108:111]
	v_mfma_f32_16x16x32_bf16 v[104:107], v[170:173], v[202:205], v[104:107]
	v_mfma_f32_16x16x32_bf16 v[92:95], v[130:133], v[210:213], v[92:95]
	v_mfma_f32_16x16x32_bf16 v[88:91], v[170:173], v[210:213], v[88:91]
	v_mfma_f32_16x16x32_bf16 v[76:79], v[130:133], v[218:221], v[76:79]
	v_mfma_f32_16x16x32_bf16 v[72:75], v[170:173], v[218:221], v[72:75]
	v_mfma_f32_16x16x32_bf16 v[124:127], v[134:137], v[198:201], v[124:127]
	v_mfma_f32_16x16x32_bf16 v[120:123], v[174:177], v[198:201], v[120:123]
	v_mfma_f32_16x16x32_bf16 v[108:111], v[134:137], v[206:209], v[108:111]
	v_mfma_f32_16x16x32_bf16 v[104:107], v[174:177], v[206:209], v[104:107]
	v_mfma_f32_16x16x32_bf16 v[92:95], v[134:137], v[214:217], v[92:95]
	v_mfma_f32_16x16x32_bf16 v[88:91], v[174:177], v[214:217], v[88:91]
	v_mfma_f32_16x16x32_bf16 v[76:79], v[134:137], v[222:225], v[76:79]
	v_mfma_f32_16x16x32_bf16 v[72:75], v[174:177], v[222:225], v[72:75]
	s_setprio 0
	s_setprio 1
	v_mfma_f32_16x16x32_bf16 v[116:119], v[178:181], v[194:197], v[116:119]
	v_mfma_f32_16x16x32_bf16 v[112:115], v[186:189], v[194:197], v[112:115]
	v_mfma_f32_16x16x32_bf16 v[100:103], v[178:181], v[202:205], v[100:103]
	v_mfma_f32_16x16x32_bf16 v[96:99], v[186:189], v[202:205], v[96:99]
	v_mfma_f32_16x16x32_bf16 v[84:87], v[178:181], v[210:213], v[84:87]
	v_mfma_f32_16x16x32_bf16 v[80:83], v[186:189], v[210:213], v[80:83]
	v_mfma_f32_16x16x32_bf16 v[68:71], v[178:181], v[218:221], v[68:71]
	v_mfma_f32_16x16x32_bf16 v[64:67], v[186:189], v[218:221], v[64:67]
	v_mfma_f32_16x16x32_bf16 v[116:119], v[182:185], v[198:201], v[116:119]
	v_mfma_f32_16x16x32_bf16 v[112:115], v[190:193], v[198:201], v[112:115]
	v_mfma_f32_16x16x32_bf16 v[100:103], v[182:185], v[206:209], v[100:103]
	v_mfma_f32_16x16x32_bf16 v[96:99], v[190:193], v[206:209], v[96:99]
	v_mfma_f32_16x16x32_bf16 v[84:87], v[182:185], v[214:217], v[84:87]
	v_mfma_f32_16x16x32_bf16 v[80:83], v[190:193], v[214:217], v[80:83]
	v_mfma_f32_16x16x32_bf16 v[68:71], v[182:185], v[222:225], v[68:71]
	v_mfma_f32_16x16x32_bf16 v[64:67], v[190:193], v[222:225], v[64:67]
	s_barrier
	s_setprio 0
	s_add_u32 s38, s58, 0x8000
	s_addc_u32 s39, s59, 0
	s_add_i32 s60, s71, s3
	s_mov_b32 m0, s60
	ds_read_b128 v[194:197], v166 offset:49152
	ds_read_b128 v[198:201], v166 offset:50176
	ds_read_b128 v[202:205], v166 offset:51200
	ds_read_b128 v[206:209], v166 offset:52224
	ds_read_b128 v[210:213], v166 offset:53248
	ds_read_b128 v[214:217], v166 offset:54272
	ds_read_b128 v[218:221], v166 offset:55296
	ds_read_b128 v[222:225], v166 offset:56320
	global_load_lds_dwordx4 v144, s[38:39]
	s_add_i32 m0, s60, 0x2000
	s_nop 0
	global_load_lds_dwordx4 v140, s[38:39]
	s_add_u32 s38, s58, 0x9000
	s_addc_u32 s39, s59, 0
	s_add_i32 s58, s72, s3
	s_mov_b32 m0, s58
	s_nop 0
	global_load_lds_dwordx4 v144, s[38:39]
	s_add_i32 m0, s58, 0x2000
	s_nop 0
	global_load_lds_dwordx4 v140, s[38:39]
	s_mov_b32 m0, s54
	s_nop 0
	global_load_lds_dwordx4 v146, s[56:57]
	s_mov_b32 m0, s55
	s_nop 0
	global_load_lds_dwordx4 v142, s[56:57]
	s_waitcnt vmcnt(8)
	s_waitcnt lgkmcnt(0)
	s_setprio 1
	s_barrier
	v_mfma_f32_16x16x32_bf16 v[60:63], v[130:133], v[194:197], v[60:63]
	v_mfma_f32_16x16x32_bf16 v[56:59], v[170:173], v[194:197], v[56:59]
	v_mfma_f32_16x16x32_bf16 v[44:47], v[130:133], v[202:205], v[44:47]
	v_mfma_f32_16x16x32_bf16 v[40:43], v[170:173], v[202:205], v[40:43]
	v_mfma_f32_16x16x32_bf16 v[28:31], v[130:133], v[210:213], v[28:31]
	v_mfma_f32_16x16x32_bf16 v[24:27], v[170:173], v[210:213], v[24:27]
	v_mfma_f32_16x16x32_bf16 v[12:15], v[130:133], v[218:221], v[12:15]
	v_mfma_f32_16x16x32_bf16 v[8:11], v[170:173], v[218:221], v[8:11]
	v_mfma_f32_16x16x32_bf16 v[60:63], v[134:137], v[198:201], v[60:63]
	v_mfma_f32_16x16x32_bf16 v[56:59], v[174:177], v[198:201], v[56:59]
	v_mfma_f32_16x16x32_bf16 v[44:47], v[134:137], v[206:209], v[44:47]
	v_mfma_f32_16x16x32_bf16 v[40:43], v[174:177], v[206:209], v[40:43]
	v_mfma_f32_16x16x32_bf16 v[28:31], v[134:137], v[214:217], v[28:31]
	v_mfma_f32_16x16x32_bf16 v[24:27], v[174:177], v[214:217], v[24:27]
	v_mfma_f32_16x16x32_bf16 v[12:15], v[134:137], v[222:225], v[12:15]
	v_mfma_f32_16x16x32_bf16 v[8:11], v[174:177], v[222:225], v[8:11]
	s_setprio 0
	s_setprio 1
	v_mfma_f32_16x16x32_bf16 v[52:55], v[178:181], v[194:197], v[52:55]
	v_mfma_f32_16x16x32_bf16 v[48:51], v[186:189], v[194:197], v[48:51]
	v_mfma_f32_16x16x32_bf16 v[36:39], v[178:181], v[202:205], v[36:39]
	v_mfma_f32_16x16x32_bf16 v[32:35], v[186:189], v[202:205], v[32:35]
	v_mfma_f32_16x16x32_bf16 v[20:23], v[178:181], v[210:213], v[20:23]
	v_mfma_f32_16x16x32_bf16 v[16:19], v[186:189], v[210:213], v[16:19]
	v_mfma_f32_16x16x32_bf16 v[4:7], v[178:181], v[218:221], v[4:7]
	v_mfma_f32_16x16x32_bf16 v[0:3], v[186:189], v[218:221], v[0:3]
	v_mfma_f32_16x16x32_bf16 v[52:55], v[182:185], v[198:201], v[52:55]
	v_mfma_f32_16x16x32_bf16 v[48:51], v[190:193], v[198:201], v[48:51]
	v_mfma_f32_16x16x32_bf16 v[36:39], v[182:185], v[206:209], v[36:39]
	v_mfma_f32_16x16x32_bf16 v[32:35], v[190:193], v[206:209], v[32:35]
	v_mfma_f32_16x16x32_bf16 v[20:23], v[182:185], v[214:217], v[20:23]
	v_mfma_f32_16x16x32_bf16 v[16:19], v[190:193], v[214:217], v[16:19]
	v_mfma_f32_16x16x32_bf16 v[4:7], v[182:185], v[222:225], v[4:7]
	v_mfma_f32_16x16x32_bf16 v[0:3], v[190:193], v[222:225], v[0:3]
	s_barrier
	s_setprio 0
	s_add_i32 s70, s70, 2
	s_add_u32 s16, s16, 0x10000
	s_addc_u32 s17, s17, 0
	s_add_u32 s68, s68, 0x10000
	s_addc_u32 s69, s69, 0
	s_cmp_gt_u32 s70, 61
	s_cbranch_scc1 .LBB0_1571

; #define PG8_STAGE(bufoff, gbase, voff) do { _Pragma("unroll") for (int _i = 0; _i < 2; ++_i) \
;         __builtin_amdgcn_global_load_lds((const unsigned*)((const char*)(gbase) + (voff)[_i]), (LAS unsigned*)(lds + (bufoff) + ldsw + _i * 8192), 16, 0, 0); } while (0)
; #define PG8_LDA(dst, b, h) do { _Pragma("unroll") for (int m = 0; m < 4; ++m) _Pragma("unroll") for (int k = 0; k < 2; ++k) dst[m][k] = *(const LAS bf16x8*)(lds + PG8_SA(b, h) + aoff + m * 2048 + k * 1024); } while (0)
; #define PG8_LDB(dst, b, h) do { _Pragma("unroll") for (int n = 0; n < 2; ++n) _Pragma("unroll") for (int k = 0; k < 2; ++k) dst[n][k] = *(const LAS bf16x8*)(lds + PG8_SB(b, h) + boff + n * 2048 + k * 1024); } while (0)
; #define PG8_MMA(ai, bj, At, Bt) do { __builtin_amdgcn_s_setprio(1); _Pragma("unroll") for (int m = 0; m < 4; ++m) _Pragma("unroll") for (int n = 0; n < 2; ++n) _Pragma("unroll") for (int k = 0; k < 2; ++k) \
;         acc[ai][bj][m][n] = __builtin_amdgcn_mfma_f32_16x16x32_bf16(Bt[n][k], At[m][k], acc[ai][bj][m][n], 0, 0, 0); __builtin_amdgcn_s_setprio(0); } while (0)
; #define PG8_WAIT_V(n) asm volatile("s_waitcnt vmcnt(" #n ")" ::: "memory")
; #define PG8_WAIT_L(n) asm volatile("s_waitcnt lgkmcnt(" #n ")" ::: "memory")
; #define PG8_BAR __builtin_amdgcn_s_barrier()
; #define PG8_SCHED __builtin_amdgcn_sched_barrier(0)
; template <class Epi, class Sched, bool ALIGN_EPI>
; __device__ __forceinline__ void gemm_phase(LAS unsigned char* lds, const Gemm g, const Sched& S, const Epi& E, const int wid) {
;     ...
;             PG8_LDB(B0, 0, 0); PG8_LDB(B1, 0, 1); PG8_SCHED; PG8_LDA(At, 0, 0); PG8_STAGE(PG8_SA(1, 1), a1 + hstepA, voffA);
;             PG8_WAIT_V(8); PG8_WAIT_L(0); PG8_BAR; PG8_MMA(0, 0, At, B0); PG8_MMA(0, 1, At, B1); PG8_BAR; PG8_SCHED;
;             PG8_LDA(At, 0, 1); PG8_STAGE(PG8_SB(0, 0), b2, voffB); PG8_STAGE(PG8_SB(0, 1), b2 + hstepB, voffB); PG8_STAGE(PG8_SA(0, 0), a2, voffA);
;             PG8_WAIT_V(8); PG8_WAIT_L(0); PG8_BAR; PG8_MMA(1, 0, At, B0); PG8_MMA(1, 1, At, B1); PG8_BAR; PG8_SCHED;
.LBB0_1672:
	ds_read_b128 v[72:75], v202
	ds_read_b128 v[76:79], v202 offset:1024
	ds_read_b128 v[136:139], v202 offset:2048
	ds_read_b128 v[140:143], v202 offset:3072
	ds_read_b128 v[144:147], v203
	ds_read_b128 v[148:151], v203 offset:1024
	ds_read_b128 v[152:155], v203 offset:2048
	ds_read_b128 v[178:181], v203 offset:3072
	s_add_u32 s38, s16, 0x4000
	s_addc_u32 s60, s17, 0
	s_cmpk_eq_i32 s78, 0xfc
	s_cselect_b32 s64, s51, s38
	s_cselect_b32 s65, s35, s60
	s_cselect_b32 s62, s57, s59
	s_cselect_b32 s63, s49, s77
	s_add_u32 s60, s64, 0x8000
	s_addc_u32 s61, s65, 0
	s_add_i32 m0, s45, 0xc000
	ds_read_b128 v[182:185], v204
	ds_read_b128 v[186:189], v204 offset:1024
	ds_read_b128 v[190:193], v204 offset:2048
	ds_read_b128 v[194:197], v204 offset:3072
	ds_read_b128 v[208:211], v204 offset:4096
	ds_read_b128 v[212:215], v204 offset:5120
	ds_read_b128 v[216:219], v204 offset:6144
	ds_read_b128 v[220:223], v204 offset:7168
	global_load_lds_dwordx4 v168, s[16:17]
	s_add_i32 m0, s45, 0xe000
	s_nop 0
	global_load_lds_dwordx4 v170, s[16:17]
	s_waitcnt vmcnt(8)
	s_waitcnt lgkmcnt(0)
	s_setprio 1
	s_barrier
	v_mfma_f32_16x16x32_bf16 v[132:135], v[72:75], v[182:185], v[132:135]
	v_mfma_f32_16x16x32_bf16 v[128:131], v[136:139], v[182:185], v[128:131]
	v_mfma_f32_16x16x32_bf16 v[116:119], v[72:75], v[190:193], v[116:119]
	v_mfma_f32_16x16x32_bf16 v[112:115], v[136:139], v[190:193], v[112:115]
	v_mfma_f32_16x16x32_bf16 v[100:103], v[72:75], v[208:211], v[100:103]
	v_mfma_f32_16x16x32_bf16 v[96:99], v[136:139], v[208:211], v[96:99]
	v_mfma_f32_16x16x32_bf16 v[84:87], v[72:75], v[216:219], v[84:87]
	v_mfma_f32_16x16x32_bf16 v[80:83], v[136:139], v[216:219], v[80:83]
	v_mfma_f32_16x16x32_bf16 v[132:135], v[76:79], v[186:189], v[132:135]
	v_mfma_f32_16x16x32_bf16 v[128:131], v[140:143], v[186:189], v[128:131]
	v_mfma_f32_16x16x32_bf16 v[116:119], v[76:79], v[194:197], v[116:119]
	v_mfma_f32_16x16x32_bf16 v[112:115], v[140:143], v[194:197], v[112:115]
	v_mfma_f32_16x16x32_bf16 v[100:103], v[76:79], v[212:215], v[100:103]
	v_mfma_f32_16x16x32_bf16 v[96:99], v[140:143], v[212:215], v[96:99]
	v_mfma_f32_16x16x32_bf16 v[84:87], v[76:79], v[220:223], v[84:87]
	v_mfma_f32_16x16x32_bf16 v[80:83], v[140:143], v[220:223], v[80:83]
	s_setprio 0
	s_setprio 1
	v_mfma_f32_16x16x32_bf16 v[124:127], v[144:147], v[182:185], v[124:127]
	v_mfma_f32_16x16x32_bf16 v[120:123], v[152:155], v[182:185], v[120:123]
	v_mfma_f32_16x16x32_bf16 v[108:111], v[144:147], v[190:193], v[108:111]
	v_mfma_f32_16x16x32_bf16 v[104:107], v[152:155], v[190:193], v[104:107]
	v_mfma_f32_16x16x32_bf16 v[92:95], v[144:147], v[208:211], v[92:95]
	v_mfma_f32_16x16x32_bf16 v[88:91], v[152:155], v[208:211], v[88:91]
	v_mfma_f32_16x16x32_bf16 v[68:71], v[144:147], v[216:219], v[68:71]
	v_mfma_f32_16x16x32_bf16 v[64:67], v[152:155], v[216:219], v[64:67]
	v_mfma_f32_16x16x32_bf16 v[124:127], v[148:151], v[186:189], v[124:127]
	v_mfma_f32_16x16x32_bf16 v[120:123], v[178:181], v[186:189], v[120:123]
	v_mfma_f32_16x16x32_bf16 v[108:111], v[148:151], v[194:197], v[108:111]
	v_mfma_f32_16x16x32_bf16 v[104:107], v[178:181], v[194:197], v[104:107]
	v_mfma_f32_16x16x32_bf16 v[92:95], v[148:151], v[212:215], v[92:95]
	v_mfma_f32_16x16x32_bf16 v[88:91], v[178:181], v[212:215], v[88:91]
	v_mfma_f32_16x16x32_bf16 v[68:71], v[148:151], v[220:223], v[68:71]
	v_mfma_f32_16x16x32_bf16 v[64:67], v[178:181], v[220:223], v[64:67]
	s_barrier
	s_setprio 0
	s_add_i32 s38, s72, s3
	s_mov_b32 m0, s38
	ds_read_b128 v[182:185], v204 offset:16384
	ds_read_b128 v[186:189], v204 offset:17408
	ds_read_b128 v[190:193], v204 offset:18432
	ds_read_b128 v[194:197], v204 offset:19456
	ds_read_b128 v[208:211], v204 offset:20480
	ds_read_b128 v[212:215], v204 offset:21504
	ds_read_b128 v[216:219], v204 offset:22528
	ds_read_b128 v[220:223], v204 offset:23552
	global_load_lds_dwordx4 v158, s[62:63]
	s_add_i32 m0, s38, 0x2000
	s_add_u32 s80, s62, 0x1000
	s_addc_u32 s81, s63, 0
	s_add_i32 s38, s73, s3
	global_load_lds_dwordx4 v162, s[62:63]
	s_mov_b32 m0, s38
	s_nop 0
	global_load_lds_dwordx4 v158, s[80:81]
	s_add_i32 m0, s38, 0x2000
	s_nop 0
	global_load_lds_dwordx4 v162, s[80:81]
	s_mov_b32 m0, s45
	s_nop 0
	global_load_lds_dwordx4 v156, s[64:65]
	s_mov_b32 m0, s47
	s_nop 0
	global_load_lds_dwordx4 v160, s[64:65]
	s_waitcnt vmcnt(8)
	s_waitcnt lgkmcnt(0)
	s_setprio 1
	s_barrier
	v_mfma_f32_16x16x32_bf16 v[60:63], v[72:75], v[182:185], v[60:63]
	v_mfma_f32_16x16x32_bf16 v[56:59], v[136:139], v[182:185], v[56:59]
	v_mfma_f32_16x16x32_bf16 v[44:47], v[72:75], v[190:193], v[44:47]
	v_mfma_f32_16x16x32_bf16 v[40:43], v[136:139], v[190:193], v[40:43]
	v_mfma_f32_16x16x32_bf16 v[28:31], v[72:75], v[208:211], v[28:31]
	v_mfma_f32_16x16x32_bf16 v[24:27], v[136:139], v[208:211], v[24:27]
	v_mfma_f32_16x16x32_bf16 v[12:15], v[72:75], v[216:219], v[12:15]
	v_mfma_f32_16x16x32_bf16 v[8:11], v[136:139], v[216:219], v[8:11]
	v_mfma_f32_16x16x32_bf16 v[60:63], v[76:79], v[186:189], v[60:63]
	v_mfma_f32_16x16x32_bf16 v[56:59], v[140:143], v[186:189], v[56:59]
	v_mfma_f32_16x16x32_bf16 v[44:47], v[76:79], v[194:197], v[44:47]
	v_mfma_f32_16x16x32_bf16 v[40:43], v[140:143], v[194:197], v[40:43]
	v_mfma_f32_16x16x32_bf16 v[28:31], v[76:79], v[212:215], v[28:31]
	v_mfma_f32_16x16x32_bf16 v[24:27], v[140:143], v[212:215], v[24:27]
	v_mfma_f32_16x16x32_bf16 v[12:15], v[76:79], v[220:223], v[12:15]
	v_mfma_f32_16x16x32_bf16 v[8:11], v[140:143], v[220:223], v[8:11]
	s_setprio 0
	s_setprio 1
	v_mfma_f32_16x16x32_bf16 v[52:55], v[144:147], v[182:185], v[52:55]
	v_mfma_f32_16x16x32_bf16 v[48:51], v[152:155], v[182:185], v[48:51]
	v_mfma_f32_16x16x32_bf16 v[36:39], v[144:147], v[190:193], v[36:39]
	v_mfma_f32_16x16x32_bf16 v[32:35], v[152:155], v[190:193], v[32:35]
	v_mfma_f32_16x16x32_bf16 v[20:23], v[144:147], v[208:211], v[20:23]
	v_mfma_f32_16x16x32_bf16 v[16:19], v[152:155], v[208:211], v[16:19]
	v_mfma_f32_16x16x32_bf16 v[4:7], v[144:147], v[216:219], v[4:7]
	v_mfma_f32_16x16x32_bf16 v[0:3], v[152:155], v[216:219], v[0:3]
	v_mfma_f32_16x16x32_bf16 v[52:55], v[148:151], v[186:189], v[52:55]
	v_mfma_f32_16x16x32_bf16 v[48:51], v[178:181], v[186:189], v[48:51]
	v_mfma_f32_16x16x32_bf16 v[36:39], v[148:151], v[194:197], v[36:39]
	v_mfma_f32_16x16x32_bf16 v[32:35], v[178:181], v[194:197], v[32:35]
	v_mfma_f32_16x16x32_bf16 v[20:23], v[148:151], v[212:215], v[20:23]
	v_mfma_f32_16x16x32_bf16 v[16:19], v[178:181], v[212:215], v[16:19]
	v_mfma_f32_16x16x32_bf16 v[4:7], v[148:151], v[220:223], v[4:7]
	v_mfma_f32_16x16x32_bf16 v[0:3], v[178:181], v[220:223], v[0:3]
	s_barrier
; #define PG8_STAGE(bufoff, gbase, voff) do { _Pragma("unroll") for (int _i = 0; _i < 2; ++_i) \
;         __builtin_amdgcn_global_load_lds((const unsigned*)((const char*)(gbase) + (voff)[_i]), (LAS unsigned*)(lds + (bufoff) + ldsw + _i * 8192), 16, 0, 0); } while (0)
; #define PG8_LDA(dst, b, h) do { _Pragma("unroll") for (int m = 0; m < 4; ++m) _Pragma("unroll") for (int k = 0; k < 2; ++k) dst[m][k] = *(const LAS bf16x8*)(lds + PG8_SA(b, h) + aoff + m * 2048 + k * 1024); } while (0)
; #define PG8_LDB(dst, b, h) do { _Pragma("unroll") for (int n = 0; n < 2; ++n) _Pragma("unroll") for (int k = 0; k < 2; ++k) dst[n][k] = *(const LAS bf16x8*)(lds + PG8_SB(b, h) + boff + n * 2048 + k * 1024); } while (0)
; #define PG8_MMA(ai, bj, At, Bt) do { __builtin_amdgcn_s_setprio(1); _Pragma("unroll") for (int m = 0; m < 4; ++m) _Pragma("unroll") for (int n = 0; n < 2; ++n) _Pragma("unroll") for (int k = 0; k < 2; ++k) \
;         acc[ai][bj][m][n] = __builtin_amdgcn_mfma_f32_16x16x32_bf16(Bt[n][k], At[m][k], acc[ai][bj][m][n], 0, 0, 0); __builtin_amdgcn_s_setprio(0); } while (0)
; #define PG8_WAIT_V(n) asm volatile("s_waitcnt vmcnt(" #n ")" ::: "memory")
; #define PG8_WAIT_L(n) asm volatile("s_waitcnt lgkmcnt(" #n ")" ::: "memory")
; #define PG8_BAR __builtin_amdgcn_s_barrier()
; #define PG8_SCHED __builtin_amdgcn_sched_barrier(0)
; template <class Epi, class Sched, bool ALIGN_EPI>
; __device__ __forceinline__ void gemm_phase(LAS unsigned char* lds, const Gemm g, const Sched& S, const Epi& E, const int wid) {
;     ...
;             PG8_LDB(B0, 1, 0); PG8_LDB(B1, 1, 1); PG8_SCHED; PG8_LDA(At, 1, 0); PG8_STAGE(PG8_SA(0, 1), a2 + hstepA, voffA);
;             PG8_WAIT_V(8); PG8_WAIT_L(0); PG8_BAR; PG8_MMA(0, 0, At, B0); PG8_MMA(0, 1, At, B1); PG8_BAR; PG8_SCHED;
;             PG8_LDA(At, 1, 1); PG8_STAGE(PG8_SB(1, 0), b3, voffB); PG8_STAGE(PG8_SB(1, 1), b3 + hstepB, voffB); PG8_STAGE(PG8_SA(1, 0), a3, voffA);
;             PG8_WAIT_V(8); PG8_WAIT_L(0); PG8_BAR; PG8_MMA(1, 0, At, B0); PG8_MMA(1, 1, At, B1); PG8_BAR; PG8_SCHED;
;         }
;         if constexpr (ALIGN_EPI) { if (wr == 0) PG8_BAR; }
	s_setprio 0
	s_add_i32 s38, 0, 0x18000
	s_add_i32 s79, 0, 0x1c000
	v_add_u32_e32 v140, s38, v198
	v_add_u32_e32 v164, s79, v198
	ds_read_b128 v[72:75], v140
	ds_read_b128 v[76:79], v140 offset:1024
	ds_read_b128 v[136:139], v140 offset:2048
	ds_read_b128 v[140:143], v140 offset:3072
	ds_read_b128 v[144:147], v164
	ds_read_b128 v[148:151], v164 offset:1024
	ds_read_b128 v[152:155], v164 offset:2048
	ds_read_b128 v[178:181], v164 offset:3072
	s_add_u32 s64, s64, 0x4000
	s_addc_u32 s65, s65, 0
	s_mov_b32 m0, s66
	ds_read_b128 v[182:185], v204 offset:32768
	ds_read_b128 v[186:189], v204 offset:33792
	ds_read_b128 v[190:193], v204 offset:34816
	ds_read_b128 v[194:197], v204 offset:35840
	ds_read_b128 v[208:211], v204 offset:36864
	ds_read_b128 v[212:215], v204 offset:37888
	ds_read_b128 v[216:219], v204 offset:38912
	ds_read_b128 v[220:223], v204 offset:39936
	global_load_lds_dwordx4 v156, s[64:65]
	s_mov_b32 m0, s67
	s_nop 0
	global_load_lds_dwordx4 v160, s[64:65]
	s_waitcnt vmcnt(8)
	s_waitcnt lgkmcnt(0)
	s_setprio 1
	s_barrier
	v_mfma_f32_16x16x32_bf16 v[132:135], v[72:75], v[182:185], v[132:135]
	v_mfma_f32_16x16x32_bf16 v[128:131], v[136:139], v[182:185], v[128:131]
	v_mfma_f32_16x16x32_bf16 v[116:119], v[72:75], v[190:193], v[116:119]
	v_mfma_f32_16x16x32_bf16 v[112:115], v[136:139], v[190:193], v[112:115]
	v_mfma_f32_16x16x32_bf16 v[100:103], v[72:75], v[208:211], v[100:103]
	v_mfma_f32_16x16x32_bf16 v[96:99], v[136:139], v[208:211], v[96:99]
	v_mfma_f32_16x16x32_bf16 v[84:87], v[72:75], v[216:219], v[84:87]
	v_mfma_f32_16x16x32_bf16 v[80:83], v[136:139], v[216:219], v[80:83]
	v_mfma_f32_16x16x32_bf16 v[132:135], v[76:79], v[186:189], v[132:135]
	v_mfma_f32_16x16x32_bf16 v[128:131], v[140:143], v[186:189], v[128:131]
	v_mfma_f32_16x16x32_bf16 v[116:119], v[76:79], v[194:197], v[116:119]
	v_mfma_f32_16x16x32_bf16 v[112:115], v[140:143], v[194:197], v[112:115]
	v_mfma_f32_16x16x32_bf16 v[100:103], v[76:79], v[212:215], v[100:103]
	v_mfma_f32_16x16x32_bf16 v[96:99], v[140:143], v[212:215], v[96:99]
	v_mfma_f32_16x16x32_bf16 v[84:87], v[76:79], v[220:223], v[84:87]
	v_mfma_f32_16x16x32_bf16 v[80:83], v[140:143], v[220:223], v[80:83]
	s_setprio 0
	s_setprio 1
	v_mfma_f32_16x16x32_bf16 v[124:127], v[144:147], v[182:185], v[124:127]
	v_mfma_f32_16x16x32_bf16 v[120:123], v[152:155], v[182:185], v[120:123]
	v_mfma_f32_16x16x32_bf16 v[108:111], v[144:147], v[190:193], v[108:111]
	v_mfma_f32_16x16x32_bf16 v[104:107], v[152:155], v[190:193], v[104:107]
	v_mfma_f32_16x16x32_bf16 v[92:95], v[144:147], v[208:211], v[92:95]
	v_mfma_f32_16x16x32_bf16 v[88:91], v[152:155], v[208:211], v[88:91]
	v_mfma_f32_16x16x32_bf16 v[68:71], v[144:147], v[216:219], v[68:71]
	v_mfma_f32_16x16x32_bf16 v[64:67], v[152:155], v[216:219], v[64:67]
	v_mfma_f32_16x16x32_bf16 v[124:127], v[148:151], v[186:189], v[124:127]
	v_mfma_f32_16x16x32_bf16 v[120:123], v[178:181], v[186:189], v[120:123]
	v_mfma_f32_16x16x32_bf16 v[108:111], v[148:151], v[194:197], v[108:111]
	v_mfma_f32_16x16x32_bf16 v[104:107], v[178:181], v[194:197], v[104:107]
	v_mfma_f32_16x16x32_bf16 v[92:95], v[148:151], v[212:215], v[92:95]
	v_mfma_f32_16x16x32_bf16 v[88:91], v[178:181], v[212:215], v[88:91]
	v_mfma_f32_16x16x32_bf16 v[68:71], v[148:151], v[220:223], v[68:71]
	v_mfma_f32_16x16x32_bf16 v[64:67], v[178:181], v[220:223], v[64:67]
	s_barrier
	s_setprio 0
	s_add_u32 s64, s62, 0x8000
	s_addc_u32 s65, s63, 0
	s_add_i32 s38, s38, s3
	s_mov_b32 m0, s38
	ds_read_b128 v[182:185], v204 offset:49152
	ds_read_b128 v[186:189], v204 offset:50176
	ds_read_b128 v[190:193], v204 offset:51200
	ds_read_b128 v[194:197], v204 offset:52224
	ds_read_b128 v[208:211], v204 offset:53248
	ds_read_b128 v[212:215], v204 offset:54272
	ds_read_b128 v[216:219], v204 offset:55296
	ds_read_b128 v[220:223], v204 offset:56320
	global_load_lds_dwordx4 v158, s[64:65]
	s_add_i32 m0, s38, 0x2000
	s_add_u32 s62, s62, 0x9000
	s_addc_u32 s63, s63, 0
	s_add_i32 s38, s79, s3
	global_load_lds_dwordx4 v162, s[64:65]
	s_mov_b32 m0, s38
	s_nop 0
	global_load_lds_dwordx4 v158, s[62:63]
	s_add_i32 m0, s38, 0x2000
	s_nop 0
	global_load_lds_dwordx4 v162, s[62:63]
	s_mov_b32 m0, s69
	s_nop 0
	global_load_lds_dwordx4 v156, s[60:61]
	s_mov_b32 m0, s70
	s_nop 0
	global_load_lds_dwordx4 v160, s[60:61]
	s_waitcnt vmcnt(8)
	s_waitcnt lgkmcnt(0)
	s_setprio 1
	s_barrier
	v_mfma_f32_16x16x32_bf16 v[60:63], v[72:75], v[182:185], v[60:63]
	v_mfma_f32_16x16x32_bf16 v[56:59], v[136:139], v[182:185], v[56:59]
	v_mfma_f32_16x16x32_bf16 v[44:47], v[72:75], v[190:193], v[44:47]
	v_mfma_f32_16x16x32_bf16 v[40:43], v[136:139], v[190:193], v[40:43]
	v_mfma_f32_16x16x32_bf16 v[28:31], v[72:75], v[208:211], v[28:31]
	v_mfma_f32_16x16x32_bf16 v[24:27], v[136:139], v[208:211], v[24:27]
	v_mfma_f32_16x16x32_bf16 v[12:15], v[72:75], v[216:219], v[12:15]
	v_mfma_f32_16x16x32_bf16 v[8:11], v[136:139], v[216:219], v[8:11]
	v_mfma_f32_16x16x32_bf16 v[60:63], v[76:79], v[186:189], v[60:63]
	v_mfma_f32_16x16x32_bf16 v[56:59], v[140:143], v[186:189], v[56:59]
	v_mfma_f32_16x16x32_bf16 v[44:47], v[76:79], v[194:197], v[44:47]
	v_mfma_f32_16x16x32_bf16 v[40:43], v[140:143], v[194:197], v[40:43]
	v_mfma_f32_16x16x32_bf16 v[28:31], v[76:79], v[212:215], v[28:31]
	v_mfma_f32_16x16x32_bf16 v[24:27], v[140:143], v[212:215], v[24:27]
	v_mfma_f32_16x16x32_bf16 v[12:15], v[76:79], v[220:223], v[12:15]
	v_mfma_f32_16x16x32_bf16 v[8:11], v[140:143], v[220:223], v[8:11]
	s_setprio 0
	s_setprio 1
	v_mfma_f32_16x16x32_bf16 v[52:55], v[144:147], v[182:185], v[52:55]
	v_mfma_f32_16x16x32_bf16 v[48:51], v[152:155], v[182:185], v[48:51]
	v_mfma_f32_16x16x32_bf16 v[36:39], v[144:147], v[190:193], v[36:39]
	v_mfma_f32_16x16x32_bf16 v[32:35], v[152:155], v[190:193], v[32:35]
	v_mfma_f32_16x16x32_bf16 v[20:23], v[144:147], v[208:211], v[20:23]
	v_mfma_f32_16x16x32_bf16 v[16:19], v[152:155], v[208:211], v[16:19]
	v_mfma_f32_16x16x32_bf16 v[4:7], v[144:147], v[216:219], v[4:7]
	v_mfma_f32_16x16x32_bf16 v[0:3], v[152:155], v[216:219], v[0:3]
	v_mfma_f32_16x16x32_bf16 v[52:55], v[148:151], v[186:189], v[52:55]
	v_mfma_f32_16x16x32_bf16 v[48:51], v[178:181], v[186:189], v[48:51]
	v_mfma_f32_16x16x32_bf16 v[36:39], v[148:151], v[194:197], v[36:39]
	v_mfma_f32_16x16x32_bf16 v[32:35], v[178:181], v[194:197], v[32:35]
	v_mfma_f32_16x16x32_bf16 v[20:23], v[148:151], v[212:215], v[20:23]
	v_mfma_f32_16x16x32_bf16 v[16:19], v[178:181], v[212:215], v[16:19]
	v_mfma_f32_16x16x32_bf16 v[4:7], v[148:151], v[220:223], v[4:7]
	v_mfma_f32_16x16x32_bf16 v[0:3], v[178:181], v[220:223], v[0:3]
	s_barrier
	s_setprio 0
	s_add_i32 s78, s78, 2
	s_add_u32 s59, s59, 0x10000
	s_addc_u32 s77, s77, 0
	s_add_u32 s16, s16, 0x10000
	s_addc_u32 s17, s17, 0
	s_cmpk_gt_u32 s78, 0xfd
	s_cbranch_scc0 .LBB0_1672
	s_and_b64 vcc, exec, s[28:29]
	s_cbranch_vccz .LBB0_1675
	s_barrier
